# LRU: hoist per-head constants out of the tile loop, W(0) reloaded after d=1 MFMAs, conv prefetch (on attn8)
# speedup vs baseline: 1.0134x; 1.0034x over previous
; __device__ __forceinline__ void lru_tile(const Params& P, int chunk, int head, int pass, char* smem_raw) {
;   u16* sm_uc = reinterpret_cast<u16*>(smem_raw);
;   u16* sm_w = sm_uc + 128 * LDSS;
;   float* sm_a = reinterpret_cast<float*>(sm_w + 128 * LDSS);
;   float* sm_b = sm_a + 64 * 64;
;   float2* sm_ph = reinterpret_cast<float2*>(sm_b + 64 * 64);
;   float* sm_init = reinterpret_cast<float*>(sm_ph + 256);
;   const int tid = VTID, lane = tid & 63, wid = tid >> 6;
;   const int q = tid >> 6, ch = tid & 63;
;   const int row0 = chunk * 128;
;   int seq_lo, seq_hi;
;   if (chunk < 256) { seq_lo = (chunk >> 6) << 13; seq_hi = seq_lo + 8192; }
;   else { const int b = (chunk - 256) >> 1; seq_lo = N_X + b * 256; seq_hi = seq_lo + 256; }
;   const int gch = head * 64 + ch;
;   const float* hfbuf = reinterpret_cast<const float*>(P.hy);
;   float* hfw = reinterpret_cast<float*>(P.hy);
;   {
;     const float w0 = P.conv_w[gch], w1 = P.conv_w[512 + gch], w2 = P.conv_w[1024 + gch], w3 = P.conv_w[1536 + gch];
;     const float cb = P.conv_b[gch];
;     const u16* zu = P.zq + gch;
;     const int r = row0 + q * 32;
.LBB0_287:
	v_readlane_b32 s0, v252, 0
	v_readlane_b32 s1, v252, 1
	v_readfirstlane_b32 s68, v153
	s_nop 3
	s_sub_u32 s0, s0, 0x170
	s_subb_u32 s1, s1, 0
	s_load_dwordx2 s[10:11], s[0:1], 0x148
	s_load_dwordx2 s[12:13], s[0:1], 0x158
	s_load_dwordx2 s[18:19], s[0:1], 0x130
	s_load_dwordx2 s[20:21], s[0:1], 0x128
	s_load_dwordx4 s[24:27], s[0:1], 0x70
	s_load_dwordx2 s[28:29], s[0:1], 0x88
	s_load_dwordx2 s[30:31], s[0:1], 0x98
	s_load_dwordx2 s[36:37], s[0:1], 0xa0
	s_lshl_b32 s4, s2, 1
	s_add_u32 s68, s4, s68
	s_mov_b32 s69, 0
	s_mov_b32 s70, 4
	s_cmp_lt_u32 s68, 64
	s_cselect_b32 s70, 5, 4
	s_mov_b32 s72, 0xffff0000
	s_mov_b32 s73, -1
	s_mov_b32 s74, 0
	s_mov_b32 s75, -1
	s_mov_b32 s76, 0
	s_mov_b32 s77, 0xffff0000
	s_mov_b32 s78, -1
	s_mov_b32 s79, 0x0000ffff
	s_mov_b32 s80, -1
	s_mov_b32 s81, 0
	s_mov_b32 s82, 0x0000ffff
	s_mov_b32 s83, 0
	v_and_b32_e32 v138, 63, v152
	v_lshrrev_b32_e32 v139, 4, v138
	v_and_b32_e32 v140, 15, v138
	v_bfe_u32 v141, v152, 6, 2
	v_lshl_add_u32 v255, v141, 4, v140
	v_mul_u32_u24_e32 v253, 0x12000, v153
	v_add_u32_e32 v253, 16, v253
	v_mul_u32_u24_e32 v134, 0x18000, v139
	v_lshl_add_u32 v134, v255, 1, v134
	v_lshlrev_b32_e32 v237, 16, v139
	v_lshl_add_u32 v237, v255, 1, v237
	v_lshlrev_b32_e32 v250, 3, v255
	v_lshlrev_b32_e32 v251, 7, v255
	v_lshl_add_u32 v251, v139, 4, v251
	v_lshrrev_b32_e32 v254, 3, v140
	v_lshl_add_u32 v254, v141, 1, v254
	v_lshlrev_b32_e32 v202, 1, v139
	v_xor_b32_e32 v89, v254, v202
	v_xor_b32_e32 v130, 1, v89
	v_and_b32_e32 v203, 7, v140
	v_lshl_add_u32 v202, v139, 12, v253
	v_lshl_add_u32 v202, v203, 1, v202
	v_lshl_add_u32 v89, v89, 4, v202
	v_lshl_add_u32 v130, v130, 4, v202
	v_lshrrev_b32_e32 v202, 2, v140
	v_and_b32_e32 v203, 3, v140
	v_lshl_add_u32 v254, v202, 5, v203
	v_lshl_add_u32 v254, v254, 7, v253
	v_lshrrev_b32_e32 v203, 1, v203
	v_lshl_add_u32 v202, v202, 1, v203
	v_xor_b32_e32 v202, v139, v202
	v_lshl_add_u32 v131, v202, 4, v254
	v_xor_b32_e32 v202, 4, v202
	v_lshl_add_u32 v133, v202, 4, v254
	v_cmp_eq_u32_e32 vcc, 0, v139
	s_mov_b64 s[84:85], vcc
	v_cmp_eq_u32_e32 vcc, 3, v139
	s_mov_b64 s[86:87], vcc
	s_waitcnt lgkmcnt(0)
; __device__ __forceinline__ float bf2f(u16 h) { return __uint_as_float(((unsigned)h) << 16); }
; __device__ __forceinline__ void lru_tile(const Params& P, int chunk, int head, int pass, char* smem_raw) {
;     ...
;   {
;     const float w0 = P.conv_w[gch], w1 = P.conv_w[512 + gch], w2 = P.conv_w[1024 + gch], w3 = P.conv_w[1536 + gch];
;     const float cb = P.conv_b[gch];
;     const u16* zu = P.zq + gch;
;     const int r = row0 + q * 32;
;     float uv[35];
; #pragma unroll
;     for (int i = 0; i < 35; ++i) {
;       const int rr = r - 2 + i;
;       uv[i] = (rr >= seq_lo && rr < seq_hi) ? bf2f(zu[(long)rr * 1536]) : 0.f;
;     ...
;     float ba[4], bi[4], c8[4];
; #pragma unroll
;     for (int tc = 0; tc < 4; ++tc) {
;       const int cidx = d * 512 + head * 64 + 16 * tc + (lane & 15);
;       ba[tc] = P.b_a[cidx] * -1.4426950408889634f; bi[tc] = P.b_i[cidx] * -1.4426950408889634f;
;       const float nl = -P.lam[cidx];
;       const float e_ = __expf(nl);
;       const float sp = (nl > 20.f) ? nl
;                      : (e_ < 0.03f ? e_ * (1.f - e_ * (0.5f - e_ * (0.33333334f - 0.25f * e_))) : __logf(1.f + e_));
;       c8[tc] = 8.f * 1.4426950408889634f * sp;
;     }
	s_and_b32 s56, s68, 7
	s_lshl_b32 s56, s56, 6
	s_lshr_b32 s59, s68, 3
	s_cmp_lt_u32 s59, 256
	s_cselect_b32 s60, 63, 1
	s_and_b32 s57, s59, s60
	s_cmp_eq_u32 s57, 0
	s_cselect_b64 s[0:1], s[84:85], 0
	s_cmp_eq_u32 s57, s60
	s_cselect_b64 s[4:5], s[86:87], 0
	v_mov_b32_e32 v255, 0x1800
	v_cndmask_b32_e64 v150, 0, v255, s[0:1]
	v_lshlrev_b32_e32 v136, 1, v150
	v_add_u32_e32 v136, v134, v136
	v_add_u32_e32 v150, v134, v150
	v_cndmask_b32_e64 v151, 0, v255, s[4:5]
	v_sub_u32_e32 v151, v134, v151
	s_lshl_b32 s61, s59, 7
	s_mul_i32 s0, s61, 0xc00
	s_lshl_b32 s1, s56, 1
	s_add_u32 s0, s0, s1
	s_add_u32 s4, s10, s0
	s_addc_u32 s5, s11, 0
	s_sub_u32 s4, s4, 0x1800
	s_subb_u32 s5, s5, 0
	global_load_ushort v205, v136, s[4:5]
	s_add_u32 s4, s4, 0xc00
	s_addc_u32 s5, s5, 0
	global_load_ushort v206, v150, s[4:5]
	s_add_u32 s4, s4, 0xc00
	s_addc_u32 s5, s5, 0
	global_load_ushort v207, v134, s[4:5]
	s_add_u32 s4, s4, 0xc00
	s_addc_u32 s5, s5, 0
	global_load_ushort v208, v134, s[4:5]
	s_add_u32 s4, s4, 0xc00
	s_addc_u32 s5, s5, 0
	global_load_ushort v209, v134, s[4:5]
	s_add_u32 s4, s4, 0xc00
	s_addc_u32 s5, s5, 0
	global_load_ushort v210, v134, s[4:5]
	s_add_u32 s4, s4, 0xc00
	s_addc_u32 s5, s5, 0
	global_load_ushort v211, v134, s[4:5]
	s_add_u32 s4, s4, 0xc00
	s_addc_u32 s5, s5, 0
	global_load_ushort v212, v134, s[4:5]
	s_add_u32 s4, s4, 0xc00
	s_addc_u32 s5, s5, 0
	global_load_ushort v213, v134, s[4:5]
	s_add_u32 s4, s4, 0xc00
	s_addc_u32 s5, s5, 0
	global_load_ushort v214, v134, s[4:5]
	s_add_u32 s4, s4, 0xc00
	s_addc_u32 s5, s5, 0
	global_load_ushort v215, v134, s[4:5]
	s_add_u32 s4, s4, 0xc00
	s_addc_u32 s5, s5, 0
	global_load_ushort v216, v134, s[4:5]
	s_add_u32 s4, s4, 0xc00
	s_addc_u32 s5, s5, 0
	global_load_ushort v217, v134, s[4:5]
	s_add_u32 s4, s4, 0xc00
	s_addc_u32 s5, s5, 0
	global_load_ushort v218, v134, s[4:5]
	s_add_u32 s4, s4, 0xc00
	s_addc_u32 s5, s5, 0
	global_load_ushort v219, v134, s[4:5]
	s_add_u32 s4, s4, 0xc00
	s_addc_u32 s5, s5, 0
	global_load_ushort v220, v134, s[4:5]
	s_add_u32 s4, s4, 0xc00
	s_addc_u32 s5, s5, 0
	global_load_ushort v221, v134, s[4:5]
	s_add_u32 s4, s4, 0xc00
	s_addc_u32 s5, s5, 0
	global_load_ushort v222, v134, s[4:5]
	s_add_u32 s4, s4, 0xc00
	s_addc_u32 s5, s5, 0
	global_load_ushort v223, v134, s[4:5]
	s_add_u32 s4, s4, 0xc00
	s_addc_u32 s5, s5, 0
	global_load_ushort v224, v134, s[4:5]
	s_add_u32 s4, s4, 0xc00
	s_addc_u32 s5, s5, 0
	global_load_ushort v225, v134, s[4:5]
	s_add_u32 s4, s4, 0xc00
	s_addc_u32 s5, s5, 0
	global_load_ushort v226, v134, s[4:5]
	s_add_u32 s4, s4, 0xc00
	s_addc_u32 s5, s5, 0
	global_load_ushort v227, v134, s[4:5]
	s_add_u32 s4, s4, 0xc00
	s_addc_u32 s5, s5, 0
	global_load_ushort v228, v134, s[4:5]
	s_add_u32 s4, s4, 0xc00
	s_addc_u32 s5, s5, 0
	global_load_ushort v229, v134, s[4:5]
	s_add_u32 s4, s4, 0xc00
	s_addc_u32 s5, s5, 0
	global_load_ushort v230, v134, s[4:5]
	s_add_u32 s4, s4, 0xc00
	s_addc_u32 s5, s5, 0
	global_load_ushort v231, v134, s[4:5]
	s_add_u32 s4, s4, 0xc00
	s_addc_u32 s5, s5, 0
	global_load_ushort v232, v134, s[4:5]
	s_add_u32 s4, s4, 0xc00
	s_addc_u32 s5, s5, 0
	global_load_ushort v233, v134, s[4:5]
	s_add_u32 s4, s4, 0xc00
	s_addc_u32 s5, s5, 0
	global_load_ushort v234, v134, s[4:5]
	s_add_u32 s4, s4, 0xc00
	s_addc_u32 s5, s5, 0
	global_load_ushort v235, v134, s[4:5]
	s_add_u32 s4, s4, 0xc00
	s_addc_u32 s5, s5, 0
	global_load_ushort v236, v134, s[4:5]
	s_add_u32 s4, s4, 0xc00
	s_addc_u32 s5, s5, 0
	global_load_ushort v142, v134, s[4:5]
	s_add_u32 s4, s4, 0xc00
	s_addc_u32 s5, s5, 0
	global_load_ushort v143, v134, s[4:5]
	s_add_u32 s4, s4, 0xc00
	s_addc_u32 s5, s5, 0
	global_load_ushort v144, v151, s[4:5]
	v_bfe_u32 v255, v152, 6, 2
	v_and_b32_e32 v253, 15, v152
	v_lshl_add_u32 v255, v255, 4, v253
	v_add_u32_e32 v255, s56, v255
	v_lshlrev_b32_e32 v255, 2, v255
	global_load_dword v65, v255, s[24:25]
	global_load_dword v67, v255, s[24:25] offset:2048
	s_add_u32 s0, s24, 0x1000
	s_addc_u32 s1, s25, 0
	global_load_dword v68, v255, s[0:1]
	global_load_dword v70, v255, s[0:1] offset:2048
	global_load_dword v73, v255, s[26:27]
	s_add_u32 s0, s28, 0x0
	s_addc_u32 s1, s29, 0
	global_load_dword v75, v255, s[0:1]
	s_add_u32 s0, s30, 0x0
	s_addc_u32 s1, s31, 0
	global_load_dword v84, v255, s[0:1]
	s_add_u32 s0, s36, 0x0
	s_addc_u32 s1, s37, 0
	global_load_dword v85, v255, s[0:1]
	s_add_u32 s0, s28, 0x800
	s_addc_u32 s1, s29, 0
	global_load_dword v145, v255, s[0:1]
	s_add_u32 s0, s30, 0x800
	s_addc_u32 s1, s31, 0
	global_load_dword v146, v255, s[0:1]
	s_add_u32 s0, s36, 0x800
	s_addc_u32 s1, s37, 0
	global_load_dword v147, v255, s[0:1]
	s_lshl_b32 s0, s56, 8
	s_add_u32 s0, s0, 0x0
	s_add_u32 s4, s20, s0
	s_addc_u32 s5, s21, 0
	global_load_dwordx4 v[238:241], v251, s[4:5]
	global_load_dwordx4 v[242:245], v251, s[4:5] offset:64
	s_add_u32 s4, s4, 0x2000
	s_addc_u32 s5, s5, 0
	global_load_dwordx4 v[246:249], v251, s[4:5]
	global_load_dwordx4 v[194:197], v251, s[4:5] offset:64
	s_waitcnt vmcnt(0)
	v_mul_f32_e32 v75, 0xbfb8aa3b, v75
	v_mul_f32_e32 v84, 0xbfb8aa3b, v84
	v_sub_f32_e32 v138, 0, v85
	v_mul_f32_e32 v139, 0x3fb8aa3b, v138
	v_exp_f32_e32 v139, v139
	s_nop 0
	v_mul_f32_e32 v140, 0xbe800000, v139
	v_add_f32_e32 v140, 0x3eaaaaab, v140
	v_fma_f32 v140, -v139, v140, 0.5
	v_fma_f32 v140, -v139, v140, 1.0
	v_mul_f32_e32 v140, v139, v140
	v_add_f32_e32 v141, 1.0, v139
	v_log_f32_e32 v141, v141
	v_mov_b32_e32 v255, 0x3cf5c28f
	v_mul_f32_e32 v141, 0x3f317218, v141
	v_cmp_gt_f32_e32 vcc, v255, v139
	s_nop 1
	v_cndmask_b32_e32 v140, v141, v140, vcc
	v_mov_b32_e32 v255, 0x41a00000
	v_cmp_lt_f32_e32 vcc, v255, v138
	s_nop 1
	v_cndmask_b32_e32 v140, v140, v138, vcc
	v_mul_f32_e32 v85, 0xc138aa3b, v140
	v_mul_f32_e32 v145, 0xbfb8aa3b, v145
	v_mul_f32_e32 v146, 0xbfb8aa3b, v146
	v_sub_f32_e32 v138, 0, v147
	v_mul_f32_e32 v139, 0x3fb8aa3b, v138
	v_exp_f32_e32 v139, v139
	s_nop 0
	v_mul_f32_e32 v140, 0xbe800000, v139
	v_add_f32_e32 v140, 0x3eaaaaab, v140
	v_fma_f32 v140, -v139, v140, 0.5
	v_fma_f32 v140, -v139, v140, 1.0
	v_mul_f32_e32 v140, v139, v140
	v_add_f32_e32 v141, 1.0, v139
	v_log_f32_e32 v141, v141
	v_mov_b32_e32 v255, 0x3cf5c28f
	v_mul_f32_e32 v141, 0x3f317218, v141
	v_cmp_gt_f32_e32 vcc, v255, v139
	s_nop 1
	v_cndmask_b32_e32 v140, v141, v140, vcc
	v_mov_b32_e32 v255, 0x41a00000
	v_cmp_lt_f32_e32 vcc, v255, v138
	s_nop 1
	v_cndmask_b32_e32 v140, v140, v138, vcc
	v_mul_f32_e32 v147, 0xc138aa3b, v140

; __device__ __forceinline__ float bf2f(u16 h) { return __uint_as_float(((unsigned)h) << 16); }
; __device__ __forceinline__ void lru_tile(const Params& P, int chunk, int head, int pass, char* smem_raw) {
;     ...
;     float uv[35];
; #pragma unroll
;     for (int i = 0; i < 35; ++i) {
;       const int rr = r - 2 + i;
;       uv[i] = (rr >= seq_lo && rr < seq_hi) ? bf2f(zu[(long)rr * 1536]) : 0.f;
;     }
;     __syncthreads();
; #pragma unroll
;     for (int i = 0; i < 32; ++i) {
;       const float v = cb + uv[i] * w0 + uv[i + 1] * w1 + uv[i + 2] * w2 + uv[i + 3] * w3;
;       sm_uc[(q * 32 + i) * LDSS + ch] = f2bf(v);
.Lmy_lrua_fl:
	s_cmp_eq_u32 s57, 0
	s_cselect_b64 s[0:1], s[84:85], 0
	s_cmp_eq_u32 s57, s60
	s_cselect_b64 s[4:5], s[86:87], 0
	v_cndmask_b32_e64 v202, 1.0, 0, s[0:1]
	v_cndmask_b32_e64 v203, 1.0, 0, s[4:5]
	s_barrier
	s_waitcnt vmcnt(1)
	v_lshlrev_b32_e32 v90, 16, v205
	v_lshlrev_b32_e32 v91, 16, v206
	v_lshlrev_b32_e32 v92, 16, v207
	v_lshlrev_b32_e32 v93, 16, v208
	v_lshlrev_b32_e32 v94, 16, v209
	v_lshlrev_b32_e32 v95, 16, v210
	v_lshlrev_b32_e32 v96, 16, v211
	v_lshlrev_b32_e32 v97, 16, v212
	v_lshlrev_b32_e32 v98, 16, v213
	v_lshlrev_b32_e32 v99, 16, v214
	v_lshlrev_b32_e32 v100, 16, v215
	v_lshlrev_b32_e32 v101, 16, v216
	v_lshlrev_b32_e32 v102, 16, v217
	v_lshlrev_b32_e32 v103, 16, v218
	v_lshlrev_b32_e32 v104, 16, v219
	v_lshlrev_b32_e32 v105, 16, v220
	v_lshlrev_b32_e32 v106, 16, v221
	v_lshlrev_b32_e32 v107, 16, v222
	v_lshlrev_b32_e32 v108, 16, v223
	v_lshlrev_b32_e32 v109, 16, v224
	v_lshlrev_b32_e32 v110, 16, v225
	v_lshlrev_b32_e32 v111, 16, v226
	v_lshlrev_b32_e32 v112, 16, v227
	v_lshlrev_b32_e32 v113, 16, v228
	v_lshlrev_b32_e32 v114, 16, v229
	v_lshlrev_b32_e32 v115, 16, v230
	v_lshlrev_b32_e32 v116, 16, v231
	v_lshlrev_b32_e32 v117, 16, v232
	v_lshlrev_b32_e32 v118, 16, v233
	v_lshlrev_b32_e32 v119, 16, v234
	v_lshlrev_b32_e32 v120, 16, v235
	v_lshlrev_b32_e32 v121, 16, v236
	v_lshlrev_b32_e32 v122, 16, v142
	v_lshlrev_b32_e32 v123, 16, v143
	v_lshlrev_b32_e32 v124, 16, v144
	v_mul_f32_e32 v90, v90, v202
	v_mul_f32_e32 v91, v91, v202
	v_mul_f32_e32 v124, v124, v203
	v_fma_f32 v162, v90, v65, v73
	v_fma_f32 v162, v91, v67, v162
	v_fma_f32 v162, v92, v68, v162
	v_fma_f32 v162, v93, v70, v162
	v_fma_f32 v163, v91, v65, v73
	v_fma_f32 v163, v92, v67, v163
	v_fma_f32 v163, v93, v68, v163
	v_fma_f32 v163, v94, v70, v163
	v_fma_f32 v164, v92, v65, v73
	v_fma_f32 v164, v93, v67, v164
	v_fma_f32 v164, v94, v68, v164
	v_fma_f32 v164, v95, v70, v164
	v_fma_f32 v165, v93, v65, v73
	v_fma_f32 v165, v94, v67, v165
	v_fma_f32 v165, v95, v68, v165
	v_fma_f32 v165, v96, v70, v165
	v_fma_f32 v166, v94, v65, v73
	v_fma_f32 v166, v95, v67, v166
	v_fma_f32 v166, v96, v68, v166
	v_fma_f32 v166, v97, v70, v166
	v_fma_f32 v167, v95, v65, v73
	v_fma_f32 v167, v96, v67, v167
	v_fma_f32 v167, v97, v68, v167
	v_fma_f32 v167, v98, v70, v167
	v_fma_f32 v168, v96, v65, v73
	v_fma_f32 v168, v97, v67, v168
	v_fma_f32 v168, v98, v68, v168
	v_fma_f32 v168, v99, v70, v168
	v_fma_f32 v169, v97, v65, v73
	v_fma_f32 v169, v98, v67, v169
	v_fma_f32 v169, v99, v68, v169
	v_fma_f32 v169, v100, v70, v169
	v_fma_f32 v170, v98, v65, v73
	v_fma_f32 v170, v99, v67, v170
	v_fma_f32 v170, v100, v68, v170
	v_fma_f32 v170, v101, v70, v170
	v_fma_f32 v171, v99, v65, v73
	v_fma_f32 v171, v100, v67, v171
	v_fma_f32 v171, v101, v68, v171
	v_fma_f32 v171, v102, v70, v171
	v_fma_f32 v172, v100, v65, v73
	v_fma_f32 v172, v101, v67, v172
	v_fma_f32 v172, v102, v68, v172
	v_fma_f32 v172, v103, v70, v172
	v_fma_f32 v173, v101, v65, v73
	v_fma_f32 v173, v102, v67, v173
	v_fma_f32 v173, v103, v68, v173
	v_fma_f32 v173, v104, v70, v173
	v_fma_f32 v174, v102, v65, v73
	v_fma_f32 v174, v103, v67, v174
	v_fma_f32 v174, v104, v68, v174
	v_fma_f32 v174, v105, v70, v174
	v_fma_f32 v175, v103, v65, v73
	v_fma_f32 v175, v104, v67, v175
	v_fma_f32 v175, v105, v68, v175
	v_fma_f32 v175, v106, v70, v175
	v_fma_f32 v176, v104, v65, v73
	v_fma_f32 v176, v105, v67, v176
	v_fma_f32 v176, v106, v68, v176
	v_fma_f32 v176, v107, v70, v176
	v_fma_f32 v177, v105, v65, v73
	v_fma_f32 v177, v106, v67, v177
	v_fma_f32 v177, v107, v68, v177
	v_fma_f32 v177, v108, v70, v177
	v_fma_f32 v178, v106, v65, v73
	v_fma_f32 v178, v107, v67, v178
	v_fma_f32 v178, v108, v68, v178
	v_fma_f32 v178, v109, v70, v178
	v_fma_f32 v179, v107, v65, v73
	v_fma_f32 v179, v108, v67, v179
	v_fma_f32 v179, v109, v68, v179
	v_fma_f32 v179, v110, v70, v179
	v_fma_f32 v180, v108, v65, v73
	v_fma_f32 v180, v109, v67, v180
	v_fma_f32 v180, v110, v68, v180
	v_fma_f32 v180, v111, v70, v180
	v_fma_f32 v181, v109, v65, v73
	v_fma_f32 v181, v110, v67, v181
	v_fma_f32 v181, v111, v68, v181
	v_fma_f32 v181, v112, v70, v181
	v_fma_f32 v182, v110, v65, v73
	v_fma_f32 v182, v111, v67, v182
	v_fma_f32 v182, v112, v68, v182
	v_fma_f32 v182, v113, v70, v182
	v_fma_f32 v183, v111, v65, v73
	v_fma_f32 v183, v112, v67, v183
	v_fma_f32 v183, v113, v68, v183
	v_fma_f32 v183, v114, v70, v183
	v_fma_f32 v184, v112, v65, v73
	v_fma_f32 v184, v113, v67, v184
	v_fma_f32 v184, v114, v68, v184
	v_fma_f32 v184, v115, v70, v184
	v_fma_f32 v185, v113, v65, v73
	v_fma_f32 v185, v114, v67, v185
	v_fma_f32 v185, v115, v68, v185
	v_fma_f32 v185, v116, v70, v185
	v_fma_f32 v186, v114, v65, v73
	v_fma_f32 v186, v115, v67, v186
	v_fma_f32 v186, v116, v68, v186
	v_fma_f32 v186, v117, v70, v186
	v_fma_f32 v187, v115, v65, v73
	v_fma_f32 v187, v116, v67, v187
	v_fma_f32 v187, v117, v68, v187
	v_fma_f32 v187, v118, v70, v187
	v_fma_f32 v188, v116, v65, v73
	v_fma_f32 v188, v117, v67, v188
	v_fma_f32 v188, v118, v68, v188
	v_fma_f32 v188, v119, v70, v188
	v_fma_f32 v189, v117, v65, v73
	v_fma_f32 v189, v118, v67, v189
	v_fma_f32 v189, v119, v68, v189
	v_fma_f32 v189, v120, v70, v189
	v_fma_f32 v190, v118, v65, v73
	v_fma_f32 v190, v119, v67, v190
	v_fma_f32 v190, v120, v68, v190
	v_fma_f32 v190, v121, v70, v190
	v_fma_f32 v191, v119, v65, v73
	v_fma_f32 v191, v120, v67, v191
	v_fma_f32 v191, v121, v68, v191
	v_fma_f32 v191, v122, v70, v191
	v_fma_f32 v192, v120, v65, v73
	v_fma_f32 v192, v121, v67, v192
	v_fma_f32 v192, v122, v68, v192
	v_fma_f32 v192, v123, v70, v192
	v_fma_f32 v193, v121, v65, v73
	v_fma_f32 v193, v122, v67, v193
	v_fma_f32 v193, v123, v68, v193
; __device__ __forceinline__ float bf2f(u16 h) { return __uint_as_float(((unsigned)h) << 16); }
; __device__ __forceinline__ void lru_tile(const Params& P, int chunk, int head, int pass, char* smem_raw) {
;     ...
;     float uv[35];
; #pragma unroll
;     for (int i = 0; i < 35; ++i) {
;       const int rr = r - 2 + i;
;       uv[i] = (rr >= seq_lo && rr < seq_hi) ? bf2f(zu[(long)rr * 1536]) : 0.f;
;     ...
; #pragma unroll
;     for (int i = 0; i < 32; ++i) {
;       const float v = cb + uv[i] * w0 + uv[i + 1] * w1 + uv[i + 2] * w2 + uv[i + 3] * w3;
;       sm_uc[(q * 32 + i) * LDSS + ch] = f2bf(v);
;     }
;   }
	v_fma_f32 v193, v124, v70, v193
	v_cvt_pk_bf16_f32 v162, v162, v162
	v_cvt_pk_bf16_f32 v163, v163, v163
	v_cvt_pk_bf16_f32 v164, v164, v164
	v_cvt_pk_bf16_f32 v165, v165, v165
	v_cvt_pk_bf16_f32 v166, v166, v166
	v_cvt_pk_bf16_f32 v167, v167, v167
	v_cvt_pk_bf16_f32 v168, v168, v168
	v_cvt_pk_bf16_f32 v169, v169, v169
	v_cvt_pk_bf16_f32 v170, v170, v170
	v_cvt_pk_bf16_f32 v171, v171, v171
	v_cvt_pk_bf16_f32 v172, v172, v172
	v_cvt_pk_bf16_f32 v173, v173, v173
	v_cvt_pk_bf16_f32 v174, v174, v174
	v_cvt_pk_bf16_f32 v175, v175, v175
	v_cvt_pk_bf16_f32 v176, v176, v176
	v_cvt_pk_bf16_f32 v177, v177, v177
	v_cvt_pk_bf16_f32 v178, v178, v178
	v_cvt_pk_bf16_f32 v179, v179, v179
	v_cvt_pk_bf16_f32 v180, v180, v180
	v_cvt_pk_bf16_f32 v181, v181, v181
	v_cvt_pk_bf16_f32 v182, v182, v182
	v_cvt_pk_bf16_f32 v183, v183, v183
	v_cvt_pk_bf16_f32 v184, v184, v184
	v_cvt_pk_bf16_f32 v185, v185, v185
	v_cvt_pk_bf16_f32 v186, v186, v186
	v_cvt_pk_bf16_f32 v187, v187, v187
	v_cvt_pk_bf16_f32 v188, v188, v188
	v_cvt_pk_bf16_f32 v189, v189, v189
	v_cvt_pk_bf16_f32 v190, v190, v190
	v_cvt_pk_bf16_f32 v191, v191, v191
	v_cvt_pk_bf16_f32 v192, v192, v192
	v_cvt_pk_bf16_f32 v193, v193, v193
	ds_write_b16 v89, v162 offset:0
	ds_write_b16 v89, v163 offset:128
	ds_write_b16 v130, v164 offset:256
	ds_write_b16 v130, v165 offset:384
	ds_write_b16 v89, v166 offset:512
	ds_write_b16 v89, v167 offset:640
	ds_write_b16 v130, v168 offset:768
	ds_write_b16 v130, v169 offset:896
	ds_write_b16 v89, v170 offset:1024
	ds_write_b16 v89, v171 offset:1152
	ds_write_b16 v130, v172 offset:1280
	ds_write_b16 v130, v173 offset:1408
	ds_write_b16 v89, v174 offset:1536
	ds_write_b16 v89, v175 offset:1664
	ds_write_b16 v130, v176 offset:1792
	ds_write_b16 v130, v177 offset:1920
	ds_write_b16 v89, v178 offset:2048
	ds_write_b16 v89, v179 offset:2176
	ds_write_b16 v130, v180 offset:2304
	ds_write_b16 v130, v181 offset:2432
	ds_write_b16 v89, v182 offset:2560
	ds_write_b16 v89, v183 offset:2688
	ds_write_b16 v130, v184 offset:2816
	ds_write_b16 v130, v185 offset:2944
	ds_write_b16 v89, v186 offset:3072
	ds_write_b16 v89, v187 offset:3200
	ds_write_b16 v130, v188 offset:3328
	ds_write_b16 v130, v189 offset:3456
	ds_write_b16 v89, v190 offset:3584
	ds_write_b16 v89, v191 offset:3712
	ds_write_b16 v130, v192 offset:3840
	ds_write_b16 v130, v193 offset:3968
	v_lshlrev_b32_e32 v162, 16, v162
	v_lshlrev_b32_e32 v163, 16, v163
	v_lshlrev_b32_e32 v164, 16, v164
	v_lshlrev_b32_e32 v165, 16, v165
	v_lshlrev_b32_e32 v166, 16, v166
	v_lshlrev_b32_e32 v167, 16, v167
	v_lshlrev_b32_e32 v168, 16, v168
	v_lshlrev_b32_e32 v169, 16, v169
	v_lshlrev_b32_e32 v170, 16, v170
	v_lshlrev_b32_e32 v171, 16, v171
	v_lshlrev_b32_e32 v172, 16, v172
	v_lshlrev_b32_e32 v173, 16, v173
	v_lshlrev_b32_e32 v174, 16, v174
	v_lshlrev_b32_e32 v175, 16, v175
	v_lshlrev_b32_e32 v176, 16, v176
	v_lshlrev_b32_e32 v177, 16, v177
	v_lshlrev_b32_e32 v178, 16, v178
	v_lshlrev_b32_e32 v179, 16, v179
	v_lshlrev_b32_e32 v180, 16, v180
	v_lshlrev_b32_e32 v181, 16, v181
	v_lshlrev_b32_e32 v182, 16, v182
	v_lshlrev_b32_e32 v183, 16, v183
	v_lshlrev_b32_e32 v184, 16, v184
	v_lshlrev_b32_e32 v185, 16, v185
	v_lshlrev_b32_e32 v186, 16, v186
	v_lshlrev_b32_e32 v187, 16, v187
	v_lshlrev_b32_e32 v188, 16, v188
	v_lshlrev_b32_e32 v189, 16, v189
	v_lshlrev_b32_e32 v190, 16, v190
	v_lshlrev_b32_e32 v191, 16, v191
	v_lshlrev_b32_e32 v192, 16, v192
	v_lshlrev_b32_e32 v193, 16, v193
	s_waitcnt lgkmcnt(0)
	s_barrier
	s_add_u32 s58, s69, 1
	s_cmp_lt_u32 s58, s70
	s_cbranch_scc0 .Lmy_lrua_nopf
	s_lshl_b32 s58, s58, 9
	s_add_u32 s58, s58, s68
	s_lshr_b32 s59, s58, 3
	s_cmp_lt_u32 s59, 256
	s_cselect_b32 s60, 63, 1
	s_and_b32 s57, s59, s60
	s_cmp_eq_u32 s57, 0
	s_cselect_b64 s[0:1], s[84:85], 0
	s_cmp_eq_u32 s57, s60
	s_cselect_b64 s[4:5], s[86:87], 0
	v_mov_b32_e32 v255, 0x1800
	v_cndmask_b32_e64 v150, 0, v255, s[0:1]
	v_lshlrev_b32_e32 v136, 1, v150
	v_add_u32_e32 v136, v134, v136
	v_add_u32_e32 v150, v134, v150
	v_cndmask_b32_e64 v151, 0, v255, s[4:5]
	v_sub_u32_e32 v151, v134, v151
	s_lshl_b32 s61, s59, 7
	s_mul_i32 s0, s61, 0xc00
	s_lshl_b32 s1, s56, 1
	s_add_u32 s0, s0, s1
	s_add_u32 s4, s10, s0
	s_addc_u32 s5, s11, 0
	s_sub_u32 s4, s4, 0x1800
	s_subb_u32 s5, s5, 0
	global_load_ushort v205, v136, s[4:5]
	s_add_u32 s4, s4, 0xc00
	s_addc_u32 s5, s5, 0
	global_load_ushort v206, v150, s[4:5]
	s_add_u32 s4, s4, 0xc00
	s_addc_u32 s5, s5, 0
	global_load_ushort v207, v134, s[4:5]
	s_add_u32 s4, s4, 0xc00
	s_addc_u32 s5, s5, 0
	global_load_ushort v208, v134, s[4:5]
	s_add_u32 s4, s4, 0xc00
	s_addc_u32 s5, s5, 0
	global_load_ushort v209, v134, s[4:5]
	s_add_u32 s4, s4, 0xc00
	s_addc_u32 s5, s5, 0
	global_load_ushort v210, v134, s[4:5]
	s_add_u32 s4, s4, 0xc00
	s_addc_u32 s5, s5, 0
	global_load_ushort v211, v134, s[4:5]
	s_add_u32 s4, s4, 0xc00
	s_addc_u32 s5, s5, 0
	global_load_ushort v212, v134, s[4:5]
	s_add_u32 s4, s4, 0xc00
	s_addc_u32 s5, s5, 0
	global_load_ushort v213, v134, s[4:5]
	s_add_u32 s4, s4, 0xc00
	s_addc_u32 s5, s5, 0
	global_load_ushort v214, v134, s[4:5]
	s_add_u32 s4, s4, 0xc00
	s_addc_u32 s5, s5, 0
	global_load_ushort v215, v134, s[4:5]
	s_add_u32 s4, s4, 0xc00
	s_addc_u32 s5, s5, 0
	global_load_ushort v216, v134, s[4:5]
	s_add_u32 s4, s4, 0xc00
	s_addc_u32 s5, s5, 0
	global_load_ushort v217, v134, s[4:5]
	s_add_u32 s4, s4, 0xc00
	s_addc_u32 s5, s5, 0
	global_load_ushort v218, v134, s[4:5]
	s_add_u32 s4, s4, 0xc00
	s_addc_u32 s5, s5, 0
	global_load_ushort v219, v134, s[4:5]
	s_add_u32 s4, s4, 0xc00
	s_addc_u32 s5, s5, 0
	global_load_ushort v220, v134, s[4:5]
	s_add_u32 s4, s4, 0xc00
	s_addc_u32 s5, s5, 0
	global_load_ushort v221, v134, s[4:5]
; __device__ __forceinline__ float bf2f(u16 h) { return __uint_as_float(((unsigned)h) << 16); }
; __device__ __forceinline__ void lru_tile(const Params& P, int chunk, int head, int pass, char* smem_raw) {
;     ...
;     float uv[35];
; #pragma unroll
;     for (int i = 0; i < 35; ++i) {
;       const int rr = r - 2 + i;
;       uv[i] = (rr >= seq_lo && rr < seq_hi) ? bf2f(zu[(long)rr * 1536]) : 0.f;
;     ...
;       for (int s = 0; s < 2; ++s) {
;         const bf16x8 af = *reinterpret_cast<const bf16x8*>(&sm_uc[(sb * 64 + wid * 16 + (lane & 15)) * LDSS + s * 32 + (lane >> 4) * 8]);
; #pragma unroll
;         for (int t = 0; t < 8; ++t) {
;           const bf16x8 bfr = *reinterpret_cast<const bf16x8*>(&sm_w[(t * 16 + (lane & 15)) * LDSS + s * 32 + (lane >> 4) * 8]);
;           acc[t] = __builtin_amdgcn_mfma_f32_16x16x32_bf16(af, bfr, acc[t], 0, 0, 0);
;         }
;       }
	s_add_u32 s4, s4, 0xc00
	s_addc_u32 s5, s5, 0
	global_load_ushort v222, v134, s[4:5]
	s_add_u32 s4, s4, 0xc00
	s_addc_u32 s5, s5, 0
	global_load_ushort v223, v134, s[4:5]
	s_add_u32 s4, s4, 0xc00
	s_addc_u32 s5, s5, 0
	global_load_ushort v224, v134, s[4:5]
	s_add_u32 s4, s4, 0xc00
	s_addc_u32 s5, s5, 0
	global_load_ushort v225, v134, s[4:5]
	s_add_u32 s4, s4, 0xc00
	s_addc_u32 s5, s5, 0
	global_load_ushort v226, v134, s[4:5]
	s_add_u32 s4, s4, 0xc00
	s_addc_u32 s5, s5, 0
	global_load_ushort v227, v134, s[4:5]
	s_add_u32 s4, s4, 0xc00
	s_addc_u32 s5, s5, 0
	global_load_ushort v228, v134, s[4:5]
	s_add_u32 s4, s4, 0xc00
	s_addc_u32 s5, s5, 0
	global_load_ushort v229, v134, s[4:5]
	s_add_u32 s4, s4, 0xc00
	s_addc_u32 s5, s5, 0
	global_load_ushort v230, v134, s[4:5]
	s_add_u32 s4, s4, 0xc00
	s_addc_u32 s5, s5, 0
	global_load_ushort v231, v134, s[4:5]
	s_add_u32 s4, s4, 0xc00
	s_addc_u32 s5, s5, 0
	global_load_ushort v232, v134, s[4:5]
	s_add_u32 s4, s4, 0xc00
	s_addc_u32 s5, s5, 0
	global_load_ushort v233, v134, s[4:5]
	s_add_u32 s4, s4, 0xc00
	s_addc_u32 s5, s5, 0
	global_load_ushort v234, v134, s[4:5]
	s_add_u32 s4, s4, 0xc00
	s_addc_u32 s5, s5, 0
	global_load_ushort v235, v134, s[4:5]
	s_add_u32 s4, s4, 0xc00
	s_addc_u32 s5, s5, 0
	global_load_ushort v236, v134, s[4:5]
	s_add_u32 s4, s4, 0xc00
	s_addc_u32 s5, s5, 0
	global_load_ushort v142, v134, s[4:5]
	s_add_u32 s4, s4, 0xc00
	s_addc_u32 s5, s5, 0
	global_load_ushort v143, v134, s[4:5]
	s_add_u32 s4, s4, 0xc00
	s_addc_u32 s5, s5, 0
	global_load_ushort v144, v151, s[4:5]
.Lmy_lrua_nopf:
	ds_read_b128 v[76:79], v131 offset:0
	ds_read_b128 v[80:83], v133 offset:0
	ds_read_b128 v[122:125], v131 offset:512
	ds_read_b128 v[126:129], v133 offset:512
	s_waitcnt lgkmcnt(3)
	v_mfma_f32_16x16x32_bf16 v[0:3], v[76:79], v[238:241], 0
	v_mfma_f32_16x16x32_bf16 v[90:93], v[76:79], v[246:249], 0
	ds_read_b128 v[76:79], v131 offset:1024
	s_waitcnt lgkmcnt(3)
	v_mfma_f32_16x16x32_bf16 v[0:3], v[80:83], v[242:245], v[0:3]
	v_mfma_f32_16x16x32_bf16 v[90:93], v[80:83], v[194:197], v[90:93]
	ds_read_b128 v[80:83], v133 offset:1024
	s_waitcnt lgkmcnt(3)
	v_mfma_f32_16x16x32_bf16 v[4:7], v[122:125], v[238:241], 0
	v_mfma_f32_16x16x32_bf16 v[94:97], v[122:125], v[246:249], 0
	ds_read_b128 v[122:125], v131 offset:1536
	s_waitcnt lgkmcnt(3)
	v_mfma_f32_16x16x32_bf16 v[4:7], v[126:129], v[242:245], v[4:7]
	v_mfma_f32_16x16x32_bf16 v[94:97], v[126:129], v[194:197], v[94:97]
	ds_read_b128 v[126:129], v133 offset:1536
	s_waitcnt lgkmcnt(3)
	v_mfma_f32_16x16x32_bf16 v[8:11], v[76:79], v[238:241], 0
	v_mfma_f32_16x16x32_bf16 v[98:101], v[76:79], v[246:249], 0
	ds_read_b128 v[76:79], v131 offset:2048
	s_waitcnt lgkmcnt(3)
	v_mfma_f32_16x16x32_bf16 v[8:11], v[80:83], v[242:245], v[8:11]
	v_mfma_f32_16x16x32_bf16 v[98:101], v[80:83], v[194:197], v[98:101]
	ds_read_b128 v[80:83], v133 offset:2048
	s_waitcnt lgkmcnt(3)
	v_mfma_f32_16x16x32_bf16 v[12:15], v[122:125], v[238:241], 0
	v_mfma_f32_16x16x32_bf16 v[102:105], v[122:125], v[246:249], 0
	ds_read_b128 v[122:125], v131 offset:2560
	s_waitcnt lgkmcnt(3)
	v_mfma_f32_16x16x32_bf16 v[12:15], v[126:129], v[242:245], v[12:15]
	v_mfma_f32_16x16x32_bf16 v[102:105], v[126:129], v[194:197], v[102:105]
	ds_read_b128 v[126:129], v133 offset:2560
	s_waitcnt lgkmcnt(3)
	v_mfma_f32_16x16x32_bf16 v[16:19], v[76:79], v[238:241], 0
	v_mfma_f32_16x16x32_bf16 v[106:109], v[76:79], v[246:249], 0
	ds_read_b128 v[76:79], v131 offset:3072
	s_waitcnt lgkmcnt(3)
	v_mfma_f32_16x16x32_bf16 v[16:19], v[80:83], v[242:245], v[16:19]
	v_mfma_f32_16x16x32_bf16 v[106:109], v[80:83], v[194:197], v[106:109]
	ds_read_b128 v[80:83], v133 offset:3072
	s_waitcnt lgkmcnt(3)
	v_mfma_f32_16x16x32_bf16 v[20:23], v[122:125], v[238:241], 0
	v_mfma_f32_16x16x32_bf16 v[110:113], v[122:125], v[246:249], 0
	ds_read_b128 v[122:125], v131 offset:3584
	s_waitcnt lgkmcnt(3)
	v_mfma_f32_16x16x32_bf16 v[20:23], v[126:129], v[242:245], v[20:23]
	v_mfma_f32_16x16x32_bf16 v[110:113], v[126:129], v[194:197], v[110:113]
	ds_read_b128 v[126:129], v133 offset:3584
	s_waitcnt lgkmcnt(3)
	v_mfma_f32_16x16x32_bf16 v[24:27], v[76:79], v[238:241], 0
	v_mfma_f32_16x16x32_bf16 v[114:117], v[76:79], v[246:249], 0
	s_waitcnt lgkmcnt(2)
	v_mfma_f32_16x16x32_bf16 v[24:27], v[80:83], v[242:245], v[24:27]
	v_mfma_f32_16x16x32_bf16 v[114:117], v[80:83], v[194:197], v[114:117]
	s_waitcnt lgkmcnt(1)
	v_mfma_f32_16x16x32_bf16 v[28:31], v[122:125], v[238:241], 0
	v_mfma_f32_16x16x32_bf16 v[118:121], v[122:125], v[246:249], 0
	s_waitcnt lgkmcnt(0)
; __device__ __forceinline__ float bf2f(u16 h) { return __uint_as_float(((unsigned)h) << 16); }
; __device__ __forceinline__ void lru_tile(const Params& P, int chunk, int head, int pass, char* smem_raw) {
;     ...
; #pragma unroll
;       for (int tc = 0; tc < 4; ++tc)
; #pragma unroll
;         for (int reg = 0; reg < 4; ++reg) {
;           const int tl = wid * 16 + (lane >> 4) * 4 + reg;
;           const int c = 16 * tc + (lane & 15);
;           const float r = __builtin_amdgcn_rcpf(1.f + __builtin_amdgcn_exp2f(acc[tc][reg] + ba[tc]));
;           const float ii = __builtin_amdgcn_rcpf(1.f + __builtin_amdgcn_exp2f(acc[tc + 4][reg] + bi[tc]));
;           const float la = -c8[tc] * r;
;           const float a = __builtin_amdgcn_exp2f(la);
;           const float ucv = bf2f(sm_uc[(sb * 64 + tl) * LDSS + c]);
;           const float bt = __builtin_amdgcn_sqrtf(fmaxf(1.f - a * a, 0.f)) * (ii * ucv);
;           sm_a[tl * 64 + c] = a;
;           sm_b[tl * 64 + c] = bt;
;         }
	v_mfma_f32_16x16x32_bf16 v[28:31], v[126:129], v[242:245], v[28:31]
	v_mfma_f32_16x16x32_bf16 v[118:121], v[126:129], v[194:197], v[118:121]
	s_lshl_b32 s0, s56, 8
	s_add_u32 s0, s0, 0x20000
	s_add_u32 s4, s20, s0
	s_addc_u32 s5, s21, 0
	global_load_dwordx4 v[238:241], v251, s[4:5]
	global_load_dwordx4 v[242:245], v251, s[4:5] offset:64
	s_add_u32 s4, s4, 0x2000
	s_addc_u32 s5, s5, 0
	global_load_dwordx4 v[246:249], v251, s[4:5]
	global_load_dwordx4 v[194:197], v251, s[4:5] offset:64
	s_nop 7
	s_nop 7
	v_add_f32_e32 v0, v0, v75
	v_add_f32_e32 v1, v1, v75
	v_add_f32_e32 v2, v2, v75
	v_add_f32_e32 v3, v3, v75
	v_add_f32_e32 v90, v90, v84
	v_add_f32_e32 v91, v91, v84
	v_add_f32_e32 v92, v92, v84
	v_add_f32_e32 v93, v93, v84
	v_exp_f32_e32 v0, v0
	v_exp_f32_e32 v1, v1
	v_exp_f32_e32 v2, v2
	v_exp_f32_e32 v3, v3
	v_exp_f32_e32 v90, v90
	v_exp_f32_e32 v91, v91
	v_exp_f32_e32 v92, v92
	v_exp_f32_e32 v93, v93
	v_add_f32_e32 v0, 1.0, v0
	v_add_f32_e32 v1, 1.0, v1
	v_add_f32_e32 v2, 1.0, v2
	v_add_f32_e32 v3, 1.0, v3
	v_add_f32_e32 v90, 1.0, v90
	v_add_f32_e32 v91, 1.0, v91
	v_add_f32_e32 v92, 1.0, v92
	v_add_f32_e32 v93, 1.0, v93
	v_rcp_f32_e32 v0, v0
	v_rcp_f32_e32 v1, v1
	v_rcp_f32_e32 v2, v2
	v_rcp_f32_e32 v3, v3
	v_rcp_f32_e32 v90, v90
	v_rcp_f32_e32 v91, v91
	v_rcp_f32_e32 v92, v92
	v_rcp_f32_e32 v93, v93
	v_mul_f32_e32 v0, v85, v0
	v_mul_f32_e32 v1, v85, v1
	v_mul_f32_e32 v2, v85, v2
	v_mul_f32_e32 v3, v85, v3
	v_mul_f32_e32 v90, v90, v162
	v_mul_f32_e32 v91, v91, v163
	v_mul_f32_e32 v92, v92, v164
	v_mul_f32_e32 v93, v93, v165
	v_exp_f32_e32 v0, v0
	v_exp_f32_e32 v1, v1
	v_exp_f32_e32 v2, v2
	v_exp_f32_e32 v3, v3
	s_nop 0
	v_fma_f32 v138, -v0, v0, 1.0
	v_fma_f32 v139, -v1, v1, 1.0
	v_fma_f32 v140, -v2, v2, 1.0
	v_fma_f32 v141, -v3, v3, 1.0
	v_max_f32_e32 v138, 0, v138
	v_max_f32_e32 v139, 0, v139
	v_max_f32_e32 v140, 0, v140
	v_max_f32_e32 v141, 0, v141
	v_sqrt_f32_e32 v138, v138
	v_sqrt_f32_e32 v139, v139
	v_sqrt_f32_e32 v140, v140
	v_sqrt_f32_e32 v141, v141
	s_nop 0
	v_mul_f32_e32 v90, v138, v90
	v_mul_f32_e32 v91, v139, v91
	v_mul_f32_e32 v92, v140, v92
	v_mul_f32_e32 v93, v141, v93
	v_add_f32_e32 v4, v4, v75
	v_add_f32_e32 v5, v5, v75
	v_add_f32_e32 v6, v6, v75
	v_add_f32_e32 v7, v7, v75
	v_add_f32_e32 v94, v94, v84
	v_add_f32_e32 v95, v95, v84
	v_add_f32_e32 v96, v96, v84
	v_add_f32_e32 v97, v97, v84
	v_exp_f32_e32 v4, v4
	v_exp_f32_e32 v5, v5
	v_exp_f32_e32 v6, v6
	v_exp_f32_e32 v7, v7
	v_exp_f32_e32 v94, v94
	v_exp_f32_e32 v95, v95
	v_exp_f32_e32 v96, v96
	v_exp_f32_e32 v97, v97
	v_add_f32_e32 v4, 1.0, v4
	v_add_f32_e32 v5, 1.0, v5
	v_add_f32_e32 v6, 1.0, v6
	v_add_f32_e32 v7, 1.0, v7
	v_add_f32_e32 v94, 1.0, v94
	v_add_f32_e32 v95, 1.0, v95
	v_add_f32_e32 v96, 1.0, v96
	v_add_f32_e32 v97, 1.0, v97
	v_rcp_f32_e32 v4, v4
	v_rcp_f32_e32 v5, v5
	v_rcp_f32_e32 v6, v6
	v_rcp_f32_e32 v7, v7
	v_rcp_f32_e32 v94, v94
	v_rcp_f32_e32 v95, v95
	v_rcp_f32_e32 v96, v96
	v_rcp_f32_e32 v97, v97
	v_mul_f32_e32 v4, v85, v4
	v_mul_f32_e32 v5, v85, v5
	v_mul_f32_e32 v6, v85, v6
	v_mul_f32_e32 v7, v85, v7
	v_mul_f32_e32 v94, v94, v166
	v_mul_f32_e32 v95, v95, v167
	v_mul_f32_e32 v96, v96, v168
	v_mul_f32_e32 v97, v97, v169
	v_exp_f32_e32 v4, v4
	v_exp_f32_e32 v5, v5
	v_exp_f32_e32 v6, v6
	v_exp_f32_e32 v7, v7
	s_nop 0
	v_fma_f32 v138, -v4, v4, 1.0
	v_fma_f32 v139, -v5, v5, 1.0
	v_fma_f32 v140, -v6, v6, 1.0
	v_fma_f32 v141, -v7, v7, 1.0
	v_max_f32_e32 v138, 0, v138
	v_max_f32_e32 v139, 0, v139
	v_max_f32_e32 v140, 0, v140
	v_max_f32_e32 v141, 0, v141
	v_sqrt_f32_e32 v138, v138
	v_sqrt_f32_e32 v139, v139
	v_sqrt_f32_e32 v140, v140
	v_sqrt_f32_e32 v141, v141
	s_nop 0
	v_mul_f32_e32 v94, v138, v94
	v_mul_f32_e32 v95, v139, v95
	v_mul_f32_e32 v96, v140, v96
	v_mul_f32_e32 v97, v141, v97
	v_add_f32_e32 v8, v8, v75
	v_add_f32_e32 v9, v9, v75
	v_add_f32_e32 v10, v10, v75
	v_add_f32_e32 v11, v11, v75
	v_add_f32_e32 v98, v98, v84
	v_add_f32_e32 v99, v99, v84
	v_add_f32_e32 v100, v100, v84
	v_add_f32_e32 v101, v101, v84
	v_exp_f32_e32 v8, v8
	v_exp_f32_e32 v9, v9
	v_exp_f32_e32 v10, v10
	v_exp_f32_e32 v11, v11
	v_exp_f32_e32 v98, v98
	v_exp_f32_e32 v99, v99
	v_exp_f32_e32 v100, v100
	v_exp_f32_e32 v101, v101
	v_add_f32_e32 v8, 1.0, v8
	v_add_f32_e32 v9, 1.0, v9
	v_add_f32_e32 v10, 1.0, v10
	v_add_f32_e32 v11, 1.0, v11
	v_add_f32_e32 v98, 1.0, v98
	v_add_f32_e32 v99, 1.0, v99
	v_add_f32_e32 v100, 1.0, v100
	v_add_f32_e32 v101, 1.0, v101
	v_rcp_f32_e32 v8, v8
	v_rcp_f32_e32 v9, v9
	v_rcp_f32_e32 v10, v10
	v_rcp_f32_e32 v11, v11
	v_rcp_f32_e32 v98, v98
	v_rcp_f32_e32 v99, v99
	v_rcp_f32_e32 v100, v100
	v_rcp_f32_e32 v101, v101
	v_mul_f32_e32 v8, v85, v8
	v_mul_f32_e32 v9, v85, v9
	v_mul_f32_e32 v10, v85, v10
	v_mul_f32_e32 v11, v85, v11
	v_mul_f32_e32 v98, v98, v170
	v_mul_f32_e32 v99, v99, v171
	v_mul_f32_e32 v100, v100, v172
	v_mul_f32_e32 v101, v101, v173
	v_exp_f32_e32 v8, v8
	v_exp_f32_e32 v9, v9
	v_exp_f32_e32 v10, v10
	v_exp_f32_e32 v11, v11
	s_nop 0
	v_fma_f32 v138, -v8, v8, 1.0
	v_fma_f32 v139, -v9, v9, 1.0
	v_fma_f32 v140, -v10, v10, 1.0
	v_fma_f32 v141, -v11, v11, 1.0
	v_max_f32_e32 v138, 0, v138
	v_max_f32_e32 v139, 0, v139
	v_max_f32_e32 v140, 0, v140
	v_max_f32_e32 v141, 0, v141
	v_sqrt_f32_e32 v138, v138
	v_sqrt_f32_e32 v139, v139
	v_sqrt_f32_e32 v140, v140
	v_sqrt_f32_e32 v141, v141
	s_nop 0
	v_mul_f32_e32 v98, v138, v98
	v_mul_f32_e32 v99, v139, v99
	v_mul_f32_e32 v100, v140, v100
	v_mul_f32_e32 v101, v141, v101
	v_add_f32_e32 v12, v12, v75
	v_add_f32_e32 v13, v13, v75
	v_add_f32_e32 v14, v14, v75
	v_add_f32_e32 v15, v15, v75
	v_add_f32_e32 v102, v102, v84
	v_add_f32_e32 v103, v103, v84
	v_add_f32_e32 v104, v104, v84
	v_add_f32_e32 v105, v105, v84
; __device__ __forceinline__ float bf2f(u16 h) { return __uint_as_float(((unsigned)h) << 16); }
; __device__ __forceinline__ void lru_tile(const Params& P, int chunk, int head, int pass, char* smem_raw) {
;     ...
; #pragma unroll
;       for (int tc = 0; tc < 4; ++tc)
; #pragma unroll
;         for (int reg = 0; reg < 4; ++reg) {
;           const int tl = wid * 16 + (lane >> 4) * 4 + reg;
;           const int c = 16 * tc + (lane & 15);
;           const float r = __builtin_amdgcn_rcpf(1.f + __builtin_amdgcn_exp2f(acc[tc][reg] + ba[tc]));
;           const float ii = __builtin_amdgcn_rcpf(1.f + __builtin_amdgcn_exp2f(acc[tc + 4][reg] + bi[tc]));
;           const float la = -c8[tc] * r;
;           const float a = __builtin_amdgcn_exp2f(la);
;           const float ucv = bf2f(sm_uc[(sb * 64 + tl) * LDSS + c]);
;           const float bt = __builtin_amdgcn_sqrtf(fmaxf(1.f - a * a, 0.f)) * (ii * ucv);
;           sm_a[tl * 64 + c] = a;
;           sm_b[tl * 64 + c] = bt;
;         }
	v_exp_f32_e32 v12, v12
	v_exp_f32_e32 v13, v13
	v_exp_f32_e32 v14, v14
	v_exp_f32_e32 v15, v15
	v_exp_f32_e32 v102, v102
	v_exp_f32_e32 v103, v103
	v_exp_f32_e32 v104, v104
	v_exp_f32_e32 v105, v105
	v_add_f32_e32 v12, 1.0, v12
	v_add_f32_e32 v13, 1.0, v13
	v_add_f32_e32 v14, 1.0, v14
	v_add_f32_e32 v15, 1.0, v15
	v_add_f32_e32 v102, 1.0, v102
	v_add_f32_e32 v103, 1.0, v103
	v_add_f32_e32 v104, 1.0, v104
	v_add_f32_e32 v105, 1.0, v105
	v_rcp_f32_e32 v12, v12
	v_rcp_f32_e32 v13, v13
	v_rcp_f32_e32 v14, v14
	v_rcp_f32_e32 v15, v15
	v_rcp_f32_e32 v102, v102
	v_rcp_f32_e32 v103, v103
	v_rcp_f32_e32 v104, v104
	v_rcp_f32_e32 v105, v105
	v_mul_f32_e32 v12, v85, v12
	v_mul_f32_e32 v13, v85, v13
	v_mul_f32_e32 v14, v85, v14
	v_mul_f32_e32 v15, v85, v15
	v_mul_f32_e32 v102, v102, v174
	v_mul_f32_e32 v103, v103, v175
	v_mul_f32_e32 v104, v104, v176
	v_mul_f32_e32 v105, v105, v177
	v_exp_f32_e32 v12, v12
	v_exp_f32_e32 v13, v13
	v_exp_f32_e32 v14, v14
	v_exp_f32_e32 v15, v15
	s_nop 0
	v_fma_f32 v138, -v12, v12, 1.0
	v_fma_f32 v139, -v13, v13, 1.0
	v_fma_f32 v140, -v14, v14, 1.0
	v_fma_f32 v141, -v15, v15, 1.0
	v_max_f32_e32 v138, 0, v138
	v_max_f32_e32 v139, 0, v139
	v_max_f32_e32 v140, 0, v140
	v_max_f32_e32 v141, 0, v141
	v_sqrt_f32_e32 v138, v138
	v_sqrt_f32_e32 v139, v139
	v_sqrt_f32_e32 v140, v140
	v_sqrt_f32_e32 v141, v141
	s_nop 0
	v_mul_f32_e32 v102, v138, v102
	v_mul_f32_e32 v103, v139, v103
	v_mul_f32_e32 v104, v140, v104
	v_mul_f32_e32 v105, v141, v105
	v_add_f32_e32 v16, v16, v75
	v_add_f32_e32 v17, v17, v75
	v_add_f32_e32 v18, v18, v75
	v_add_f32_e32 v19, v19, v75
	v_add_f32_e32 v106, v106, v84
	v_add_f32_e32 v107, v107, v84
	v_add_f32_e32 v108, v108, v84
	v_add_f32_e32 v109, v109, v84
	v_exp_f32_e32 v16, v16
	v_exp_f32_e32 v17, v17
	v_exp_f32_e32 v18, v18
	v_exp_f32_e32 v19, v19
	v_exp_f32_e32 v106, v106
	v_exp_f32_e32 v107, v107
	v_exp_f32_e32 v108, v108
	v_exp_f32_e32 v109, v109
	v_add_f32_e32 v16, 1.0, v16
	v_add_f32_e32 v17, 1.0, v17
	v_add_f32_e32 v18, 1.0, v18
	v_add_f32_e32 v19, 1.0, v19
	v_add_f32_e32 v106, 1.0, v106
	v_add_f32_e32 v107, 1.0, v107
	v_add_f32_e32 v108, 1.0, v108
	v_add_f32_e32 v109, 1.0, v109
	v_rcp_f32_e32 v16, v16
	v_rcp_f32_e32 v17, v17
	v_rcp_f32_e32 v18, v18
	v_rcp_f32_e32 v19, v19
	v_rcp_f32_e32 v106, v106
	v_rcp_f32_e32 v107, v107
	v_rcp_f32_e32 v108, v108
	v_rcp_f32_e32 v109, v109
	v_mul_f32_e32 v16, v85, v16
	v_mul_f32_e32 v17, v85, v17
	v_mul_f32_e32 v18, v85, v18
	v_mul_f32_e32 v19, v85, v19
	v_mul_f32_e32 v106, v106, v178
	v_mul_f32_e32 v107, v107, v179
	v_mul_f32_e32 v108, v108, v180
	v_mul_f32_e32 v109, v109, v181
	v_exp_f32_e32 v16, v16
	v_exp_f32_e32 v17, v17
	v_exp_f32_e32 v18, v18
	v_exp_f32_e32 v19, v19
	s_nop 0
	v_fma_f32 v138, -v16, v16, 1.0
	v_fma_f32 v139, -v17, v17, 1.0
	v_fma_f32 v140, -v18, v18, 1.0
	v_fma_f32 v141, -v19, v19, 1.0
	v_max_f32_e32 v138, 0, v138
	v_max_f32_e32 v139, 0, v139
	v_max_f32_e32 v140, 0, v140
	v_max_f32_e32 v141, 0, v141
	v_sqrt_f32_e32 v138, v138
	v_sqrt_f32_e32 v139, v139
	v_sqrt_f32_e32 v140, v140
	v_sqrt_f32_e32 v141, v141
	s_nop 0
	v_mul_f32_e32 v106, v138, v106
	v_mul_f32_e32 v107, v139, v107
	v_mul_f32_e32 v108, v140, v108
	v_mul_f32_e32 v109, v141, v109
	v_add_f32_e32 v20, v20, v75
	v_add_f32_e32 v21, v21, v75
	v_add_f32_e32 v22, v22, v75
	v_add_f32_e32 v23, v23, v75
	v_add_f32_e32 v110, v110, v84
	v_add_f32_e32 v111, v111, v84
	v_add_f32_e32 v112, v112, v84
	v_add_f32_e32 v113, v113, v84
	v_exp_f32_e32 v20, v20
	v_exp_f32_e32 v21, v21
	v_exp_f32_e32 v22, v22
	v_exp_f32_e32 v23, v23
	v_exp_f32_e32 v110, v110
	v_exp_f32_e32 v111, v111
	v_exp_f32_e32 v112, v112
	v_exp_f32_e32 v113, v113
	v_add_f32_e32 v20, 1.0, v20
	v_add_f32_e32 v21, 1.0, v21
	v_add_f32_e32 v22, 1.0, v22
	v_add_f32_e32 v23, 1.0, v23
	v_add_f32_e32 v110, 1.0, v110
	v_add_f32_e32 v111, 1.0, v111
	v_add_f32_e32 v112, 1.0, v112
	v_add_f32_e32 v113, 1.0, v113
	v_rcp_f32_e32 v20, v20
	v_rcp_f32_e32 v21, v21
	v_rcp_f32_e32 v22, v22
	v_rcp_f32_e32 v23, v23
	v_rcp_f32_e32 v110, v110
	v_rcp_f32_e32 v111, v111
	v_rcp_f32_e32 v112, v112
	v_rcp_f32_e32 v113, v113
	v_mul_f32_e32 v20, v85, v20
	v_mul_f32_e32 v21, v85, v21
	v_mul_f32_e32 v22, v85, v22
	v_mul_f32_e32 v23, v85, v23
	v_mul_f32_e32 v110, v110, v182
	v_mul_f32_e32 v111, v111, v183
	v_mul_f32_e32 v112, v112, v184
	v_mul_f32_e32 v113, v113, v185
	v_exp_f32_e32 v20, v20
	v_exp_f32_e32 v21, v21
	v_exp_f32_e32 v22, v22
	v_exp_f32_e32 v23, v23
	s_nop 0
	v_fma_f32 v138, -v20, v20, 1.0
	v_fma_f32 v139, -v21, v21, 1.0
	v_fma_f32 v140, -v22, v22, 1.0
	v_fma_f32 v141, -v23, v23, 1.0
	v_max_f32_e32 v138, 0, v138
	v_max_f32_e32 v139, 0, v139
	v_max_f32_e32 v140, 0, v140
	v_max_f32_e32 v141, 0, v141
	v_sqrt_f32_e32 v138, v138
	v_sqrt_f32_e32 v139, v139
	v_sqrt_f32_e32 v140, v140
	v_sqrt_f32_e32 v141, v141
	s_nop 0
	v_mul_f32_e32 v110, v138, v110
	v_mul_f32_e32 v111, v139, v111
	v_mul_f32_e32 v112, v140, v112
	v_mul_f32_e32 v113, v141, v113
	v_add_f32_e32 v24, v24, v75
	v_add_f32_e32 v25, v25, v75
	v_add_f32_e32 v26, v26, v75
	v_add_f32_e32 v27, v27, v75
	v_add_f32_e32 v114, v114, v84
	v_add_f32_e32 v115, v115, v84
	v_add_f32_e32 v116, v116, v84
	v_add_f32_e32 v117, v117, v84
	v_exp_f32_e32 v24, v24
	v_exp_f32_e32 v25, v25
	v_exp_f32_e32 v26, v26
	v_exp_f32_e32 v27, v27
	v_exp_f32_e32 v114, v114
	v_exp_f32_e32 v115, v115
	v_exp_f32_e32 v116, v116
	v_exp_f32_e32 v117, v117
	v_add_f32_e32 v24, 1.0, v24
	v_add_f32_e32 v25, 1.0, v25
	v_add_f32_e32 v26, 1.0, v26
	v_add_f32_e32 v27, 1.0, v27
	v_add_f32_e32 v114, 1.0, v114
	v_add_f32_e32 v115, 1.0, v115
	v_add_f32_e32 v116, 1.0, v116
	v_add_f32_e32 v117, 1.0, v117
	v_rcp_f32_e32 v24, v24
	v_rcp_f32_e32 v25, v25
; __device__ __forceinline__ float bf2f(u16 h) { return __uint_as_float(((unsigned)h) << 16); }
; __device__ __forceinline__ void lru_tile(const Params& P, int chunk, int head, int pass, char* smem_raw) {
;     ...
;           const float r = __builtin_amdgcn_rcpf(1.f + __builtin_amdgcn_exp2f(acc[tc][reg] + ba[tc]));
;           const float ii = __builtin_amdgcn_rcpf(1.f + __builtin_amdgcn_exp2f(acc[tc + 4][reg] + bi[tc]));
;           const float la = -c8[tc] * r;
;           const float a = __builtin_amdgcn_exp2f(la);
;           const float ucv = bf2f(sm_uc[(sb * 64 + tl) * LDSS + c]);
;           const float bt = __builtin_amdgcn_sqrtf(fmaxf(1.f - a * a, 0.f)) * (ii * ucv);
;           sm_a[tl * 64 + c] = a;
;           sm_b[tl * 64 + c] = bt;
;         }
;       __syncthreads();
;       const int pos = (d == 0) ? q : 3 - q;
;       {
;         float Pp = 1.f, H = 0.f;
; #pragma unroll 4
;         for (int i = 0; i < 16; ++i) {
;           const int tl = (d == 0) ? (q * 16 + i) : (q * 16 + 15 - i);
;           const float a = sm_a[tl * 64 + ch], b = sm_b[tl * 64 + ch];
;           H = a * H + b; Pp *= a;
;         }
;         sm_ph[pos * 64 + ch] = make_float2(Pp, H);
;     ...
;       cB = p0.x * cB + p0.y; cA *= p0.x;
;       cB = p1.x * cB + p1.y; cA *= p1.x;
;       cB = p2.x * cB + p2.y; cA *= p2.x;
;       cB = p3.x * cB + p3.y; cA *= p3.x;
;       __syncthreads();
;     }
;     if (pass == 1 && q == 0) P.summ[((long)d * 264 + chunk) * 512 + gch] = make_float2(cA, cB);
	v_rcp_f32_e32 v26, v26
	v_rcp_f32_e32 v27, v27
	v_rcp_f32_e32 v114, v114
	v_rcp_f32_e32 v115, v115
	v_rcp_f32_e32 v116, v116
	v_rcp_f32_e32 v117, v117
	v_mul_f32_e32 v24, v85, v24
	v_mul_f32_e32 v25, v85, v25
	v_mul_f32_e32 v26, v85, v26
	v_mul_f32_e32 v27, v85, v27
	v_mul_f32_e32 v114, v114, v186
	v_mul_f32_e32 v115, v115, v187
	v_mul_f32_e32 v116, v116, v188
	v_mul_f32_e32 v117, v117, v189
	v_exp_f32_e32 v24, v24
	v_exp_f32_e32 v25, v25
	v_exp_f32_e32 v26, v26
	v_exp_f32_e32 v27, v27
	s_nop 0
	v_fma_f32 v138, -v24, v24, 1.0
	v_fma_f32 v139, -v25, v25, 1.0
	v_fma_f32 v140, -v26, v26, 1.0
	v_fma_f32 v141, -v27, v27, 1.0
	v_max_f32_e32 v138, 0, v138
	v_max_f32_e32 v139, 0, v139
	v_max_f32_e32 v140, 0, v140
	v_max_f32_e32 v141, 0, v141
	v_sqrt_f32_e32 v138, v138
	v_sqrt_f32_e32 v139, v139
	v_sqrt_f32_e32 v140, v140
	v_sqrt_f32_e32 v141, v141
	s_nop 0
	v_mul_f32_e32 v114, v138, v114
	v_mul_f32_e32 v115, v139, v115
	v_mul_f32_e32 v116, v140, v116
	v_mul_f32_e32 v117, v141, v117
	v_add_f32_e32 v28, v28, v75
	v_add_f32_e32 v29, v29, v75
	v_add_f32_e32 v30, v30, v75
	v_add_f32_e32 v31, v31, v75
	v_add_f32_e32 v118, v118, v84
	v_add_f32_e32 v119, v119, v84
	v_add_f32_e32 v120, v120, v84
	v_add_f32_e32 v121, v121, v84
	v_exp_f32_e32 v28, v28
	v_exp_f32_e32 v29, v29
	v_exp_f32_e32 v30, v30
	v_exp_f32_e32 v31, v31
	v_exp_f32_e32 v118, v118
	v_exp_f32_e32 v119, v119
	v_exp_f32_e32 v120, v120
	v_exp_f32_e32 v121, v121
	v_add_f32_e32 v28, 1.0, v28
	v_add_f32_e32 v29, 1.0, v29
	v_add_f32_e32 v30, 1.0, v30
	v_add_f32_e32 v31, 1.0, v31
	v_add_f32_e32 v118, 1.0, v118
	v_add_f32_e32 v119, 1.0, v119
	v_add_f32_e32 v120, 1.0, v120
	v_add_f32_e32 v121, 1.0, v121
	v_rcp_f32_e32 v28, v28
	v_rcp_f32_e32 v29, v29
	v_rcp_f32_e32 v30, v30
	v_rcp_f32_e32 v31, v31
	v_rcp_f32_e32 v118, v118
	v_rcp_f32_e32 v119, v119
	v_rcp_f32_e32 v120, v120
	v_rcp_f32_e32 v121, v121
	v_mul_f32_e32 v28, v85, v28
	v_mul_f32_e32 v29, v85, v29
	v_mul_f32_e32 v30, v85, v30
	v_mul_f32_e32 v31, v85, v31
	v_mul_f32_e32 v118, v118, v190
	v_mul_f32_e32 v119, v119, v191
	v_mul_f32_e32 v120, v120, v192
	v_mul_f32_e32 v121, v121, v193
	v_exp_f32_e32 v28, v28
	v_exp_f32_e32 v29, v29
	v_exp_f32_e32 v30, v30
	v_exp_f32_e32 v31, v31
	s_nop 0
	v_fma_f32 v138, -v28, v28, 1.0
	v_fma_f32 v139, -v29, v29, 1.0
	v_fma_f32 v140, -v30, v30, 1.0
	v_fma_f32 v141, -v31, v31, 1.0
	v_max_f32_e32 v138, 0, v138
	v_max_f32_e32 v139, 0, v139
	v_max_f32_e32 v140, 0, v140
	v_max_f32_e32 v141, 0, v141
	v_sqrt_f32_e32 v138, v138
	v_sqrt_f32_e32 v139, v139
	v_sqrt_f32_e32 v140, v140
	v_sqrt_f32_e32 v141, v141
	s_nop 0
	v_mul_f32_e32 v118, v138, v118
	v_mul_f32_e32 v119, v139, v119
	v_mul_f32_e32 v120, v140, v120
	v_mul_f32_e32 v121, v141, v121
	v_mov_b32_e32 v253, v0
	v_mov_b32_e32 v254, v90
	v_fma_f32 v254, v1, v254, v91
	v_mul_f32_e32 v253, v253, v1
	v_fma_f32 v254, v2, v254, v92
	v_mul_f32_e32 v253, v253, v2
	v_fma_f32 v254, v3, v254, v93
	v_mul_f32_e32 v253, v253, v3
	v_fma_f32 v254, v4, v254, v94
	v_mul_f32_e32 v253, v253, v4
	v_fma_f32 v254, v5, v254, v95
	v_mul_f32_e32 v253, v253, v5
	v_fma_f32 v254, v6, v254, v96
	v_mul_f32_e32 v253, v253, v6
	v_fma_f32 v254, v7, v254, v97
	v_mul_f32_e32 v253, v253, v7
	v_fma_f32 v254, v8, v254, v98
	v_mul_f32_e32 v253, v253, v8
	v_fma_f32 v254, v9, v254, v99
	v_mul_f32_e32 v253, v253, v9
	v_fma_f32 v254, v10, v254, v100
	v_mul_f32_e32 v253, v253, v10
	v_fma_f32 v254, v11, v254, v101
	v_mul_f32_e32 v253, v253, v11
	v_fma_f32 v254, v12, v254, v102
	v_mul_f32_e32 v253, v253, v12
	v_fma_f32 v254, v13, v254, v103
	v_mul_f32_e32 v253, v253, v13
	v_fma_f32 v254, v14, v254, v104
	v_mul_f32_e32 v253, v253, v14
	v_fma_f32 v254, v15, v254, v105
	v_mul_f32_e32 v253, v253, v15
	v_fma_f32 v254, v16, v254, v106
	v_mul_f32_e32 v253, v253, v16
	v_fma_f32 v254, v17, v254, v107
	v_mul_f32_e32 v253, v253, v17
	v_fma_f32 v254, v18, v254, v108
	v_mul_f32_e32 v253, v253, v18
	v_fma_f32 v254, v19, v254, v109
	v_mul_f32_e32 v253, v253, v19
	v_fma_f32 v254, v20, v254, v110
	v_mul_f32_e32 v253, v253, v20
	v_fma_f32 v254, v21, v254, v111
	v_mul_f32_e32 v253, v253, v21
	v_fma_f32 v254, v22, v254, v112
	v_mul_f32_e32 v253, v253, v22
	v_fma_f32 v254, v23, v254, v113
	v_mul_f32_e32 v253, v253, v23
	v_fma_f32 v254, v24, v254, v114
	v_mul_f32_e32 v253, v253, v24
	v_fma_f32 v254, v25, v254, v115
	v_mul_f32_e32 v253, v253, v25
	v_fma_f32 v254, v26, v254, v116
	v_mul_f32_e32 v253, v253, v26
	v_fma_f32 v254, v27, v254, v117
	v_mul_f32_e32 v253, v253, v27
	v_fma_f32 v254, v28, v254, v118
	v_mul_f32_e32 v253, v253, v28
	v_fma_f32 v254, v29, v254, v119
	v_mul_f32_e32 v253, v253, v29
	v_fma_f32 v254, v30, v254, v120
	v_mul_f32_e32 v253, v253, v30
	v_fma_f32 v254, v31, v254, v121
	v_mul_f32_e32 v253, v253, v31
	v_mov_b32_e32 v138, v253
	v_mov_b32_e32 v139, v253
	s_nop 1
	v_permlane16_swap_b32_e32 v138, v139
	v_mov_b32_e32 v140, v138
	v_mov_b32_e32 v141, v139
	s_nop 1
	v_permlane32_swap_b32_e32 v138, v140
	v_permlane32_swap_b32_e32 v139, v141
	v_mov_b32_e32 v198, v254
	v_mov_b32_e32 v199, v254
	s_nop 1
	v_permlane16_swap_b32_e32 v198, v199
	v_mov_b32_e32 v200, v198
	v_mov_b32_e32 v201, v199
	s_nop 1
	v_permlane32_swap_b32_e32 v198, v200
	v_permlane32_swap_b32_e32 v199, v201
	v_mov_b32_e32 v136, 0
	v_fma_f32 v150, v138, v136, v198
	v_fma_f32 v151, v139, v150, v199
	v_fma_f32 v202, v140, v151, v200
	v_fma_f32 v254, v141, v202, v201
	v_mul_f32_e32 v253, v138, v139
	v_mul_f32_e32 v253, v253, v140
	v_mul_f32_e32 v200, v253, v141
	v_mov_b32_e32 v201, v254
	s_add_u32 s0, s71, 0
	s_lshl_b32 s0, s0, 12
	s_lshl_b32 s1, s56, 3
	s_add_u32 s0, s0, s1
	s_add_u32 s4, s18, s0
	s_addc_u32 s5, s19, 0
	global_store_dwordx2 v250, v[200:201], s[4:5]
	ds_read_b128 v[76:79], v131 offset:0
	ds_read_b128 v[80:83], v133 offset:0
	ds_read_b128 v[122:125], v131 offset:512
	ds_read_b128 v[126:129], v133 offset:512
	s_waitcnt vmcnt(1)
; __device__ __forceinline__ void lru_tile(const Params& P, int chunk, int head, int pass, char* smem_raw) {
;     ...
;     for (int i = 0; i < 4; ++i) {
;       const int idx = tid + 256 * i, rowi = idx >> 3, kg = idx & 7;
;       *reinterpret_cast<uint4*>(&sm_w[rowi * LDSS + kg * 8]) = ldg16(P.wg + ((long)(d * 8 + head) * 128 + rowi) * 64 + kg * 8);
;     }
;     float ba[4], bi[4], c8[4];
; #pragma unroll
;     for (int tc = 0; tc < 4; ++tc) {
;       const int cidx = d * 512 + head * 64 + 16 * tc + (lane & 15);
;       ba[tc] = P.b_a[cidx] * -1.4426950408889634f; bi[tc] = P.b_i[cidx] * -1.4426950408889634f;
;       const float nl = -P.lam[cidx];
;       const float e_ = __expf(nl);
;       const float sp = (nl > 20.f) ? nl
;                      : (e_ < 0.03f ? e_ * (1.f - e_ * (0.5f - e_ * (0.33333334f - 0.25f * e_))) : __logf(1.f + e_));
;       c8[tc] = 8.f * 1.4426950408889634f * sp;
;     }
;     __syncthreads();
;     float cA = 1.f, cB = (pass == 2) ? sm_init[d * 64 + ch] : 0.f;
;     for (int sbi = 0; sbi < 2; ++sbi) {
;       const int sb = (d == 0) ? sbi : 1 - sbi;
;       f32x4 acc[8];
; #pragma unroll
;       for (int t = 0; t < 8; ++t) acc[t] = f32x4{0.f, 0.f, 0.f, 0.f};
; #pragma unroll
;       for (int s = 0; s < 2; ++s) {
;         const bf16x8 af = *reinterpret_cast<const bf16x8*>(&sm_uc[(sb * 64 + wid * 16 + (lane & 15)) * LDSS + s * 32 + (lane >> 4) * 8]);
; #pragma unroll
;         for (int t = 0; t < 8; ++t) {
;           const bf16x8 bfr = *reinterpret_cast<const bf16x8*>(&sm_w[(t * 16 + (lane & 15)) * LDSS + s * 32 + (lane >> 4) * 8]);
;           acc[t] = __builtin_amdgcn_mfma_f32_16x16x32_bf16(af, bfr, acc[t], 0, 0, 0);
;         }
;       }
; #pragma unroll
;       for (int tc = 0; tc < 4; ++tc)
; #pragma unroll
;         for (int reg = 0; reg < 4; ++reg) {
;           const int tl = wid * 16 + (lane >> 4) * 4 + reg;
;           const int c = 16 * tc + (lane & 15);
;           const float r = __builtin_amdgcn_rcpf(1.f + __builtin_amdgcn_exp2f(acc[tc][reg] + ba[tc]));
;           const float ii = __builtin_amdgcn_rcpf(1.f + __builtin_amdgcn_exp2f(acc[tc + 4][reg] + bi[tc]));
;           const float la = -c8[tc] * r;
;           const float a = __builtin_amdgcn_exp2f(la);
;           const float ucv = bf2f(sm_uc[(sb * 64 + tl) * LDSS + c]);
;           const float bt = __builtin_amdgcn_sqrtf(fmaxf(1.f - a * a, 0.f)) * (ii * ucv);
	s_waitcnt lgkmcnt(3)
	v_mfma_f32_16x16x32_bf16 v[0:3], v[76:79], v[238:241], 0
	v_mfma_f32_16x16x32_bf16 v[90:93], v[76:79], v[246:249], 0
	ds_read_b128 v[76:79], v131 offset:1024
	s_waitcnt lgkmcnt(3)
	v_mfma_f32_16x16x32_bf16 v[0:3], v[80:83], v[242:245], v[0:3]
	v_mfma_f32_16x16x32_bf16 v[90:93], v[80:83], v[194:197], v[90:93]
	ds_read_b128 v[80:83], v133 offset:1024
	s_waitcnt lgkmcnt(3)
	v_mfma_f32_16x16x32_bf16 v[4:7], v[122:125], v[238:241], 0
	v_mfma_f32_16x16x32_bf16 v[94:97], v[122:125], v[246:249], 0
	ds_read_b128 v[122:125], v131 offset:1536
	s_waitcnt lgkmcnt(3)
	v_mfma_f32_16x16x32_bf16 v[4:7], v[126:129], v[242:245], v[4:7]
	v_mfma_f32_16x16x32_bf16 v[94:97], v[126:129], v[194:197], v[94:97]
	ds_read_b128 v[126:129], v133 offset:1536
	s_waitcnt lgkmcnt(3)
	v_mfma_f32_16x16x32_bf16 v[8:11], v[76:79], v[238:241], 0
	v_mfma_f32_16x16x32_bf16 v[98:101], v[76:79], v[246:249], 0
	ds_read_b128 v[76:79], v131 offset:2048
	s_waitcnt lgkmcnt(3)
	v_mfma_f32_16x16x32_bf16 v[8:11], v[80:83], v[242:245], v[8:11]
	v_mfma_f32_16x16x32_bf16 v[98:101], v[80:83], v[194:197], v[98:101]
	ds_read_b128 v[80:83], v133 offset:2048
	s_waitcnt lgkmcnt(3)
	v_mfma_f32_16x16x32_bf16 v[12:15], v[122:125], v[238:241], 0
	v_mfma_f32_16x16x32_bf16 v[102:105], v[122:125], v[246:249], 0
	ds_read_b128 v[122:125], v131 offset:2560
	s_waitcnt lgkmcnt(3)
	v_mfma_f32_16x16x32_bf16 v[12:15], v[126:129], v[242:245], v[12:15]
	v_mfma_f32_16x16x32_bf16 v[102:105], v[126:129], v[194:197], v[102:105]
	ds_read_b128 v[126:129], v133 offset:2560
	s_waitcnt lgkmcnt(3)
	v_mfma_f32_16x16x32_bf16 v[16:19], v[76:79], v[238:241], 0
	v_mfma_f32_16x16x32_bf16 v[106:109], v[76:79], v[246:249], 0
	ds_read_b128 v[76:79], v131 offset:3072
	s_waitcnt lgkmcnt(3)
	v_mfma_f32_16x16x32_bf16 v[16:19], v[80:83], v[242:245], v[16:19]
	v_mfma_f32_16x16x32_bf16 v[106:109], v[80:83], v[194:197], v[106:109]
	ds_read_b128 v[80:83], v133 offset:3072
	s_waitcnt lgkmcnt(3)
	v_mfma_f32_16x16x32_bf16 v[20:23], v[122:125], v[238:241], 0
	v_mfma_f32_16x16x32_bf16 v[110:113], v[122:125], v[246:249], 0
	ds_read_b128 v[122:125], v131 offset:3584
	s_waitcnt lgkmcnt(3)
	v_mfma_f32_16x16x32_bf16 v[20:23], v[126:129], v[242:245], v[20:23]
	v_mfma_f32_16x16x32_bf16 v[110:113], v[126:129], v[194:197], v[110:113]
	ds_read_b128 v[126:129], v133 offset:3584
	s_waitcnt lgkmcnt(3)
	v_mfma_f32_16x16x32_bf16 v[24:27], v[76:79], v[238:241], 0
	v_mfma_f32_16x16x32_bf16 v[114:117], v[76:79], v[246:249], 0
	s_waitcnt lgkmcnt(2)
	v_mfma_f32_16x16x32_bf16 v[24:27], v[80:83], v[242:245], v[24:27]
	v_mfma_f32_16x16x32_bf16 v[114:117], v[80:83], v[194:197], v[114:117]
	s_waitcnt lgkmcnt(1)
	v_mfma_f32_16x16x32_bf16 v[28:31], v[122:125], v[238:241], 0
	v_mfma_f32_16x16x32_bf16 v[118:121], v[122:125], v[246:249], 0
	s_waitcnt lgkmcnt(0)
	v_mfma_f32_16x16x32_bf16 v[28:31], v[126:129], v[242:245], v[28:31]
	v_mfma_f32_16x16x32_bf16 v[118:121], v[126:129], v[194:197], v[118:121]
	s_lshl_b32 s0, s56, 8
	s_add_u32 s0, s0, 0x0
	s_add_u32 s4, s20, s0
	s_addc_u32 s5, s21, 0
	global_load_dwordx4 v[238:241], v251, s[4:5]
	global_load_dwordx4 v[242:245], v251, s[4:5] offset:64
	s_add_u32 s4, s4, 0x2000
	s_addc_u32 s5, s5, 0
	global_load_dwordx4 v[246:249], v251, s[4:5]
	global_load_dwordx4 v[194:197], v251, s[4:5] offset:64
	s_nop 7
	s_nop 7
	v_add_f32_e32 v0, v0, v145
	v_add_f32_e32 v1, v1, v145
	v_add_f32_e32 v2, v2, v145
	v_add_f32_e32 v3, v3, v145
	v_add_f32_e32 v90, v90, v146
	v_add_f32_e32 v91, v91, v146
	v_add_f32_e32 v92, v92, v146
	v_add_f32_e32 v93, v93, v146
	v_exp_f32_e32 v0, v0
	v_exp_f32_e32 v1, v1
	v_exp_f32_e32 v2, v2
	v_exp_f32_e32 v3, v3
	v_exp_f32_e32 v90, v90
	v_exp_f32_e32 v91, v91
	v_exp_f32_e32 v92, v92
	v_exp_f32_e32 v93, v93
	v_add_f32_e32 v0, 1.0, v0
	v_add_f32_e32 v1, 1.0, v1
	v_add_f32_e32 v2, 1.0, v2
	v_add_f32_e32 v3, 1.0, v3
	v_add_f32_e32 v90, 1.0, v90
	v_add_f32_e32 v91, 1.0, v91
	v_add_f32_e32 v92, 1.0, v92
	v_add_f32_e32 v93, 1.0, v93
	v_rcp_f32_e32 v0, v0
	v_rcp_f32_e32 v1, v1
	v_rcp_f32_e32 v2, v2
	v_rcp_f32_e32 v3, v3
	v_rcp_f32_e32 v90, v90
	v_rcp_f32_e32 v91, v91
	v_rcp_f32_e32 v92, v92
	v_rcp_f32_e32 v93, v93
	v_mul_f32_e32 v0, v147, v0
	v_mul_f32_e32 v1, v147, v1
	v_mul_f32_e32 v2, v147, v2
	v_mul_f32_e32 v3, v147, v3
	v_mul_f32_e32 v90, v90, v162
	v_mul_f32_e32 v91, v91, v163
	v_mul_f32_e32 v92, v92, v164
	v_mul_f32_e32 v93, v93, v165
	v_exp_f32_e32 v0, v0
	v_exp_f32_e32 v1, v1
	v_exp_f32_e32 v2, v2
	v_exp_f32_e32 v3, v3
	s_nop 0
	v_fma_f32 v138, -v0, v0, 1.0
	v_fma_f32 v139, -v1, v1, 1.0
	v_fma_f32 v140, -v2, v2, 1.0
	v_fma_f32 v141, -v3, v3, 1.0
	v_max_f32_e32 v138, 0, v138
	v_max_f32_e32 v139, 0, v139
	v_max_f32_e32 v140, 0, v140
	v_max_f32_e32 v141, 0, v141
	v_sqrt_f32_e32 v138, v138
	v_sqrt_f32_e32 v139, v139
	v_sqrt_f32_e32 v140, v140
	v_sqrt_f32_e32 v141, v141
	s_nop 0
	v_mul_f32_e32 v90, v138, v90
	v_mul_f32_e32 v91, v139, v91
	v_mul_f32_e32 v92, v140, v92
	v_mul_f32_e32 v93, v141, v93
	v_add_f32_e32 v4, v4, v145
	v_add_f32_e32 v5, v5, v145
	v_add_f32_e32 v6, v6, v145
	v_add_f32_e32 v7, v7, v145
	v_add_f32_e32 v94, v94, v146
	v_add_f32_e32 v95, v95, v146
	v_add_f32_e32 v96, v96, v146
	v_add_f32_e32 v97, v97, v146
	v_exp_f32_e32 v4, v4
	v_exp_f32_e32 v5, v5
	v_exp_f32_e32 v6, v6
	v_exp_f32_e32 v7, v7
	v_exp_f32_e32 v94, v94
	v_exp_f32_e32 v95, v95
	v_exp_f32_e32 v96, v96
	v_exp_f32_e32 v97, v97
	v_add_f32_e32 v4, 1.0, v4
	v_add_f32_e32 v5, 1.0, v5
	v_add_f32_e32 v6, 1.0, v6
	v_add_f32_e32 v7, 1.0, v7
	v_add_f32_e32 v94, 1.0, v94
	v_add_f32_e32 v95, 1.0, v95
	v_add_f32_e32 v96, 1.0, v96
	v_add_f32_e32 v97, 1.0, v97
	v_rcp_f32_e32 v4, v4
	v_rcp_f32_e32 v5, v5
	v_rcp_f32_e32 v6, v6
; __device__ __forceinline__ float bf2f(u16 h) { return __uint_as_float(((unsigned)h) << 16); }
; __device__ __forceinline__ void lru_tile(const Params& P, int chunk, int head, int pass, char* smem_raw) {
;     ...
;           const float r = __builtin_amdgcn_rcpf(1.f + __builtin_amdgcn_exp2f(acc[tc][reg] + ba[tc]));
;           const float ii = __builtin_amdgcn_rcpf(1.f + __builtin_amdgcn_exp2f(acc[tc + 4][reg] + bi[tc]));
;           const float la = -c8[tc] * r;
;           const float a = __builtin_amdgcn_exp2f(la);
;           const float ucv = bf2f(sm_uc[(sb * 64 + tl) * LDSS + c]);
;           const float bt = __builtin_amdgcn_sqrtf(fmaxf(1.f - a * a, 0.f)) * (ii * ucv);
	v_rcp_f32_e32 v7, v7
	v_rcp_f32_e32 v94, v94
	v_rcp_f32_e32 v95, v95
	v_rcp_f32_e32 v96, v96
	v_rcp_f32_e32 v97, v97
	v_mul_f32_e32 v4, v147, v4
	v_mul_f32_e32 v5, v147, v5
	v_mul_f32_e32 v6, v147, v6
	v_mul_f32_e32 v7, v147, v7
	v_mul_f32_e32 v94, v94, v166
	v_mul_f32_e32 v95, v95, v167
	v_mul_f32_e32 v96, v96, v168
	v_mul_f32_e32 v97, v97, v169
	v_exp_f32_e32 v4, v4
	v_exp_f32_e32 v5, v5
	v_exp_f32_e32 v6, v6
	v_exp_f32_e32 v7, v7
	s_nop 0
	v_fma_f32 v138, -v4, v4, 1.0
	v_fma_f32 v139, -v5, v5, 1.0
	v_fma_f32 v140, -v6, v6, 1.0
	v_fma_f32 v141, -v7, v7, 1.0
	v_max_f32_e32 v138, 0, v138
	v_max_f32_e32 v139, 0, v139
	v_max_f32_e32 v140, 0, v140
	v_max_f32_e32 v141, 0, v141
	v_sqrt_f32_e32 v138, v138
	v_sqrt_f32_e32 v139, v139
	v_sqrt_f32_e32 v140, v140
	v_sqrt_f32_e32 v141, v141
	s_nop 0
	v_mul_f32_e32 v94, v138, v94
	v_mul_f32_e32 v95, v139, v95
	v_mul_f32_e32 v96, v140, v96
	v_mul_f32_e32 v97, v141, v97
	v_add_f32_e32 v8, v8, v145
	v_add_f32_e32 v9, v9, v145
	v_add_f32_e32 v10, v10, v145
	v_add_f32_e32 v11, v11, v145
	v_add_f32_e32 v98, v98, v146
	v_add_f32_e32 v99, v99, v146
	v_add_f32_e32 v100, v100, v146
	v_add_f32_e32 v101, v101, v146
	v_exp_f32_e32 v8, v8
	v_exp_f32_e32 v9, v9
	v_exp_f32_e32 v10, v10
	v_exp_f32_e32 v11, v11
	v_exp_f32_e32 v98, v98
	v_exp_f32_e32 v99, v99
	v_exp_f32_e32 v100, v100
	v_exp_f32_e32 v101, v101
	v_add_f32_e32 v8, 1.0, v8
	v_add_f32_e32 v9, 1.0, v9
	v_add_f32_e32 v10, 1.0, v10
	v_add_f32_e32 v11, 1.0, v11
	v_add_f32_e32 v98, 1.0, v98
	v_add_f32_e32 v99, 1.0, v99
	v_add_f32_e32 v100, 1.0, v100
	v_add_f32_e32 v101, 1.0, v101
	v_rcp_f32_e32 v8, v8
	v_rcp_f32_e32 v9, v9
	v_rcp_f32_e32 v10, v10
	v_rcp_f32_e32 v11, v11
	v_rcp_f32_e32 v98, v98
	v_rcp_f32_e32 v99, v99
	v_rcp_f32_e32 v100, v100
	v_rcp_f32_e32 v101, v101
	v_mul_f32_e32 v8, v147, v8
	v_mul_f32_e32 v9, v147, v9
	v_mul_f32_e32 v10, v147, v10
	v_mul_f32_e32 v11, v147, v11
	v_mul_f32_e32 v98, v98, v170
	v_mul_f32_e32 v99, v99, v171
	v_mul_f32_e32 v100, v100, v172
	v_mul_f32_e32 v101, v101, v173
	v_exp_f32_e32 v8, v8
	v_exp_f32_e32 v9, v9
	v_exp_f32_e32 v10, v10
	v_exp_f32_e32 v11, v11
	s_nop 0
	v_fma_f32 v138, -v8, v8, 1.0
	v_fma_f32 v139, -v9, v9, 1.0
	v_fma_f32 v140, -v10, v10, 1.0
	v_fma_f32 v141, -v11, v11, 1.0
	v_max_f32_e32 v138, 0, v138
	v_max_f32_e32 v139, 0, v139
	v_max_f32_e32 v140, 0, v140
	v_max_f32_e32 v141, 0, v141
	v_sqrt_f32_e32 v138, v138
	v_sqrt_f32_e32 v139, v139
	v_sqrt_f32_e32 v140, v140
	v_sqrt_f32_e32 v141, v141
	s_nop 0
	v_mul_f32_e32 v98, v138, v98
	v_mul_f32_e32 v99, v139, v99
	v_mul_f32_e32 v100, v140, v100
	v_mul_f32_e32 v101, v141, v101
	v_add_f32_e32 v12, v12, v145
	v_add_f32_e32 v13, v13, v145
	v_add_f32_e32 v14, v14, v145
	v_add_f32_e32 v15, v15, v145
	v_add_f32_e32 v102, v102, v146
	v_add_f32_e32 v103, v103, v146
	v_add_f32_e32 v104, v104, v146
	v_add_f32_e32 v105, v105, v146
	v_exp_f32_e32 v12, v12
	v_exp_f32_e32 v13, v13
	v_exp_f32_e32 v14, v14
	v_exp_f32_e32 v15, v15
	v_exp_f32_e32 v102, v102
	v_exp_f32_e32 v103, v103
	v_exp_f32_e32 v104, v104
	v_exp_f32_e32 v105, v105
	v_add_f32_e32 v12, 1.0, v12
	v_add_f32_e32 v13, 1.0, v13
	v_add_f32_e32 v14, 1.0, v14
	v_add_f32_e32 v15, 1.0, v15
	v_add_f32_e32 v102, 1.0, v102
	v_add_f32_e32 v103, 1.0, v103
	v_add_f32_e32 v104, 1.0, v104
	v_add_f32_e32 v105, 1.0, v105
	v_rcp_f32_e32 v12, v12
	v_rcp_f32_e32 v13, v13
	v_rcp_f32_e32 v14, v14
	v_rcp_f32_e32 v15, v15
	v_rcp_f32_e32 v102, v102
	v_rcp_f32_e32 v103, v103
	v_rcp_f32_e32 v104, v104
	v_rcp_f32_e32 v105, v105
	v_mul_f32_e32 v12, v147, v12
	v_mul_f32_e32 v13, v147, v13
	v_mul_f32_e32 v14, v147, v14
	v_mul_f32_e32 v15, v147, v15
	v_mul_f32_e32 v102, v102, v174
	v_mul_f32_e32 v103, v103, v175
	v_mul_f32_e32 v104, v104, v176
	v_mul_f32_e32 v105, v105, v177
	v_exp_f32_e32 v12, v12
	v_exp_f32_e32 v13, v13
	v_exp_f32_e32 v14, v14
	v_exp_f32_e32 v15, v15
	s_nop 0
	v_fma_f32 v138, -v12, v12, 1.0
	v_fma_f32 v139, -v13, v13, 1.0
	v_fma_f32 v140, -v14, v14, 1.0
	v_fma_f32 v141, -v15, v15, 1.0
	v_max_f32_e32 v138, 0, v138
	v_max_f32_e32 v139, 0, v139
	v_max_f32_e32 v140, 0, v140
	v_max_f32_e32 v141, 0, v141
	v_sqrt_f32_e32 v138, v138
	v_sqrt_f32_e32 v139, v139
	v_sqrt_f32_e32 v140, v140
	v_sqrt_f32_e32 v141, v141
	s_nop 0
	v_mul_f32_e32 v102, v138, v102
	v_mul_f32_e32 v103, v139, v103
	v_mul_f32_e32 v104, v140, v104
	v_mul_f32_e32 v105, v141, v105
	v_add_f32_e32 v16, v16, v145
	v_add_f32_e32 v17, v17, v145
	v_add_f32_e32 v18, v18, v145
	v_add_f32_e32 v19, v19, v145
	v_add_f32_e32 v106, v106, v146
	v_add_f32_e32 v107, v107, v146
	v_add_f32_e32 v108, v108, v146
	v_add_f32_e32 v109, v109, v146
	v_exp_f32_e32 v16, v16
	v_exp_f32_e32 v17, v17
	v_exp_f32_e32 v18, v18
	v_exp_f32_e32 v19, v19
	v_exp_f32_e32 v106, v106
	v_exp_f32_e32 v107, v107
	v_exp_f32_e32 v108, v108
	v_exp_f32_e32 v109, v109
	v_add_f32_e32 v16, 1.0, v16
	v_add_f32_e32 v17, 1.0, v17
	v_add_f32_e32 v18, 1.0, v18
	v_add_f32_e32 v19, 1.0, v19
	v_add_f32_e32 v106, 1.0, v106
	v_add_f32_e32 v107, 1.0, v107
	v_add_f32_e32 v108, 1.0, v108
	v_add_f32_e32 v109, 1.0, v109
	v_rcp_f32_e32 v16, v16
	v_rcp_f32_e32 v17, v17
	v_rcp_f32_e32 v18, v18
	v_rcp_f32_e32 v19, v19
	v_rcp_f32_e32 v106, v106
	v_rcp_f32_e32 v107, v107
	v_rcp_f32_e32 v108, v108
	v_rcp_f32_e32 v109, v109
	v_mul_f32_e32 v16, v147, v16
	v_mul_f32_e32 v17, v147, v17
	v_mul_f32_e32 v18, v147, v18
	v_mul_f32_e32 v19, v147, v19
	v_mul_f32_e32 v106, v106, v178
	v_mul_f32_e32 v107, v107, v179
	v_mul_f32_e32 v108, v108, v180
	v_mul_f32_e32 v109, v109, v181
	v_exp_f32_e32 v16, v16
	v_exp_f32_e32 v17, v17
	v_exp_f32_e32 v18, v18
	v_exp_f32_e32 v19, v19
	s_nop 0
	v_fma_f32 v138, -v16, v16, 1.0
	v_fma_f32 v139, -v17, v17, 1.0
; __device__ __forceinline__ float bf2f(u16 h) { return __uint_as_float(((unsigned)h) << 16); }
; __device__ __forceinline__ void lru_tile(const Params& P, int chunk, int head, int pass, char* smem_raw) {
;     ...
;           const float r = __builtin_amdgcn_rcpf(1.f + __builtin_amdgcn_exp2f(acc[tc][reg] + ba[tc]));
;           const float ii = __builtin_amdgcn_rcpf(1.f + __builtin_amdgcn_exp2f(acc[tc + 4][reg] + bi[tc]));
;           const float la = -c8[tc] * r;
;           const float a = __builtin_amdgcn_exp2f(la);
;           const float ucv = bf2f(sm_uc[(sb * 64 + tl) * LDSS + c]);
;           const float bt = __builtin_amdgcn_sqrtf(fmaxf(1.f - a * a, 0.f)) * (ii * ucv);
	v_fma_f32 v140, -v18, v18, 1.0
	v_fma_f32 v141, -v19, v19, 1.0
	v_max_f32_e32 v138, 0, v138
	v_max_f32_e32 v139, 0, v139
	v_max_f32_e32 v140, 0, v140
	v_max_f32_e32 v141, 0, v141
	v_sqrt_f32_e32 v138, v138
	v_sqrt_f32_e32 v139, v139
	v_sqrt_f32_e32 v140, v140
	v_sqrt_f32_e32 v141, v141
	s_nop 0
	v_mul_f32_e32 v106, v138, v106
	v_mul_f32_e32 v107, v139, v107
	v_mul_f32_e32 v108, v140, v108
	v_mul_f32_e32 v109, v141, v109
	v_add_f32_e32 v20, v20, v145
	v_add_f32_e32 v21, v21, v145
	v_add_f32_e32 v22, v22, v145
	v_add_f32_e32 v23, v23, v145
	v_add_f32_e32 v110, v110, v146
	v_add_f32_e32 v111, v111, v146
	v_add_f32_e32 v112, v112, v146
	v_add_f32_e32 v113, v113, v146
	v_exp_f32_e32 v20, v20
	v_exp_f32_e32 v21, v21
	v_exp_f32_e32 v22, v22
	v_exp_f32_e32 v23, v23
	v_exp_f32_e32 v110, v110
	v_exp_f32_e32 v111, v111
	v_exp_f32_e32 v112, v112
	v_exp_f32_e32 v113, v113
	v_add_f32_e32 v20, 1.0, v20
	v_add_f32_e32 v21, 1.0, v21
	v_add_f32_e32 v22, 1.0, v22
	v_add_f32_e32 v23, 1.0, v23
	v_add_f32_e32 v110, 1.0, v110
	v_add_f32_e32 v111, 1.0, v111
	v_add_f32_e32 v112, 1.0, v112
	v_add_f32_e32 v113, 1.0, v113
	v_rcp_f32_e32 v20, v20
	v_rcp_f32_e32 v21, v21
	v_rcp_f32_e32 v22, v22
	v_rcp_f32_e32 v23, v23
	v_rcp_f32_e32 v110, v110
	v_rcp_f32_e32 v111, v111
	v_rcp_f32_e32 v112, v112
	v_rcp_f32_e32 v113, v113
	v_mul_f32_e32 v20, v147, v20
	v_mul_f32_e32 v21, v147, v21
	v_mul_f32_e32 v22, v147, v22
	v_mul_f32_e32 v23, v147, v23
	v_mul_f32_e32 v110, v110, v182
	v_mul_f32_e32 v111, v111, v183
	v_mul_f32_e32 v112, v112, v184
	v_mul_f32_e32 v113, v113, v185
	v_exp_f32_e32 v20, v20
	v_exp_f32_e32 v21, v21
	v_exp_f32_e32 v22, v22
	v_exp_f32_e32 v23, v23
	s_nop 0
	v_fma_f32 v138, -v20, v20, 1.0
	v_fma_f32 v139, -v21, v21, 1.0
	v_fma_f32 v140, -v22, v22, 1.0
	v_fma_f32 v141, -v23, v23, 1.0
	v_max_f32_e32 v138, 0, v138
	v_max_f32_e32 v139, 0, v139
	v_max_f32_e32 v140, 0, v140
	v_max_f32_e32 v141, 0, v141
	v_sqrt_f32_e32 v138, v138
	v_sqrt_f32_e32 v139, v139
	v_sqrt_f32_e32 v140, v140
	v_sqrt_f32_e32 v141, v141
	s_nop 0
	v_mul_f32_e32 v110, v138, v110
	v_mul_f32_e32 v111, v139, v111
	v_mul_f32_e32 v112, v140, v112
	v_mul_f32_e32 v113, v141, v113
	v_add_f32_e32 v24, v24, v145
	v_add_f32_e32 v25, v25, v145
	v_add_f32_e32 v26, v26, v145
	v_add_f32_e32 v27, v27, v145
	v_add_f32_e32 v114, v114, v146
	v_add_f32_e32 v115, v115, v146
	v_add_f32_e32 v116, v116, v146
	v_add_f32_e32 v117, v117, v146
	v_exp_f32_e32 v24, v24
	v_exp_f32_e32 v25, v25
	v_exp_f32_e32 v26, v26
	v_exp_f32_e32 v27, v27
	v_exp_f32_e32 v114, v114
	v_exp_f32_e32 v115, v115
	v_exp_f32_e32 v116, v116
	v_exp_f32_e32 v117, v117
	v_add_f32_e32 v24, 1.0, v24
	v_add_f32_e32 v25, 1.0, v25
	v_add_f32_e32 v26, 1.0, v26
	v_add_f32_e32 v27, 1.0, v27
	v_add_f32_e32 v114, 1.0, v114
	v_add_f32_e32 v115, 1.0, v115
	v_add_f32_e32 v116, 1.0, v116
	v_add_f32_e32 v117, 1.0, v117
	v_rcp_f32_e32 v24, v24
	v_rcp_f32_e32 v25, v25
	v_rcp_f32_e32 v26, v26
	v_rcp_f32_e32 v27, v27
	v_rcp_f32_e32 v114, v114
	v_rcp_f32_e32 v115, v115
	v_rcp_f32_e32 v116, v116
	v_rcp_f32_e32 v117, v117
	v_mul_f32_e32 v24, v147, v24
	v_mul_f32_e32 v25, v147, v25
	v_mul_f32_e32 v26, v147, v26
	v_mul_f32_e32 v27, v147, v27
	v_mul_f32_e32 v114, v114, v186
	v_mul_f32_e32 v115, v115, v187
	v_mul_f32_e32 v116, v116, v188
	v_mul_f32_e32 v117, v117, v189
	v_exp_f32_e32 v24, v24
	v_exp_f32_e32 v25, v25
	v_exp_f32_e32 v26, v26
	v_exp_f32_e32 v27, v27
	s_nop 0
	v_fma_f32 v138, -v24, v24, 1.0
	v_fma_f32 v139, -v25, v25, 1.0
	v_fma_f32 v140, -v26, v26, 1.0
	v_fma_f32 v141, -v27, v27, 1.0
	v_max_f32_e32 v138, 0, v138
	v_max_f32_e32 v139, 0, v139
	v_max_f32_e32 v140, 0, v140
	v_max_f32_e32 v141, 0, v141
	v_sqrt_f32_e32 v138, v138
	v_sqrt_f32_e32 v139, v139
	v_sqrt_f32_e32 v140, v140
	v_sqrt_f32_e32 v141, v141
	s_nop 0
	v_mul_f32_e32 v114, v138, v114
	v_mul_f32_e32 v115, v139, v115
	v_mul_f32_e32 v116, v140, v116
	v_mul_f32_e32 v117, v141, v117
	v_add_f32_e32 v28, v28, v145
	v_add_f32_e32 v29, v29, v145
	v_add_f32_e32 v30, v30, v145
	v_add_f32_e32 v31, v31, v145
	v_add_f32_e32 v118, v118, v146
	v_add_f32_e32 v119, v119, v146
	v_add_f32_e32 v120, v120, v146
	v_add_f32_e32 v121, v121, v146
	v_exp_f32_e32 v28, v28
	v_exp_f32_e32 v29, v29
	v_exp_f32_e32 v30, v30
	v_exp_f32_e32 v31, v31
	v_exp_f32_e32 v118, v118
	v_exp_f32_e32 v119, v119
	v_exp_f32_e32 v120, v120
	v_exp_f32_e32 v121, v121
; __device__ __forceinline__ float bf2f(u16 h) { return __uint_as_float(((unsigned)h) << 16); }
; __device__ __forceinline__ void lru_tile(const Params& P, int chunk, int head, int pass, char* smem_raw) {
;     ...
;           const float r = __builtin_amdgcn_rcpf(1.f + __builtin_amdgcn_exp2f(acc[tc][reg] + ba[tc]));
;           const float ii = __builtin_amdgcn_rcpf(1.f + __builtin_amdgcn_exp2f(acc[tc + 4][reg] + bi[tc]));
;           const float la = -c8[tc] * r;
;           const float a = __builtin_amdgcn_exp2f(la);
;           const float ucv = bf2f(sm_uc[(sb * 64 + tl) * LDSS + c]);
;           const float bt = __builtin_amdgcn_sqrtf(fmaxf(1.f - a * a, 0.f)) * (ii * ucv);
;           sm_a[tl * 64 + c] = a;
;           sm_b[tl * 64 + c] = bt;
;         }
;       __syncthreads();
;       const int pos = (d == 0) ? q : 3 - q;
;       {
;         float Pp = 1.f, H = 0.f;
; #pragma unroll 4
;         for (int i = 0; i < 16; ++i) {
;           const int tl = (d == 0) ? (q * 16 + i) : (q * 16 + 15 - i);
;           const float a = sm_a[tl * 64 + ch], b = sm_b[tl * 64 + ch];
;           H = a * H + b; Pp *= a;
;         }
;         sm_ph[pos * 64 + ch] = make_float2(Pp, H);
;     ...
;       cB = p0.x * cB + p0.y; cA *= p0.x;
;       cB = p1.x * cB + p1.y; cA *= p1.x;
;       cB = p2.x * cB + p2.y; cA *= p2.x;
;       cB = p3.x * cB + p3.y; cA *= p3.x;
;       __syncthreads();
;     }
;     if (pass == 1 && q == 0) P.summ[((long)d * 264 + chunk) * 512 + gch] = make_float2(cA, cB);
	v_add_f32_e32 v28, 1.0, v28
	v_add_f32_e32 v29, 1.0, v29
	v_add_f32_e32 v30, 1.0, v30
	v_add_f32_e32 v31, 1.0, v31
	v_add_f32_e32 v118, 1.0, v118
	v_add_f32_e32 v119, 1.0, v119
	v_add_f32_e32 v120, 1.0, v120
	v_add_f32_e32 v121, 1.0, v121
	v_rcp_f32_e32 v28, v28
	v_rcp_f32_e32 v29, v29
	v_rcp_f32_e32 v30, v30
	v_rcp_f32_e32 v31, v31
	v_rcp_f32_e32 v118, v118
	v_rcp_f32_e32 v119, v119
	v_rcp_f32_e32 v120, v120
	v_rcp_f32_e32 v121, v121
	v_mul_f32_e32 v28, v147, v28
	v_mul_f32_e32 v29, v147, v29
	v_mul_f32_e32 v30, v147, v30
	v_mul_f32_e32 v31, v147, v31
	v_mul_f32_e32 v118, v118, v190
	v_mul_f32_e32 v119, v119, v191
	v_mul_f32_e32 v120, v120, v192
	v_mul_f32_e32 v121, v121, v193
	v_exp_f32_e32 v28, v28
	v_exp_f32_e32 v29, v29
	v_exp_f32_e32 v30, v30
	v_exp_f32_e32 v31, v31
	s_nop 0
	v_fma_f32 v138, -v28, v28, 1.0
	v_fma_f32 v139, -v29, v29, 1.0
	v_fma_f32 v140, -v30, v30, 1.0
	v_fma_f32 v141, -v31, v31, 1.0
	v_max_f32_e32 v138, 0, v138
	v_max_f32_e32 v139, 0, v139
	v_max_f32_e32 v140, 0, v140
	v_max_f32_e32 v141, 0, v141
	v_sqrt_f32_e32 v138, v138
	v_sqrt_f32_e32 v139, v139
	v_sqrt_f32_e32 v140, v140
	v_sqrt_f32_e32 v141, v141
	s_nop 0
	v_mul_f32_e32 v118, v138, v118
	v_mul_f32_e32 v119, v139, v119
	v_mul_f32_e32 v120, v140, v120
	v_mul_f32_e32 v121, v141, v121
	v_mov_b32_e32 v253, v31
	v_mov_b32_e32 v254, v121
	v_fma_f32 v254, v30, v254, v120
	v_mul_f32_e32 v253, v253, v30
	v_fma_f32 v254, v29, v254, v119
	v_mul_f32_e32 v253, v253, v29
	v_fma_f32 v254, v28, v254, v118
	v_mul_f32_e32 v253, v253, v28
	v_fma_f32 v254, v27, v254, v117
	v_mul_f32_e32 v253, v253, v27
	v_fma_f32 v254, v26, v254, v116
	v_mul_f32_e32 v253, v253, v26
	v_fma_f32 v254, v25, v254, v115
	v_mul_f32_e32 v253, v253, v25
	v_fma_f32 v254, v24, v254, v114
	v_mul_f32_e32 v253, v253, v24
	v_fma_f32 v254, v23, v254, v113
	v_mul_f32_e32 v253, v253, v23
	v_fma_f32 v254, v22, v254, v112
	v_mul_f32_e32 v253, v253, v22
	v_fma_f32 v254, v21, v254, v111
	v_mul_f32_e32 v253, v253, v21
	v_fma_f32 v254, v20, v254, v110
	v_mul_f32_e32 v253, v253, v20
	v_fma_f32 v254, v19, v254, v109
	v_mul_f32_e32 v253, v253, v19
	v_fma_f32 v254, v18, v254, v108
	v_mul_f32_e32 v253, v253, v18
	v_fma_f32 v254, v17, v254, v107
	v_mul_f32_e32 v253, v253, v17
	v_fma_f32 v254, v16, v254, v106
	v_mul_f32_e32 v253, v253, v16
	v_fma_f32 v254, v15, v254, v105
	v_mul_f32_e32 v253, v253, v15
	v_fma_f32 v254, v14, v254, v104
	v_mul_f32_e32 v253, v253, v14
	v_fma_f32 v254, v13, v254, v103
	v_mul_f32_e32 v253, v253, v13
	v_fma_f32 v254, v12, v254, v102
	v_mul_f32_e32 v253, v253, v12
	v_fma_f32 v254, v11, v254, v101
	v_mul_f32_e32 v253, v253, v11
	v_fma_f32 v254, v10, v254, v100
	v_mul_f32_e32 v253, v253, v10
	v_fma_f32 v254, v9, v254, v99
	v_mul_f32_e32 v253, v253, v9
	v_fma_f32 v254, v8, v254, v98
	v_mul_f32_e32 v253, v253, v8
	v_fma_f32 v254, v7, v254, v97
	v_mul_f32_e32 v253, v253, v7
	v_fma_f32 v254, v6, v254, v96
	v_mul_f32_e32 v253, v253, v6
	v_fma_f32 v254, v5, v254, v95
	v_mul_f32_e32 v253, v253, v5
	v_fma_f32 v254, v4, v254, v94
	v_mul_f32_e32 v253, v253, v4
	v_fma_f32 v254, v3, v254, v93
	v_mul_f32_e32 v253, v253, v3
	v_fma_f32 v254, v2, v254, v92
	v_mul_f32_e32 v253, v253, v2
	v_fma_f32 v254, v1, v254, v91
	v_mul_f32_e32 v253, v253, v1
	v_fma_f32 v254, v0, v254, v90
	v_mul_f32_e32 v253, v253, v0
	v_mov_b32_e32 v138, v253
	v_mov_b32_e32 v139, v253
	s_nop 1
	v_permlane16_swap_b32_e32 v138, v139
	v_mov_b32_e32 v140, v138
	v_mov_b32_e32 v141, v139
	s_nop 1
	v_permlane32_swap_b32_e32 v138, v140
	v_permlane32_swap_b32_e32 v139, v141
	v_mov_b32_e32 v198, v254
	v_mov_b32_e32 v199, v254
	s_nop 1
	v_permlane16_swap_b32_e32 v198, v199
	v_mov_b32_e32 v200, v198
	v_mov_b32_e32 v201, v199
	s_nop 1
	v_permlane32_swap_b32_e32 v198, v200
	v_permlane32_swap_b32_e32 v199, v201
	v_mov_b32_e32 v202, 0
	v_fma_f32 v151, v141, v202, v201
	v_fma_f32 v150, v140, v151, v200
	v_fma_f32 v136, v139, v150, v199
	v_fma_f32 v254, v138, v136, v198
	v_mul_f32_e32 v253, v138, v139
	v_mul_f32_e32 v253, v253, v140
	v_mul_f32_e32 v200, v253, v141
	v_mov_b32_e32 v201, v254
	s_add_u32 s0, s71, 264
	s_lshl_b32 s0, s0, 12
	s_lshl_b32 s1, s56, 3
	s_add_u32 s0, s0, s1
	s_add_u32 s4, s18, s0
	s_addc_u32 s5, s19, 0
	global_store_dwordx2 v250, v[200:201], s[4:5]
	s_add_u32 s69, s69, 1
	s_cmp_lt_u32 s69, s70
	s_cbranch_scc1 .Lmy_lrua_tile
	s_waitcnt lgkmcnt(0)
	s_barrier

; __device__ __forceinline__ void lru_tile(const Params& P, int chunk, int head, int pass, char* smem_raw) {
;     ...
;   const int tid = VTID, lane = tid & 63, wid = tid >> 6;
;   const int q = tid >> 6, ch = tid & 63;
;   const int row0 = chunk * 128;
;   int seq_lo, seq_hi;
;   if (chunk < 256) { seq_lo = (chunk >> 6) << 13; seq_hi = seq_lo + 8192; }
;   else { const int b = (chunk - 256) >> 1; seq_lo = N_X + b * 256; seq_hi = seq_lo + 256; }
;   const int gch = head * 64 + ch;
;   const float* hfbuf = reinterpret_cast<const float*>(P.hy);
;   float* hfw = reinterpret_cast<float*>(P.hy);
;   {
;     const float w0 = P.conv_w[gch], w1 = P.conv_w[512 + gch], w2 = P.conv_w[1024 + gch], w3 = P.conv_w[1536 + gch];
;     const float cb = P.conv_b[gch];
;     const u16* zu = P.zq + gch;
;     const int r = row0 + q * 32;
.LBB0_477:
	v_readlane_b32 s0, v252, 0
	v_readlane_b32 s1, v252, 1
	v_readfirstlane_b32 s68, v153
	s_nop 3
	s_sub_u32 s0, s0, 0x170
	s_subb_u32 s1, s1, 0
	s_load_dwordx2 s[10:11], s[0:1], 0x148
	s_load_dwordx2 s[12:13], s[0:1], 0x158
	s_load_dwordx2 s[18:19], s[0:1], 0x130
	s_load_dwordx2 s[20:21], s[0:1], 0x128
	s_load_dwordx4 s[24:27], s[0:1], 0x70
	s_load_dwordx2 s[28:29], s[0:1], 0x88
	s_load_dwordx2 s[30:31], s[0:1], 0x98
	s_load_dwordx2 s[36:37], s[0:1], 0xa0
	s_lshl_b32 s4, s2, 1
	s_add_u32 s68, s4, s68
	s_mov_b32 s69, 0
	s_mov_b32 s70, 4
	s_cmp_lt_u32 s68, 64
	s_cselect_b32 s70, 5, 4
	s_mov_b32 s72, 0xffff0000
	s_mov_b32 s73, -1
	s_mov_b32 s74, 0
	s_mov_b32 s75, -1
	s_mov_b32 s76, 0
	s_mov_b32 s77, 0xffff0000
	s_mov_b32 s78, -1
	s_mov_b32 s79, 0x0000ffff
	s_mov_b32 s80, -1
	s_mov_b32 s81, 0
	s_mov_b32 s82, 0x0000ffff
	s_mov_b32 s83, 0
	v_and_b32_e32 v138, 63, v152
	v_lshrrev_b32_e32 v139, 4, v138
	v_and_b32_e32 v140, 15, v138
	v_bfe_u32 v141, v152, 6, 2
	v_lshl_add_u32 v255, v141, 4, v140
	v_mul_u32_u24_e32 v253, 0x12000, v153
	v_add_u32_e32 v253, 16, v253
	v_mul_u32_u24_e32 v134, 0x18000, v139
	v_lshl_add_u32 v134, v255, 1, v134
	v_lshlrev_b32_e32 v237, 16, v139
	v_lshl_add_u32 v237, v255, 1, v237
	v_lshlrev_b32_e32 v250, 3, v255
	v_lshlrev_b32_e32 v251, 7, v255
	v_lshl_add_u32 v251, v139, 4, v251
	v_lshrrev_b32_e32 v254, 3, v140
	v_lshl_add_u32 v254, v141, 1, v254
	v_lshlrev_b32_e32 v202, 1, v139
	v_xor_b32_e32 v89, v254, v202
	v_xor_b32_e32 v130, 1, v89
	v_and_b32_e32 v203, 7, v140
	v_lshl_add_u32 v202, v139, 12, v253
	v_lshl_add_u32 v202, v203, 1, v202
	v_lshl_add_u32 v89, v89, 4, v202
	v_lshl_add_u32 v130, v130, 4, v202
	v_lshrrev_b32_e32 v202, 2, v140
	v_and_b32_e32 v203, 3, v140
	v_lshl_add_u32 v254, v202, 5, v203
	v_lshl_add_u32 v254, v254, 7, v253
	v_lshrrev_b32_e32 v203, 1, v203
	v_lshl_add_u32 v202, v202, 1, v203
	v_xor_b32_e32 v202, v139, v202
	v_lshl_add_u32 v131, v202, 4, v254
	v_xor_b32_e32 v202, 4, v202
	v_lshl_add_u32 v133, v202, 4, v254
	v_cmp_eq_u32_e32 vcc, 0, v139
	s_mov_b64 s[84:85], vcc
	v_cmp_eq_u32_e32 vcc, 3, v139
	s_mov_b64 s[86:87], vcc
	s_waitcnt lgkmcnt(0)
; __device__ __forceinline__ float bf2f(u16 h) { return __uint_as_float(((unsigned)h) << 16); }
; __device__ __forceinline__ void lru_tile(const Params& P, int chunk, int head, int pass, char* smem_raw) {
;     ...
;   {
;     const float w0 = P.conv_w[gch], w1 = P.conv_w[512 + gch], w2 = P.conv_w[1024 + gch], w3 = P.conv_w[1536 + gch];
;     const float cb = P.conv_b[gch];
;     const u16* zu = P.zq + gch;
;     const int r = row0 + q * 32;
;     float uv[35];
; #pragma unroll
;     for (int i = 0; i < 35; ++i) {
;       const int rr = r - 2 + i;
;       uv[i] = (rr >= seq_lo && rr < seq_hi) ? bf2f(zu[(long)rr * 1536]) : 0.f;
;     ...
;     for (int i = 0; i < 4; ++i) {
;       const int idx = tid + 256 * i, rowi = idx >> 3, kg = idx & 7;
;       *reinterpret_cast<uint4*>(&sm_w[rowi * LDSS + kg * 8]) = ldg16(P.wg + ((long)(d * 8 + head) * 128 + rowi) * 64 + kg * 8);
;     }
;     float ba[4], bi[4], c8[4];
; #pragma unroll
;     for (int tc = 0; tc < 4; ++tc) {
;       const int cidx = d * 512 + head * 64 + 16 * tc + (lane & 15);
;       ba[tc] = P.b_a[cidx] * -1.4426950408889634f; bi[tc] = P.b_i[cidx] * -1.4426950408889634f;
;       const float nl = -P.lam[cidx];
;       const float e_ = __expf(nl);
;       const float sp = (nl > 20.f) ? nl
;                      : (e_ < 0.03f ? e_ * (1.f - e_ * (0.5f - e_ * (0.33333334f - 0.25f * e_))) : __logf(1.f + e_));
;       c8[tc] = 8.f * 1.4426950408889634f * sp;
	s_and_b32 s56, s68, 7
	s_lshl_b32 s56, s56, 6
	s_lshr_b32 s59, s68, 3
	s_cmp_lt_u32 s59, 256
	s_cselect_b32 s60, 63, 1
	s_and_b32 s57, s59, s60
	s_cmp_eq_u32 s57, 0
	s_cselect_b64 s[0:1], s[84:85], 0
	s_cmp_eq_u32 s57, s60
	s_cselect_b64 s[4:5], s[86:87], 0
	v_mov_b32_e32 v255, 0x1800
	v_cndmask_b32_e64 v150, 0, v255, s[0:1]
	v_lshlrev_b32_e32 v136, 1, v150
	v_add_u32_e32 v136, v134, v136
	v_add_u32_e32 v150, v134, v150
	v_cndmask_b32_e64 v151, 0, v255, s[4:5]
	v_sub_u32_e32 v151, v134, v151
	s_lshl_b32 s61, s59, 7
	s_mul_i32 s0, s61, 0xc00
	s_lshl_b32 s1, s56, 1
	s_add_u32 s0, s0, s1
	s_add_u32 s4, s10, s0
	s_addc_u32 s5, s11, 0
	s_sub_u32 s4, s4, 0x1800
	s_subb_u32 s5, s5, 0
	global_load_ushort v32, v136, s[4:5]
	s_add_u32 s4, s4, 0xc00
	s_addc_u32 s5, s5, 0
	global_load_ushort v33, v150, s[4:5]
	s_add_u32 s4, s4, 0xc00
	s_addc_u32 s5, s5, 0
	global_load_ushort v34, v134, s[4:5]
	s_add_u32 s4, s4, 0xc00
	s_addc_u32 s5, s5, 0
	global_load_ushort v35, v134, s[4:5]
	s_add_u32 s4, s4, 0xc00
	s_addc_u32 s5, s5, 0
	global_load_ushort v36, v134, s[4:5]
	s_add_u32 s4, s4, 0xc00
	s_addc_u32 s5, s5, 0
	global_load_ushort v37, v134, s[4:5]
	s_add_u32 s4, s4, 0xc00
	s_addc_u32 s5, s5, 0
	global_load_ushort v38, v134, s[4:5]
	s_add_u32 s4, s4, 0xc00
	s_addc_u32 s5, s5, 0
	global_load_ushort v39, v134, s[4:5]
	s_add_u32 s4, s4, 0xc00
	s_addc_u32 s5, s5, 0
	global_load_ushort v40, v134, s[4:5]
	s_add_u32 s4, s4, 0xc00
	s_addc_u32 s5, s5, 0
	global_load_ushort v41, v134, s[4:5]
	s_add_u32 s4, s4, 0xc00
	s_addc_u32 s5, s5, 0
	global_load_ushort v42, v134, s[4:5]
	s_add_u32 s4, s4, 0xc00
	s_addc_u32 s5, s5, 0
	global_load_ushort v43, v134, s[4:5]
	s_add_u32 s4, s4, 0xc00
	s_addc_u32 s5, s5, 0
	global_load_ushort v44, v134, s[4:5]
	s_add_u32 s4, s4, 0xc00
	s_addc_u32 s5, s5, 0
	global_load_ushort v45, v134, s[4:5]
	s_add_u32 s4, s4, 0xc00
	s_addc_u32 s5, s5, 0
	global_load_ushort v46, v134, s[4:5]
	s_add_u32 s4, s4, 0xc00
	s_addc_u32 s5, s5, 0
	global_load_ushort v47, v134, s[4:5]
	s_add_u32 s4, s4, 0xc00
	s_addc_u32 s5, s5, 0
	global_load_ushort v48, v134, s[4:5]
	s_add_u32 s4, s4, 0xc00
	s_addc_u32 s5, s5, 0
	global_load_ushort v49, v134, s[4:5]
	s_add_u32 s4, s4, 0xc00
	s_addc_u32 s5, s5, 0
	global_load_ushort v50, v134, s[4:5]
	s_add_u32 s4, s4, 0xc00
	s_addc_u32 s5, s5, 0
	global_load_ushort v51, v134, s[4:5]
	s_add_u32 s4, s4, 0xc00
	s_addc_u32 s5, s5, 0
	global_load_ushort v52, v134, s[4:5]
	s_add_u32 s4, s4, 0xc00
	s_addc_u32 s5, s5, 0
	global_load_ushort v53, v134, s[4:5]
	s_add_u32 s4, s4, 0xc00
	s_addc_u32 s5, s5, 0
	global_load_ushort v54, v134, s[4:5]
	s_add_u32 s4, s4, 0xc00
	s_addc_u32 s5, s5, 0
	global_load_ushort v55, v134, s[4:5]
	s_add_u32 s4, s4, 0xc00
	s_addc_u32 s5, s5, 0
	global_load_ushort v56, v134, s[4:5]
	s_add_u32 s4, s4, 0xc00
	s_addc_u32 s5, s5, 0
	global_load_ushort v57, v134, s[4:5]
	s_add_u32 s4, s4, 0xc00
	s_addc_u32 s5, s5, 0
	global_load_ushort v58, v134, s[4:5]
	s_add_u32 s4, s4, 0xc00
	s_addc_u32 s5, s5, 0
	global_load_ushort v59, v134, s[4:5]
	s_add_u32 s4, s4, 0xc00
	s_addc_u32 s5, s5, 0
	global_load_ushort v60, v134, s[4:5]
	s_add_u32 s4, s4, 0xc00
	s_addc_u32 s5, s5, 0
	global_load_ushort v61, v134, s[4:5]
	s_add_u32 s4, s4, 0xc00
	s_addc_u32 s5, s5, 0
	global_load_ushort v62, v134, s[4:5]
	s_add_u32 s4, s4, 0xc00
	s_addc_u32 s5, s5, 0
	global_load_ushort v63, v134, s[4:5]
	s_add_u32 s4, s4, 0xc00
	s_addc_u32 s5, s5, 0
	global_load_ushort v64, v134, s[4:5]
	s_add_u32 s4, s4, 0xc00
	s_addc_u32 s5, s5, 0
	global_load_ushort v66, v134, s[4:5]
	s_add_u32 s4, s4, 0xc00
	s_addc_u32 s5, s5, 0
	global_load_ushort v69, v151, s[4:5]
	v_bfe_u32 v255, v152, 6, 2
	v_and_b32_e32 v253, 15, v152
	v_lshl_add_u32 v255, v255, 4, v253
	v_add_u32_e32 v255, s56, v255
	v_lshlrev_b32_e32 v255, 2, v255
	global_load_dword v65, v255, s[24:25]
	global_load_dword v67, v255, s[24:25] offset:2048
	s_add_u32 s0, s24, 0x1000
	s_addc_u32 s1, s25, 0
	global_load_dword v68, v255, s[0:1]
	global_load_dword v70, v255, s[0:1] offset:2048
	global_load_dword v73, v255, s[26:27]
	s_add_u32 s0, s28, 0x0
	s_addc_u32 s1, s29, 0
	global_load_dword v75, v255, s[0:1]
	s_add_u32 s0, s30, 0x0
	s_addc_u32 s1, s31, 0
	global_load_dword v84, v255, s[0:1]
	s_add_u32 s0, s36, 0x0
	s_addc_u32 s1, s37, 0
	global_load_dword v85, v255, s[0:1]
	s_add_u32 s0, s28, 0x800
	s_addc_u32 s1, s29, 0
	global_load_dword v145, v255, s[0:1]
	s_add_u32 s0, s30, 0x800
	s_addc_u32 s1, s31, 0
	global_load_dword v146, v255, s[0:1]
	s_add_u32 s0, s36, 0x800
	s_addc_u32 s1, s37, 0
	global_load_dword v147, v255, s[0:1]
	s_lshl_b32 s0, s56, 8
	s_add_u32 s0, s0, 0x0
	s_add_u32 s4, s20, s0
	s_addc_u32 s5, s21, 0
	global_load_dwordx4 v[238:241], v251, s[4:5]
	global_load_dwordx4 v[242:245], v251, s[4:5] offset:64
	s_add_u32 s4, s4, 0x2000
	s_addc_u32 s5, s5, 0
	global_load_dwordx4 v[246:249], v251, s[4:5]
	global_load_dwordx4 v[194:197], v251, s[4:5] offset:64
	s_waitcnt vmcnt(0)
	v_mul_f32_e32 v75, 0xbfb8aa3b, v75
	v_mul_f32_e32 v84, 0xbfb8aa3b, v84
	v_sub_f32_e32 v138, 0, v85
	v_mul_f32_e32 v139, 0x3fb8aa3b, v138
	v_exp_f32_e32 v139, v139
	s_nop 0
	v_mul_f32_e32 v140, 0xbe800000, v139
	v_add_f32_e32 v140, 0x3eaaaaab, v140
	v_fma_f32 v140, -v139, v140, 0.5
	v_fma_f32 v140, -v139, v140, 1.0
	v_mul_f32_e32 v140, v139, v140
	v_add_f32_e32 v141, 1.0, v139
	v_log_f32_e32 v141, v141
	v_mov_b32_e32 v255, 0x3cf5c28f
	v_mul_f32_e32 v141, 0x3f317218, v141
	v_cmp_gt_f32_e32 vcc, v255, v139
	s_nop 1
	v_cndmask_b32_e32 v140, v141, v140, vcc
	v_mov_b32_e32 v255, 0x41a00000
	v_cmp_lt_f32_e32 vcc, v255, v138
	s_nop 1
	v_cndmask_b32_e32 v140, v140, v138, vcc
	v_mul_f32_e32 v85, 0xc138aa3b, v140
	v_mul_f32_e32 v145, 0xbfb8aa3b, v145
	v_mul_f32_e32 v146, 0xbfb8aa3b, v146
	v_sub_f32_e32 v138, 0, v147
	v_mul_f32_e32 v139, 0x3fb8aa3b, v138
	v_exp_f32_e32 v139, v139
	s_nop 0
	v_mul_f32_e32 v140, 0xbe800000, v139
	v_add_f32_e32 v140, 0x3eaaaaab, v140
	v_fma_f32 v140, -v139, v140, 0.5
	v_fma_f32 v140, -v139, v140, 1.0
	v_mul_f32_e32 v140, v139, v140
	v_add_f32_e32 v141, 1.0, v139
	v_log_f32_e32 v141, v141
	v_mov_b32_e32 v255, 0x3cf5c28f
	v_mul_f32_e32 v141, 0x3f317218, v141
	v_cmp_gt_f32_e32 vcc, v255, v139
	s_nop 1
	v_cndmask_b32_e32 v140, v141, v140, vcc
	v_mov_b32_e32 v255, 0x41a00000
	v_cmp_lt_f32_e32 vcc, v255, v138
	s_nop 1
	v_cndmask_b32_e32 v140, v140, v138, vcc
	v_mul_f32_e32 v147, 0xc138aa3b, v140

; __device__ __forceinline__ float bf2f(u16 h) { return __uint_as_float(((unsigned)h) << 16); }
; __device__ __forceinline__ void lru_tile(const Params& P, int chunk, int head, int pass, char* smem_raw) {
;     ...
; #pragma unroll
;     for (int i = 0; i < 35; ++i) {
;       const int rr = r - 2 + i;
;       uv[i] = (rr >= seq_lo && rr < seq_hi) ? bf2f(zu[(long)rr * 1536]) : 0.f;
;     }
;     __syncthreads();
; #pragma unroll
;     for (int i = 0; i < 32; ++i) {
;       const float v = cb + uv[i] * w0 + uv[i + 1] * w1 + uv[i + 2] * w2 + uv[i + 3] * w3;
;       sm_uc[(q * 32 + i) * LDSS + ch] = f2bf(v);
;     }
.Lmy_lrub_fl:
	s_cmp_eq_u32 s57, 0
	s_cselect_b64 s[0:1], s[84:85], 0
	s_cmp_eq_u32 s57, s60
	s_cselect_b64 s[4:5], s[86:87], 0
	v_cndmask_b32_e64 v202, 1.0, 0, s[0:1]
	v_cndmask_b32_e64 v203, 1.0, 0, s[4:5]
	s_barrier
	s_waitcnt vmcnt(32)
	v_lshlrev_b32_e32 v90, 16, v32
	v_lshlrev_b32_e32 v91, 16, v33
	v_lshlrev_b32_e32 v92, 16, v34
	v_lshlrev_b32_e32 v93, 16, v35
	v_lshlrev_b32_e32 v94, 16, v36
	v_lshlrev_b32_e32 v95, 16, v37
	v_lshlrev_b32_e32 v96, 16, v38
	v_lshlrev_b32_e32 v97, 16, v39
	v_lshlrev_b32_e32 v98, 16, v40
	v_lshlrev_b32_e32 v99, 16, v41
	v_lshlrev_b32_e32 v100, 16, v42
	v_lshlrev_b32_e32 v101, 16, v43
	v_lshlrev_b32_e32 v102, 16, v44
	v_lshlrev_b32_e32 v103, 16, v45
	v_lshlrev_b32_e32 v104, 16, v46
	v_lshlrev_b32_e32 v105, 16, v47
	v_lshlrev_b32_e32 v106, 16, v48
	v_lshlrev_b32_e32 v107, 16, v49
	v_lshlrev_b32_e32 v108, 16, v50
	v_lshlrev_b32_e32 v109, 16, v51
	v_lshlrev_b32_e32 v110, 16, v52
	v_lshlrev_b32_e32 v111, 16, v53
	v_lshlrev_b32_e32 v112, 16, v54
	v_lshlrev_b32_e32 v113, 16, v55
	v_lshlrev_b32_e32 v114, 16, v56
	v_lshlrev_b32_e32 v115, 16, v57
	v_lshlrev_b32_e32 v116, 16, v58
	v_lshlrev_b32_e32 v117, 16, v59
	v_lshlrev_b32_e32 v118, 16, v60
	v_lshlrev_b32_e32 v119, 16, v61
	v_lshlrev_b32_e32 v120, 16, v62
	v_lshlrev_b32_e32 v121, 16, v63
	v_lshlrev_b32_e32 v122, 16, v64
	v_lshlrev_b32_e32 v123, 16, v66
	v_lshlrev_b32_e32 v124, 16, v69
	v_mul_f32_e32 v90, v90, v202
	v_mul_f32_e32 v91, v91, v202
	v_mul_f32_e32 v124, v124, v203
	v_fma_f32 v162, v90, v65, v73
	v_fma_f32 v162, v91, v67, v162
	v_fma_f32 v162, v92, v68, v162
	v_fma_f32 v162, v93, v70, v162
	v_fma_f32 v163, v91, v65, v73
	v_fma_f32 v163, v92, v67, v163
	v_fma_f32 v163, v93, v68, v163
	v_fma_f32 v163, v94, v70, v163
	v_fma_f32 v164, v92, v65, v73
	v_fma_f32 v164, v93, v67, v164
	v_fma_f32 v164, v94, v68, v164
	v_fma_f32 v164, v95, v70, v164
	v_fma_f32 v165, v93, v65, v73
	v_fma_f32 v165, v94, v67, v165
	v_fma_f32 v165, v95, v68, v165
	v_fma_f32 v165, v96, v70, v165
	v_fma_f32 v166, v94, v65, v73
	v_fma_f32 v166, v95, v67, v166
	v_fma_f32 v166, v96, v68, v166
	v_fma_f32 v166, v97, v70, v166
	v_fma_f32 v167, v95, v65, v73
	v_fma_f32 v167, v96, v67, v167
	v_fma_f32 v167, v97, v68, v167
	v_fma_f32 v167, v98, v70, v167
	v_fma_f32 v168, v96, v65, v73
	v_fma_f32 v168, v97, v67, v168
	v_fma_f32 v168, v98, v68, v168
	v_fma_f32 v168, v99, v70, v168
	v_fma_f32 v169, v97, v65, v73
	v_fma_f32 v169, v98, v67, v169
	v_fma_f32 v169, v99, v68, v169
	v_fma_f32 v169, v100, v70, v169
	v_fma_f32 v170, v98, v65, v73
	v_fma_f32 v170, v99, v67, v170
	v_fma_f32 v170, v100, v68, v170
	v_fma_f32 v170, v101, v70, v170
	v_fma_f32 v171, v99, v65, v73
	v_fma_f32 v171, v100, v67, v171
	v_fma_f32 v171, v101, v68, v171
	v_fma_f32 v171, v102, v70, v171
	v_fma_f32 v172, v100, v65, v73
	v_fma_f32 v172, v101, v67, v172
	v_fma_f32 v172, v102, v68, v172
	v_fma_f32 v172, v103, v70, v172
	v_fma_f32 v173, v101, v65, v73
	v_fma_f32 v173, v102, v67, v173
	v_fma_f32 v173, v103, v68, v173
	v_fma_f32 v173, v104, v70, v173
	v_fma_f32 v174, v102, v65, v73
	v_fma_f32 v174, v103, v67, v174
	v_fma_f32 v174, v104, v68, v174
	v_fma_f32 v174, v105, v70, v174
	v_fma_f32 v175, v103, v65, v73
	v_fma_f32 v175, v104, v67, v175
	v_fma_f32 v175, v105, v68, v175
	v_fma_f32 v175, v106, v70, v175
	v_fma_f32 v176, v104, v65, v73
	v_fma_f32 v176, v105, v67, v176
	v_fma_f32 v176, v106, v68, v176
	v_fma_f32 v176, v107, v70, v176
	v_fma_f32 v177, v105, v65, v73
	v_fma_f32 v177, v106, v67, v177
	v_fma_f32 v177, v107, v68, v177
	v_fma_f32 v177, v108, v70, v177
	v_fma_f32 v178, v106, v65, v73
	v_fma_f32 v178, v107, v67, v178
	v_fma_f32 v178, v108, v68, v178
	v_fma_f32 v178, v109, v70, v178
	v_fma_f32 v179, v107, v65, v73
	v_fma_f32 v179, v108, v67, v179
	v_fma_f32 v179, v109, v68, v179
	v_fma_f32 v179, v110, v70, v179
	v_fma_f32 v180, v108, v65, v73
	v_fma_f32 v180, v109, v67, v180
	v_fma_f32 v180, v110, v68, v180
	v_fma_f32 v180, v111, v70, v180
	v_fma_f32 v181, v109, v65, v73
	v_fma_f32 v181, v110, v67, v181
	v_fma_f32 v181, v111, v68, v181
	v_fma_f32 v181, v112, v70, v181
	v_fma_f32 v182, v110, v65, v73
	v_fma_f32 v182, v111, v67, v182
	v_fma_f32 v182, v112, v68, v182
	v_fma_f32 v182, v113, v70, v182
	v_fma_f32 v183, v111, v65, v73
	v_fma_f32 v183, v112, v67, v183
	v_fma_f32 v183, v113, v68, v183
	v_fma_f32 v183, v114, v70, v183
	v_fma_f32 v184, v112, v65, v73
	v_fma_f32 v184, v113, v67, v184
	v_fma_f32 v184, v114, v68, v184
	v_fma_f32 v184, v115, v70, v184
	v_fma_f32 v185, v113, v65, v73
	v_fma_f32 v185, v114, v67, v185
	v_fma_f32 v185, v115, v68, v185
	v_fma_f32 v185, v116, v70, v185
	v_fma_f32 v186, v114, v65, v73
	v_fma_f32 v186, v115, v67, v186
	v_fma_f32 v186, v116, v68, v186
	v_fma_f32 v186, v117, v70, v186
	v_fma_f32 v187, v115, v65, v73
	v_fma_f32 v187, v116, v67, v187
	v_fma_f32 v187, v117, v68, v187
	v_fma_f32 v187, v118, v70, v187
	v_fma_f32 v188, v116, v65, v73
	v_fma_f32 v188, v117, v67, v188
	v_fma_f32 v188, v118, v68, v188
	v_fma_f32 v188, v119, v70, v188
	v_fma_f32 v189, v117, v65, v73
	v_fma_f32 v189, v118, v67, v189
	v_fma_f32 v189, v119, v68, v189
	v_fma_f32 v189, v120, v70, v189
	v_fma_f32 v190, v118, v65, v73
	v_fma_f32 v190, v119, v67, v190
	v_fma_f32 v190, v120, v68, v190
	v_fma_f32 v190, v121, v70, v190
	v_fma_f32 v191, v119, v65, v73
	v_fma_f32 v191, v120, v67, v191
	v_fma_f32 v191, v121, v68, v191
	v_fma_f32 v191, v122, v70, v191
	v_fma_f32 v192, v120, v65, v73
	v_fma_f32 v192, v121, v67, v192
	v_fma_f32 v192, v122, v68, v192
	v_fma_f32 v192, v123, v70, v192
	v_fma_f32 v193, v121, v65, v73
	v_fma_f32 v193, v122, v67, v193
	v_fma_f32 v193, v123, v68, v193
	v_fma_f32 v193, v124, v70, v193
; __device__ __forceinline__ void lru_tile(const Params& P, int chunk, int head, int pass, char* smem_raw) {
;     ...
;     for (int i = 0; i < 32; ++i) {
;       const float v = cb + uv[i] * w0 + uv[i + 1] * w1 + uv[i + 2] * w2 + uv[i + 3] * w3;
;       sm_uc[(q * 32 + i) * LDSS + ch] = f2bf(v);
;     }
;   }
;   if (pass == 2 && tid < 128) {
;     const int d = tid >> 6;
;     float h = 0.f;
;     const float2* S = P.summ + (long)d * 264 * 512 + gch;
;     if (chunk < 256) {
;       const int b = chunk >> 6, j = chunk & 63;
;       if (d == 0) {
;         float2 s = S[(long)(256 + 2 * b) * 512]; h = s.x * h + s.y;
;         s = S[(long)(256 + 2 * b + 1) * 512]; h = s.x * h + s.y;
;         int i = 0;
;         for (; i + 8 <= j; i += 8) {
;           float2 sv[8];
; #pragma unroll
;           for (int u = 0; u < 8; ++u) sv[u] = S[(long)(b * 64 + i + u) * 512];
; #pragma unroll
;           for (int u = 0; u < 8; ++u) h = sv[u].x * h + sv[u].y;
;         }
;         for (; i < j; ++i) { s = S[(long)(b * 64 + i) * 512]; h = s.x * h + s.y; }
	v_cvt_pk_bf16_f32 v162, v162, v162
	v_cvt_pk_bf16_f32 v163, v163, v163
	v_cvt_pk_bf16_f32 v164, v164, v164
	v_cvt_pk_bf16_f32 v165, v165, v165
	v_cvt_pk_bf16_f32 v166, v166, v166
	v_cvt_pk_bf16_f32 v167, v167, v167
	v_cvt_pk_bf16_f32 v168, v168, v168
	v_cvt_pk_bf16_f32 v169, v169, v169
	v_cvt_pk_bf16_f32 v170, v170, v170
	v_cvt_pk_bf16_f32 v171, v171, v171
	v_cvt_pk_bf16_f32 v172, v172, v172
	v_cvt_pk_bf16_f32 v173, v173, v173
	v_cvt_pk_bf16_f32 v174, v174, v174
	v_cvt_pk_bf16_f32 v175, v175, v175
	v_cvt_pk_bf16_f32 v176, v176, v176
	v_cvt_pk_bf16_f32 v177, v177, v177
	v_cvt_pk_bf16_f32 v178, v178, v178
	v_cvt_pk_bf16_f32 v179, v179, v179
	v_cvt_pk_bf16_f32 v180, v180, v180
	v_cvt_pk_bf16_f32 v181, v181, v181
	v_cvt_pk_bf16_f32 v182, v182, v182
	v_cvt_pk_bf16_f32 v183, v183, v183
	v_cvt_pk_bf16_f32 v184, v184, v184
	v_cvt_pk_bf16_f32 v185, v185, v185
	v_cvt_pk_bf16_f32 v186, v186, v186
	v_cvt_pk_bf16_f32 v187, v187, v187
	v_cvt_pk_bf16_f32 v188, v188, v188
	v_cvt_pk_bf16_f32 v189, v189, v189
	v_cvt_pk_bf16_f32 v190, v190, v190
	v_cvt_pk_bf16_f32 v191, v191, v191
	v_cvt_pk_bf16_f32 v192, v192, v192
	v_cvt_pk_bf16_f32 v193, v193, v193
	ds_write_b16 v89, v162 offset:0
	ds_write_b16 v89, v163 offset:128
	ds_write_b16 v130, v164 offset:256
	ds_write_b16 v130, v165 offset:384
	ds_write_b16 v89, v166 offset:512
	ds_write_b16 v89, v167 offset:640
	ds_write_b16 v130, v168 offset:768
	ds_write_b16 v130, v169 offset:896
	ds_write_b16 v89, v170 offset:1024
	ds_write_b16 v89, v171 offset:1152
	ds_write_b16 v130, v172 offset:1280
	ds_write_b16 v130, v173 offset:1408
	ds_write_b16 v89, v174 offset:1536
	ds_write_b16 v89, v175 offset:1664
	ds_write_b16 v130, v176 offset:1792
	ds_write_b16 v130, v177 offset:1920
	ds_write_b16 v89, v178 offset:2048
	ds_write_b16 v89, v179 offset:2176
	ds_write_b16 v130, v180 offset:2304
	ds_write_b16 v130, v181 offset:2432
	ds_write_b16 v89, v182 offset:2560
	ds_write_b16 v89, v183 offset:2688
	ds_write_b16 v130, v184 offset:2816
	ds_write_b16 v130, v185 offset:2944
	ds_write_b16 v89, v186 offset:3072
	ds_write_b16 v89, v187 offset:3200
	ds_write_b16 v130, v188 offset:3328
	ds_write_b16 v130, v189 offset:3456
	ds_write_b16 v89, v190 offset:3584
	ds_write_b16 v89, v191 offset:3712
	ds_write_b16 v130, v192 offset:3840
	ds_write_b16 v130, v193 offset:3968
	v_lshlrev_b32_e32 v162, 16, v162
	v_lshlrev_b32_e32 v163, 16, v163
	v_lshlrev_b32_e32 v164, 16, v164
	v_lshlrev_b32_e32 v165, 16, v165
	v_lshlrev_b32_e32 v166, 16, v166
	v_lshlrev_b32_e32 v167, 16, v167
	v_lshlrev_b32_e32 v168, 16, v168
	v_lshlrev_b32_e32 v169, 16, v169
	v_lshlrev_b32_e32 v170, 16, v170
	v_lshlrev_b32_e32 v171, 16, v171
	v_lshlrev_b32_e32 v172, 16, v172
	v_lshlrev_b32_e32 v173, 16, v173
	v_lshlrev_b32_e32 v174, 16, v174
	v_lshlrev_b32_e32 v175, 16, v175
	v_lshlrev_b32_e32 v176, 16, v176
	v_lshlrev_b32_e32 v177, 16, v177
	v_lshlrev_b32_e32 v178, 16, v178
	v_lshlrev_b32_e32 v179, 16, v179
	v_lshlrev_b32_e32 v180, 16, v180
	v_lshlrev_b32_e32 v181, 16, v181
	v_lshlrev_b32_e32 v182, 16, v182
	v_lshlrev_b32_e32 v183, 16, v183
	v_lshlrev_b32_e32 v184, 16, v184
	v_lshlrev_b32_e32 v185, 16, v185
	v_lshlrev_b32_e32 v186, 16, v186
	v_lshlrev_b32_e32 v187, 16, v187
	v_lshlrev_b32_e32 v188, 16, v188
	v_lshlrev_b32_e32 v189, 16, v189
	v_lshlrev_b32_e32 v190, 16, v190
	v_lshlrev_b32_e32 v191, 16, v191
	v_lshlrev_b32_e32 v192, 16, v192
	v_lshlrev_b32_e32 v193, 16, v193
	s_waitcnt lgkmcnt(0)
	s_barrier
	v_mov_b32_e32 v148, 0
	s_lshl_b32 s0, s56, 3
	s_add_u32 s0, s0, 0x0
	s_add_u32 s4, s18, s0
	s_addc_u32 s5, s19, 0
	s_cmp_lt_u32 s71, 256
	s_cbranch_scc0 .Lmy_lrub_lb0_ctx
	s_lshr_b32 s0, s71, 6
	s_lshl_b32 s1, s0, 1
	s_add_u32 s1, s1, 256
	s_add_u32 s60, s1, 0
	s_lshl_b32 s60, s60, 12
	s_add_u32 s60, s4, s60
	s_addc_u32 s61, s5, 0
	global_load_dwordx2 v[0:1], v250, s[60:61]
	s_add_u32 s60, s1, 1
	s_lshl_b32 s60, s60, 12
	s_add_u32 s60, s4, s60
	s_addc_u32 s61, s5, 0
	global_load_dwordx2 v[2:3], v250, s[60:61]
	s_lshl_b32 s0, s0, 6
	v_bfe_u32 v150, v152, 4, 2
	s_mov_b32 s1, s57
	v_lshl_add_u32 v136, v150, 16, v250
	s_lshl_b32 s60, s0, 12
	v_lshlrev_b32_e32 v150, 4, v150
	v_sub_u32_e32 v150, s1, v150
	s_add_u32 s60, s4, s60
	s_addc_u32 s61, s5, 0
	global_load_dwordx2 v[4:5], v136, s[60:61]
	s_add_u32 s60, s60, 0x1000
	s_addc_u32 s61, s61, 0
	global_load_dwordx2 v[6:7], v136, s[60:61]
	s_add_u32 s60, s60, 0x1000
	s_addc_u32 s61, s61, 0
	global_load_dwordx2 v[8:9], v136, s[60:61]
	s_add_u32 s60, s60, 0x1000
	s_addc_u32 s61, s61, 0
	global_load_dwordx2 v[10:11], v136, s[60:61]
	s_add_u32 s60, s60, 0x1000
	s_addc_u32 s61, s61, 0
	global_load_dwordx2 v[12:13], v136, s[60:61]
	s_add_u32 s60, s60, 0x1000
	s_addc_u32 s61, s61, 0
	global_load_dwordx2 v[14:15], v136, s[60:61]
	s_add_u32 s60, s60, 0x1000
	s_addc_u32 s61, s61, 0
	global_load_dwordx2 v[16:17], v136, s[60:61]
	s_add_u32 s60, s60, 0x1000
	s_addc_u32 s61, s61, 0
	global_load_dwordx2 v[18:19], v136, s[60:61]
	s_add_u32 s60, s60, 0x1000
	s_addc_u32 s61, s61, 0
	global_load_dwordx2 v[20:21], v136, s[60:61]
	s_add_u32 s60, s60, 0x1000
	s_addc_u32 s61, s61, 0
	global_load_dwordx2 v[22:23], v136, s[60:61]
	s_add_u32 s60, s60, 0x1000
	s_addc_u32 s61, s61, 0
	global_load_dwordx2 v[24:25], v136, s[60:61]
	s_add_u32 s60, s60, 0x1000
	s_addc_u32 s61, s61, 0
	global_load_dwordx2 v[26:27], v136, s[60:61]
	s_add_u32 s60, s60, 0x1000
	s_addc_u32 s61, s61, 0
	global_load_dwordx2 v[28:29], v136, s[60:61]
	s_add_u32 s60, s60, 0x1000
	s_addc_u32 s61, s61, 0
	global_load_dwordx2 v[30:31], v136, s[60:61]
	s_add_u32 s60, s60, 0x1000
	s_addc_u32 s61, s61, 0
	global_load_dwordx2 v[32:33], v136, s[60:61]
	s_add_u32 s60, s60, 0x1000
	s_addc_u32 s61, s61, 0
	global_load_dwordx2 v[34:35], v136, s[60:61]
	s_waitcnt vmcnt(16)
; __device__ __forceinline__ void lru_tile(const Params& P, int chunk, int head, int pass, char* smem_raw) {
;     ...
;     if (chunk < 256) {
;       const int b = chunk >> 6, j = chunk & 63;
;       if (d == 0) {
;         float2 s = S[(long)(256 + 2 * b) * 512]; h = s.x * h + s.y;
;         s = S[(long)(256 + 2 * b + 1) * 512]; h = s.x * h + s.y;
;         int i = 0;
;         for (; i + 8 <= j; i += 8) {
;           float2 sv[8];
; #pragma unroll
;           for (int u = 0; u < 8; ++u) sv[u] = S[(long)(b * 64 + i + u) * 512];
; #pragma unroll
;           for (int u = 0; u < 8; ++u) h = sv[u].x * h + sv[u].y;
;         }
;         for (; i < j; ++i) { s = S[(long)(b * 64 + i) * 512]; h = s.x * h + s.y; }
;       } else {
;         float2 s = S[(long)(256 + 2 * b + 1) * 512]; h = s.x * h + s.y;
;         s = S[(long)(256 + 2 * b) * 512]; h = s.x * h + s.y;
;         int i = 63;
;         for (; i - 8 >= j; i -= 8) {
;           float2 sv[8];
; #pragma unroll
;           for (int u = 0; u < 8; ++u) sv[u] = S[(long)(b * 64 + i - u) * 512];
; #pragma unroll
;           for (int u = 0; u < 8; ++u) h = sv[u].x * h + sv[u].y;
;         }
;         for (; i > j; --i) { s = S[(long)(b * 64 + i) * 512]; h = s.x * h + s.y; }
	v_fma_f32 v148, v0, v148, v1
	v_fma_f32 v148, v2, v148, v3
	v_mov_b32_e32 v253, 1.0
	v_mov_b32_e32 v254, 0
	s_waitcnt vmcnt(0)
	v_cmp_lt_i32_e32 vcc, 0, v150
	s_nop 1
	v_cndmask_b32_e32 v4, 1.0, v4, vcc
	v_cndmask_b32_e32 v5, 0, v5, vcc
	v_fma_f32 v254, v4, v254, v5
	v_mul_f32_e32 v253, v253, v4
	v_cmp_lt_i32_e32 vcc, 1, v150
	s_nop 1
	v_cndmask_b32_e32 v6, 1.0, v6, vcc
	v_cndmask_b32_e32 v7, 0, v7, vcc
	v_fma_f32 v254, v6, v254, v7
	v_mul_f32_e32 v253, v253, v6
	v_cmp_lt_i32_e32 vcc, 2, v150
	s_nop 1
	v_cndmask_b32_e32 v8, 1.0, v8, vcc
	v_cndmask_b32_e32 v9, 0, v9, vcc
	v_fma_f32 v254, v8, v254, v9
	v_mul_f32_e32 v253, v253, v8
	v_cmp_lt_i32_e32 vcc, 3, v150
	s_nop 1
	v_cndmask_b32_e32 v10, 1.0, v10, vcc
	v_cndmask_b32_e32 v11, 0, v11, vcc
	v_fma_f32 v254, v10, v254, v11
	v_mul_f32_e32 v253, v253, v10
	v_cmp_lt_i32_e32 vcc, 4, v150
	s_nop 1
	v_cndmask_b32_e32 v12, 1.0, v12, vcc
	v_cndmask_b32_e32 v13, 0, v13, vcc
	v_fma_f32 v254, v12, v254, v13
	v_mul_f32_e32 v253, v253, v12
	v_cmp_lt_i32_e32 vcc, 5, v150
	s_nop 1
	v_cndmask_b32_e32 v14, 1.0, v14, vcc
	v_cndmask_b32_e32 v15, 0, v15, vcc
	v_fma_f32 v254, v14, v254, v15
	v_mul_f32_e32 v253, v253, v14
	v_cmp_lt_i32_e32 vcc, 6, v150
	s_nop 1
	v_cndmask_b32_e32 v16, 1.0, v16, vcc
	v_cndmask_b32_e32 v17, 0, v17, vcc
	v_fma_f32 v254, v16, v254, v17
	v_mul_f32_e32 v253, v253, v16
	v_cmp_lt_i32_e32 vcc, 7, v150
	s_nop 1
	v_cndmask_b32_e32 v18, 1.0, v18, vcc
	v_cndmask_b32_e32 v19, 0, v19, vcc
	v_fma_f32 v254, v18, v254, v19
	v_mul_f32_e32 v253, v253, v18
	v_cmp_lt_i32_e32 vcc, 8, v150
	s_nop 1
	v_cndmask_b32_e32 v20, 1.0, v20, vcc
	v_cndmask_b32_e32 v21, 0, v21, vcc
	v_fma_f32 v254, v20, v254, v21
	v_mul_f32_e32 v253, v253, v20
	v_cmp_lt_i32_e32 vcc, 9, v150
	s_nop 1
	v_cndmask_b32_e32 v22, 1.0, v22, vcc
	v_cndmask_b32_e32 v23, 0, v23, vcc
	v_fma_f32 v254, v22, v254, v23
	v_mul_f32_e32 v253, v253, v22
	v_cmp_lt_i32_e32 vcc, 10, v150
	s_nop 1
	v_cndmask_b32_e32 v24, 1.0, v24, vcc
	v_cndmask_b32_e32 v25, 0, v25, vcc
	v_fma_f32 v254, v24, v254, v25
	v_mul_f32_e32 v253, v253, v24
	v_cmp_lt_i32_e32 vcc, 11, v150
	s_nop 1
	v_cndmask_b32_e32 v26, 1.0, v26, vcc
	v_cndmask_b32_e32 v27, 0, v27, vcc
	v_fma_f32 v254, v26, v254, v27
	v_mul_f32_e32 v253, v253, v26
	v_cmp_lt_i32_e32 vcc, 12, v150
	s_nop 1
	v_cndmask_b32_e32 v28, 1.0, v28, vcc
	v_cndmask_b32_e32 v29, 0, v29, vcc
	v_fma_f32 v254, v28, v254, v29
	v_mul_f32_e32 v253, v253, v28
	v_cmp_lt_i32_e32 vcc, 13, v150
	s_nop 1
	v_cndmask_b32_e32 v30, 1.0, v30, vcc
	v_cndmask_b32_e32 v31, 0, v31, vcc
	v_fma_f32 v254, v30, v254, v31
	v_mul_f32_e32 v253, v253, v30
	v_cmp_lt_i32_e32 vcc, 14, v150
	s_nop 1
	v_cndmask_b32_e32 v32, 1.0, v32, vcc
	v_cndmask_b32_e32 v33, 0, v33, vcc
	v_fma_f32 v254, v32, v254, v33
	v_mul_f32_e32 v253, v253, v32
	v_cmp_lt_i32_e32 vcc, 15, v150
	s_nop 1
	v_cndmask_b32_e32 v34, 1.0, v34, vcc
	v_cndmask_b32_e32 v35, 0, v35, vcc
	v_fma_f32 v254, v34, v254, v35
	v_mul_f32_e32 v253, v253, v34
	v_mov_b32_e32 v138, v253
	v_mov_b32_e32 v139, v253
	s_nop 1
	v_permlane16_swap_b32_e32 v138, v139
	v_mov_b32_e32 v140, v138
	v_mov_b32_e32 v141, v139
	s_nop 1
	v_permlane32_swap_b32_e32 v138, v140
	v_permlane32_swap_b32_e32 v139, v141
	v_mov_b32_e32 v198, v254
	v_mov_b32_e32 v199, v254
	s_nop 1
	v_permlane16_swap_b32_e32 v198, v199
	v_mov_b32_e32 v200, v198
	v_mov_b32_e32 v201, v199
	s_nop 1
	v_permlane32_swap_b32_e32 v198, v200
	v_permlane32_swap_b32_e32 v199, v201
	v_fma_f32 v148, v138, v148, v198
	v_fma_f32 v148, v139, v148, v199
	v_fma_f32 v148, v140, v148, v200
	v_fma_f32 v148, v141, v148, v201
	s_branch .Lmy_lrub_lb0_done
.Lmy_lrub_lb0_ctx:
	s_sub_u32 s0, s71, 256
	s_and_b32 s1, s0, 1
	s_cmp_eq_u32 s1, 1
	s_cbranch_scc0 .Lmy_lrub_lb0_done
	s_and_b32 s0, s0, -2
	s_add_u32 s0, s0, 256
	s_lshl_b32 s0, s0, 12
	s_add_u32 s60, s4, s0
	s_addc_u32 s61, s5, 0
	global_load_dwordx2 v[0:1], v250, s[60:61]
	s_waitcnt vmcnt(0)
	v_mov_b32_e32 v148, v1
.Lmy_lrub_lb0_done:
	v_mov_b32_e32 v149, 0
	s_lshl_b32 s0, s56, 3
	s_add_u32 s0, s0, 0x108000
	s_add_u32 s4, s18, s0
	s_addc_u32 s5, s19, 0
	s_cmp_lt_u32 s71, 256
	s_cbranch_scc0 .Lmy_lrub_lb1_ctx
	s_lshr_b32 s0, s71, 6
	s_lshl_b32 s1, s0, 1
	s_add_u32 s1, s1, 256
	s_add_u32 s60, s1, 1
	s_lshl_b32 s60, s60, 12
	s_add_u32 s60, s4, s60
	s_addc_u32 s61, s5, 0
	global_load_dwordx2 v[0:1], v250, s[60:61]
	s_add_u32 s60, s1, 0
	s_lshl_b32 s60, s60, 12
	s_add_u32 s60, s4, s60
	s_addc_u32 s61, s5, 0
	global_load_dwordx2 v[2:3], v250, s[60:61]
	s_lshl_b32 s0, s0, 6
	v_bfe_u32 v150, v152, 4, 2
	s_sub_u32 s1, 63, s57
	v_sub_u32_e32 v136, 3, v150
	v_lshl_add_u32 v136, v136, 16, v250
	s_add_u32 s60, s0, 15
	s_lshl_b32 s60, s60, 12
	v_lshlrev_b32_e32 v150, 4, v150
	v_sub_u32_e32 v150, s1, v150
	s_add_u32 s60, s4, s60
	s_addc_u32 s61, s5, 0
	global_load_dwordx2 v[4:5], v136, s[60:61]
	s_sub_u32 s60, s60, 0x1000
	s_subb_u32 s61, s61, 0
	global_load_dwordx2 v[6:7], v136, s[60:61]
	s_sub_u32 s60, s60, 0x1000
	s_subb_u32 s61, s61, 0
	global_load_dwordx2 v[8:9], v136, s[60:61]
	s_sub_u32 s60, s60, 0x1000
	s_subb_u32 s61, s61, 0
	global_load_dwordx2 v[10:11], v136, s[60:61]
	s_sub_u32 s60, s60, 0x1000
	s_subb_u32 s61, s61, 0
	global_load_dwordx2 v[12:13], v136, s[60:61]
	s_sub_u32 s60, s60, 0x1000
	s_subb_u32 s61, s61, 0
	global_load_dwordx2 v[14:15], v136, s[60:61]
	s_sub_u32 s60, s60, 0x1000
	s_subb_u32 s61, s61, 0
	global_load_dwordx2 v[16:17], v136, s[60:61]
	s_sub_u32 s60, s60, 0x1000
	s_subb_u32 s61, s61, 0
	global_load_dwordx2 v[18:19], v136, s[60:61]
	s_sub_u32 s60, s60, 0x1000
	s_subb_u32 s61, s61, 0
	global_load_dwordx2 v[20:21], v136, s[60:61]
	s_sub_u32 s60, s60, 0x1000
	s_subb_u32 s61, s61, 0
	global_load_dwordx2 v[22:23], v136, s[60:61]
	s_sub_u32 s60, s60, 0x1000
	s_subb_u32 s61, s61, 0
	global_load_dwordx2 v[24:25], v136, s[60:61]
	s_sub_u32 s60, s60, 0x1000
	s_subb_u32 s61, s61, 0
	global_load_dwordx2 v[26:27], v136, s[60:61]
	s_sub_u32 s60, s60, 0x1000
	s_subb_u32 s61, s61, 0
	global_load_dwordx2 v[28:29], v136, s[60:61]
	s_sub_u32 s60, s60, 0x1000
	s_subb_u32 s61, s61, 0
	global_load_dwordx2 v[30:31], v136, s[60:61]
	s_sub_u32 s60, s60, 0x1000
	s_subb_u32 s61, s61, 0
	global_load_dwordx2 v[32:33], v136, s[60:61]
	s_sub_u32 s60, s60, 0x1000
	s_subb_u32 s61, s61, 0
	global_load_dwordx2 v[34:35], v136, s[60:61]
	s_waitcnt vmcnt(16)
; __device__ __forceinline__ float bf2f(u16 h) { return __uint_as_float(((unsigned)h) << 16); }
; __device__ __forceinline__ void lru_tile(const Params& P, int chunk, int head, int pass, char* smem_raw) {
;     ...
;     const int r = row0 + q * 32;
;     float uv[35];
; #pragma unroll
;     for (int i = 0; i < 35; ++i) {
;       const int rr = r - 2 + i;
;       uv[i] = (rr >= seq_lo && rr < seq_hi) ? bf2f(zu[(long)rr * 1536]) : 0.f;
;     ...
;         float2 s = S[(long)(256 + 2 * b + 1) * 512]; h = s.x * h + s.y;
;         s = S[(long)(256 + 2 * b) * 512]; h = s.x * h + s.y;
;         int i = 63;
;         for (; i - 8 >= j; i -= 8) {
;           float2 sv[8];
; #pragma unroll
;           for (int u = 0; u < 8; ++u) sv[u] = S[(long)(b * 64 + i - u) * 512];
; #pragma unroll
;           for (int u = 0; u < 8; ++u) h = sv[u].x * h + sv[u].y;
;         }
;         for (; i > j; --i) { s = S[(long)(b * 64 + i) * 512]; h = s.x * h + s.y; }
;       }
;     } else {
;       const int b = (chunk - 256) >> 1, j = (chunk - 256) & 1;
;       if (d == 0) { if (j == 1) { const float2 s = S[(long)(256 + 2 * b) * 512]; h = s.y; } }
;       else        { if (j == 0) { const float2 s = S[(long)(256 + 2 * b + 1) * 512]; h = s.y; } }
;     }
;     sm_init[d * 64 + ch] = h;
	v_fma_f32 v149, v0, v149, v1
	v_fma_f32 v149, v2, v149, v3
	v_mov_b32_e32 v253, 1.0
	v_mov_b32_e32 v254, 0
	s_waitcnt vmcnt(0)
	v_cmp_lt_i32_e32 vcc, 0, v150
	s_nop 1
	v_cndmask_b32_e32 v4, 1.0, v4, vcc
	v_cndmask_b32_e32 v5, 0, v5, vcc
	v_fma_f32 v254, v4, v254, v5
	v_mul_f32_e32 v253, v253, v4
	v_cmp_lt_i32_e32 vcc, 1, v150
	s_nop 1
	v_cndmask_b32_e32 v6, 1.0, v6, vcc
	v_cndmask_b32_e32 v7, 0, v7, vcc
	v_fma_f32 v254, v6, v254, v7
	v_mul_f32_e32 v253, v253, v6
	v_cmp_lt_i32_e32 vcc, 2, v150
	s_nop 1
	v_cndmask_b32_e32 v8, 1.0, v8, vcc
	v_cndmask_b32_e32 v9, 0, v9, vcc
	v_fma_f32 v254, v8, v254, v9
	v_mul_f32_e32 v253, v253, v8
	v_cmp_lt_i32_e32 vcc, 3, v150
	s_nop 1
	v_cndmask_b32_e32 v10, 1.0, v10, vcc
	v_cndmask_b32_e32 v11, 0, v11, vcc
	v_fma_f32 v254, v10, v254, v11
	v_mul_f32_e32 v253, v253, v10
	v_cmp_lt_i32_e32 vcc, 4, v150
	s_nop 1
	v_cndmask_b32_e32 v12, 1.0, v12, vcc
	v_cndmask_b32_e32 v13, 0, v13, vcc
	v_fma_f32 v254, v12, v254, v13
	v_mul_f32_e32 v253, v253, v12
	v_cmp_lt_i32_e32 vcc, 5, v150
	s_nop 1
	v_cndmask_b32_e32 v14, 1.0, v14, vcc
	v_cndmask_b32_e32 v15, 0, v15, vcc
	v_fma_f32 v254, v14, v254, v15
	v_mul_f32_e32 v253, v253, v14
	v_cmp_lt_i32_e32 vcc, 6, v150
	s_nop 1
	v_cndmask_b32_e32 v16, 1.0, v16, vcc
	v_cndmask_b32_e32 v17, 0, v17, vcc
	v_fma_f32 v254, v16, v254, v17
	v_mul_f32_e32 v253, v253, v16
	v_cmp_lt_i32_e32 vcc, 7, v150
	s_nop 1
	v_cndmask_b32_e32 v18, 1.0, v18, vcc
	v_cndmask_b32_e32 v19, 0, v19, vcc
	v_fma_f32 v254, v18, v254, v19
	v_mul_f32_e32 v253, v253, v18
	v_cmp_lt_i32_e32 vcc, 8, v150
	s_nop 1
	v_cndmask_b32_e32 v20, 1.0, v20, vcc
	v_cndmask_b32_e32 v21, 0, v21, vcc
	v_fma_f32 v254, v20, v254, v21
	v_mul_f32_e32 v253, v253, v20
	v_cmp_lt_i32_e32 vcc, 9, v150
	s_nop 1
	v_cndmask_b32_e32 v22, 1.0, v22, vcc
	v_cndmask_b32_e32 v23, 0, v23, vcc
	v_fma_f32 v254, v22, v254, v23
	v_mul_f32_e32 v253, v253, v22
	v_cmp_lt_i32_e32 vcc, 10, v150
	s_nop 1
	v_cndmask_b32_e32 v24, 1.0, v24, vcc
	v_cndmask_b32_e32 v25, 0, v25, vcc
	v_fma_f32 v254, v24, v254, v25
	v_mul_f32_e32 v253, v253, v24
	v_cmp_lt_i32_e32 vcc, 11, v150
	s_nop 1
	v_cndmask_b32_e32 v26, 1.0, v26, vcc
	v_cndmask_b32_e32 v27, 0, v27, vcc
	v_fma_f32 v254, v26, v254, v27
	v_mul_f32_e32 v253, v253, v26
	v_cmp_lt_i32_e32 vcc, 12, v150
	s_nop 1
	v_cndmask_b32_e32 v28, 1.0, v28, vcc
	v_cndmask_b32_e32 v29, 0, v29, vcc
	v_fma_f32 v254, v28, v254, v29
	v_mul_f32_e32 v253, v253, v28
	v_cmp_lt_i32_e32 vcc, 13, v150
	s_nop 1
	v_cndmask_b32_e32 v30, 1.0, v30, vcc
	v_cndmask_b32_e32 v31, 0, v31, vcc
	v_fma_f32 v254, v30, v254, v31
	v_mul_f32_e32 v253, v253, v30
	v_cmp_lt_i32_e32 vcc, 14, v150
	s_nop 1
	v_cndmask_b32_e32 v32, 1.0, v32, vcc
	v_cndmask_b32_e32 v33, 0, v33, vcc
	v_fma_f32 v254, v32, v254, v33
	v_mul_f32_e32 v253, v253, v32
	v_cmp_lt_i32_e32 vcc, 15, v150
	s_nop 1
	v_cndmask_b32_e32 v34, 1.0, v34, vcc
	v_cndmask_b32_e32 v35, 0, v35, vcc
	v_fma_f32 v254, v34, v254, v35
	v_mul_f32_e32 v253, v253, v34
	v_mov_b32_e32 v138, v253
	v_mov_b32_e32 v139, v253
	s_nop 1
	v_permlane16_swap_b32_e32 v138, v139
	v_mov_b32_e32 v140, v138
	v_mov_b32_e32 v141, v139
	s_nop 1
	v_permlane32_swap_b32_e32 v138, v140
	v_permlane32_swap_b32_e32 v139, v141
	v_mov_b32_e32 v198, v254
	v_mov_b32_e32 v199, v254
	s_nop 1
	v_permlane16_swap_b32_e32 v198, v199
	v_mov_b32_e32 v200, v198
	v_mov_b32_e32 v201, v199
	s_nop 1
	v_permlane32_swap_b32_e32 v198, v200
	v_permlane32_swap_b32_e32 v199, v201
	v_fma_f32 v149, v138, v149, v198
	v_fma_f32 v149, v139, v149, v199
	v_fma_f32 v149, v140, v149, v200
	v_fma_f32 v149, v141, v149, v201
	s_branch .Lmy_lrub_lb1_done
.Lmy_lrub_lb1_ctx:
	s_sub_u32 s0, s71, 256
	s_and_b32 s1, s0, 1
	s_cmp_eq_u32 s1, 0
	s_cbranch_scc0 .Lmy_lrub_lb1_done
	s_and_b32 s0, s0, -2
	s_add_u32 s0, s0, 257
	s_lshl_b32 s0, s0, 12
	s_add_u32 s60, s4, s0
	s_addc_u32 s61, s5, 0
	global_load_dwordx2 v[0:1], v250, s[60:61]
	s_waitcnt vmcnt(0)
	v_mov_b32_e32 v149, v1
.Lmy_lrub_lb1_done:
	s_add_u32 s58, s69, 1
	s_cmp_lt_u32 s58, s70
	s_cbranch_scc0 .Lmy_lrub_nopf
	s_lshl_b32 s58, s58, 9
	s_add_u32 s58, s58, s68
	s_lshr_b32 s59, s58, 3
	s_cmp_lt_u32 s59, 256
	s_cselect_b32 s60, 63, 1
	s_and_b32 s57, s59, s60
	s_cmp_eq_u32 s57, 0
	s_cselect_b64 s[0:1], s[84:85], 0
	s_cmp_eq_u32 s57, s60
	s_cselect_b64 s[4:5], s[86:87], 0
	v_mov_b32_e32 v255, 0x1800
	v_cndmask_b32_e64 v150, 0, v255, s[0:1]
	v_lshlrev_b32_e32 v136, 1, v150
	v_add_u32_e32 v136, v134, v136
	v_add_u32_e32 v150, v134, v150
	v_cndmask_b32_e64 v151, 0, v255, s[4:5]
	v_sub_u32_e32 v151, v134, v151
	s_lshl_b32 s61, s59, 7
	s_mul_i32 s0, s61, 0xc00
	s_lshl_b32 s1, s56, 1
	s_add_u32 s0, s0, s1
	s_add_u32 s4, s10, s0
	s_addc_u32 s5, s11, 0
	s_sub_u32 s4, s4, 0x1800
	s_subb_u32 s5, s5, 0
	global_load_ushort v32, v136, s[4:5]
	s_add_u32 s4, s4, 0xc00
	s_addc_u32 s5, s5, 0
	global_load_ushort v33, v150, s[4:5]
	s_add_u32 s4, s4, 0xc00
	s_addc_u32 s5, s5, 0
	global_load_ushort v34, v134, s[4:5]
	s_add_u32 s4, s4, 0xc00
	s_addc_u32 s5, s5, 0
	global_load_ushort v35, v134, s[4:5]
	s_add_u32 s4, s4, 0xc00
	s_addc_u32 s5, s5, 0
	global_load_ushort v36, v134, s[4:5]
	s_add_u32 s4, s4, 0xc00
	s_addc_u32 s5, s5, 0
	global_load_ushort v37, v134, s[4:5]
	s_add_u32 s4, s4, 0xc00
	s_addc_u32 s5, s5, 0
	global_load_ushort v38, v134, s[4:5]
	s_add_u32 s4, s4, 0xc00
	s_addc_u32 s5, s5, 0
	global_load_ushort v39, v134, s[4:5]
	s_add_u32 s4, s4, 0xc00
	s_addc_u32 s5, s5, 0
	global_load_ushort v40, v134, s[4:5]
	s_add_u32 s4, s4, 0xc00
	s_addc_u32 s5, s5, 0
	global_load_ushort v41, v134, s[4:5]
	s_add_u32 s4, s4, 0xc00
	s_addc_u32 s5, s5, 0
	global_load_ushort v42, v134, s[4:5]
	s_add_u32 s4, s4, 0xc00
	s_addc_u32 s5, s5, 0
; __device__ __forceinline__ float bf2f(u16 h) { return __uint_as_float(((unsigned)h) << 16); }
; __device__ __forceinline__ void lru_tile(const Params& P, int chunk, int head, int pass, char* smem_raw) {
;     ...
;     const int r = row0 + q * 32;
;     float uv[35];
; #pragma unroll
;     for (int i = 0; i < 35; ++i) {
;       const int rr = r - 2 + i;
;       uv[i] = (rr >= seq_lo && rr < seq_hi) ? bf2f(zu[(long)rr * 1536]) : 0.f;
;     ...
;       for (int s = 0; s < 2; ++s) {
;         const bf16x8 af = *reinterpret_cast<const bf16x8*>(&sm_uc[(sb * 64 + wid * 16 + (lane & 15)) * LDSS + s * 32 + (lane >> 4) * 8]);
; #pragma unroll
;         for (int t = 0; t < 8; ++t) {
;           const bf16x8 bfr = *reinterpret_cast<const bf16x8*>(&sm_w[(t * 16 + (lane & 15)) * LDSS + s * 32 + (lane >> 4) * 8]);
;           acc[t] = __builtin_amdgcn_mfma_f32_16x16x32_bf16(af, bfr, acc[t], 0, 0, 0);
;         }
;       }
	global_load_ushort v43, v134, s[4:5]
	s_add_u32 s4, s4, 0xc00
	s_addc_u32 s5, s5, 0
	global_load_ushort v44, v134, s[4:5]
	s_add_u32 s4, s4, 0xc00
	s_addc_u32 s5, s5, 0
	global_load_ushort v45, v134, s[4:5]
	s_add_u32 s4, s4, 0xc00
	s_addc_u32 s5, s5, 0
	global_load_ushort v46, v134, s[4:5]
	s_add_u32 s4, s4, 0xc00
	s_addc_u32 s5, s5, 0
	global_load_ushort v47, v134, s[4:5]
	s_add_u32 s4, s4, 0xc00
	s_addc_u32 s5, s5, 0
	global_load_ushort v48, v134, s[4:5]
	s_add_u32 s4, s4, 0xc00
	s_addc_u32 s5, s5, 0
	global_load_ushort v49, v134, s[4:5]
	s_add_u32 s4, s4, 0xc00
	s_addc_u32 s5, s5, 0
	global_load_ushort v50, v134, s[4:5]
	s_add_u32 s4, s4, 0xc00
	s_addc_u32 s5, s5, 0
	global_load_ushort v51, v134, s[4:5]
	s_add_u32 s4, s4, 0xc00
	s_addc_u32 s5, s5, 0
	global_load_ushort v52, v134, s[4:5]
	s_add_u32 s4, s4, 0xc00
	s_addc_u32 s5, s5, 0
	global_load_ushort v53, v134, s[4:5]
	s_add_u32 s4, s4, 0xc00
	s_addc_u32 s5, s5, 0
	global_load_ushort v54, v134, s[4:5]
	s_add_u32 s4, s4, 0xc00
	s_addc_u32 s5, s5, 0
	global_load_ushort v55, v134, s[4:5]
	s_add_u32 s4, s4, 0xc00
	s_addc_u32 s5, s5, 0
	global_load_ushort v56, v134, s[4:5]
	s_add_u32 s4, s4, 0xc00
	s_addc_u32 s5, s5, 0
	global_load_ushort v57, v134, s[4:5]
	s_add_u32 s4, s4, 0xc00
	s_addc_u32 s5, s5, 0
	global_load_ushort v58, v134, s[4:5]
	s_add_u32 s4, s4, 0xc00
	s_addc_u32 s5, s5, 0
	global_load_ushort v59, v134, s[4:5]
	s_add_u32 s4, s4, 0xc00
	s_addc_u32 s5, s5, 0
	global_load_ushort v60, v134, s[4:5]
	s_add_u32 s4, s4, 0xc00
	s_addc_u32 s5, s5, 0
	global_load_ushort v61, v134, s[4:5]
	s_add_u32 s4, s4, 0xc00
	s_addc_u32 s5, s5, 0
	global_load_ushort v62, v134, s[4:5]
	s_add_u32 s4, s4, 0xc00
	s_addc_u32 s5, s5, 0
	global_load_ushort v63, v134, s[4:5]
	s_add_u32 s4, s4, 0xc00
	s_addc_u32 s5, s5, 0
	global_load_ushort v64, v134, s[4:5]
	s_add_u32 s4, s4, 0xc00
	s_addc_u32 s5, s5, 0
	global_load_ushort v66, v134, s[4:5]
	s_add_u32 s4, s4, 0xc00
	s_addc_u32 s5, s5, 0
	global_load_ushort v69, v151, s[4:5]
.Lmy_lrub_nopf:
	ds_read_b128 v[76:79], v131 offset:0
	ds_read_b128 v[80:83], v133 offset:0
	ds_read_b128 v[122:125], v131 offset:512
	ds_read_b128 v[126:129], v133 offset:512
	s_waitcnt lgkmcnt(3)
	v_mfma_f32_16x16x32_bf16 v[0:3], v[76:79], v[238:241], 0
	v_mfma_f32_16x16x32_bf16 v[90:93], v[76:79], v[246:249], 0
	ds_read_b128 v[76:79], v131 offset:1024
	s_waitcnt lgkmcnt(3)
	v_mfma_f32_16x16x32_bf16 v[0:3], v[80:83], v[242:245], v[0:3]
	v_mfma_f32_16x16x32_bf16 v[90:93], v[80:83], v[194:197], v[90:93]
	ds_read_b128 v[80:83], v133 offset:1024
	s_waitcnt lgkmcnt(3)
	v_mfma_f32_16x16x32_bf16 v[4:7], v[122:125], v[238:241], 0
	v_mfma_f32_16x16x32_bf16 v[94:97], v[122:125], v[246:249], 0
	ds_read_b128 v[122:125], v131 offset:1536
	s_waitcnt lgkmcnt(3)
	v_mfma_f32_16x16x32_bf16 v[4:7], v[126:129], v[242:245], v[4:7]
	v_mfma_f32_16x16x32_bf16 v[94:97], v[126:129], v[194:197], v[94:97]
	ds_read_b128 v[126:129], v133 offset:1536
	s_waitcnt lgkmcnt(3)
	v_mfma_f32_16x16x32_bf16 v[8:11], v[76:79], v[238:241], 0
	v_mfma_f32_16x16x32_bf16 v[98:101], v[76:79], v[246:249], 0
	ds_read_b128 v[76:79], v131 offset:2048
	s_waitcnt lgkmcnt(3)
	v_mfma_f32_16x16x32_bf16 v[8:11], v[80:83], v[242:245], v[8:11]
	v_mfma_f32_16x16x32_bf16 v[98:101], v[80:83], v[194:197], v[98:101]
	ds_read_b128 v[80:83], v133 offset:2048
	s_waitcnt lgkmcnt(3)
	v_mfma_f32_16x16x32_bf16 v[12:15], v[122:125], v[238:241], 0
	v_mfma_f32_16x16x32_bf16 v[102:105], v[122:125], v[246:249], 0
	ds_read_b128 v[122:125], v131 offset:2560
	s_waitcnt lgkmcnt(3)
	v_mfma_f32_16x16x32_bf16 v[12:15], v[126:129], v[242:245], v[12:15]
	v_mfma_f32_16x16x32_bf16 v[102:105], v[126:129], v[194:197], v[102:105]
	ds_read_b128 v[126:129], v133 offset:2560
	s_waitcnt lgkmcnt(3)
	v_mfma_f32_16x16x32_bf16 v[16:19], v[76:79], v[238:241], 0
	v_mfma_f32_16x16x32_bf16 v[106:109], v[76:79], v[246:249], 0
	ds_read_b128 v[76:79], v131 offset:3072
	s_waitcnt lgkmcnt(3)
	v_mfma_f32_16x16x32_bf16 v[16:19], v[80:83], v[242:245], v[16:19]
	v_mfma_f32_16x16x32_bf16 v[106:109], v[80:83], v[194:197], v[106:109]
	ds_read_b128 v[80:83], v133 offset:3072
	s_waitcnt lgkmcnt(3)
	v_mfma_f32_16x16x32_bf16 v[20:23], v[122:125], v[238:241], 0
	v_mfma_f32_16x16x32_bf16 v[110:113], v[122:125], v[246:249], 0
	ds_read_b128 v[122:125], v131 offset:3584
	s_waitcnt lgkmcnt(3)
	v_mfma_f32_16x16x32_bf16 v[20:23], v[126:129], v[242:245], v[20:23]
	v_mfma_f32_16x16x32_bf16 v[110:113], v[126:129], v[194:197], v[110:113]
	ds_read_b128 v[126:129], v133 offset:3584
	s_waitcnt lgkmcnt(3)
	v_mfma_f32_16x16x32_bf16 v[24:27], v[76:79], v[238:241], 0
	v_mfma_f32_16x16x32_bf16 v[114:117], v[76:79], v[246:249], 0
	s_waitcnt lgkmcnt(2)
	v_mfma_f32_16x16x32_bf16 v[24:27], v[80:83], v[242:245], v[24:27]
	v_mfma_f32_16x16x32_bf16 v[114:117], v[80:83], v[194:197], v[114:117]
	s_waitcnt lgkmcnt(1)
	v_mfma_f32_16x16x32_bf16 v[28:31], v[122:125], v[238:241], 0
	v_mfma_f32_16x16x32_bf16 v[118:121], v[122:125], v[246:249], 0
	s_waitcnt lgkmcnt(0)
; __device__ __forceinline__ void lru_tile(const Params& P, int chunk, int head, int pass, char* smem_raw) {
;     ...
;     for (int i = 0; i < 4; ++i) {
;       const int idx = tid + 256 * i, rowi = idx >> 3, kg = idx & 7;
;       *reinterpret_cast<uint4*>(&sm_w[rowi * LDSS + kg * 8]) = ldg16(P.wg + ((long)(d * 8 + head) * 128 + rowi) * 64 + kg * 8);
;     }
;     float ba[4], bi[4], c8[4];
; #pragma unroll
;     for (int tc = 0; tc < 4; ++tc) {
;       const int cidx = d * 512 + head * 64 + 16 * tc + (lane & 15);
;       ba[tc] = P.b_a[cidx] * -1.4426950408889634f; bi[tc] = P.b_i[cidx] * -1.4426950408889634f;
;       const float nl = -P.lam[cidx];
;       const float e_ = __expf(nl);
;       const float sp = (nl > 20.f) ? nl
;                      : (e_ < 0.03f ? e_ * (1.f - e_ * (0.5f - e_ * (0.33333334f - 0.25f * e_))) : __logf(1.f + e_));
;       c8[tc] = 8.f * 1.4426950408889634f * sp;
;     }
;     __syncthreads();
;     float cA = 1.f, cB = (pass == 2) ? sm_init[d * 64 + ch] : 0.f;
;     for (int sbi = 0; sbi < 2; ++sbi) {
;       const int sb = (d == 0) ? sbi : 1 - sbi;
;       f32x4 acc[8];
; #pragma unroll
;       for (int t = 0; t < 8; ++t) acc[t] = f32x4{0.f, 0.f, 0.f, 0.f};
; #pragma unroll
;       for (int s = 0; s < 2; ++s) {
;         const bf16x8 af = *reinterpret_cast<const bf16x8*>(&sm_uc[(sb * 64 + wid * 16 + (lane & 15)) * LDSS + s * 32 + (lane >> 4) * 8]);
; #pragma unroll
;         for (int t = 0; t < 8; ++t) {
;           const bf16x8 bfr = *reinterpret_cast<const bf16x8*>(&sm_w[(t * 16 + (lane & 15)) * LDSS + s * 32 + (lane >> 4) * 8]);
;           acc[t] = __builtin_amdgcn_mfma_f32_16x16x32_bf16(af, bfr, acc[t], 0, 0, 0);
;         }
;       }
; #pragma unroll
;       for (int tc = 0; tc < 4; ++tc)
; #pragma unroll
;         for (int reg = 0; reg < 4; ++reg) {
;           const int tl = wid * 16 + (lane >> 4) * 4 + reg;
;           const int c = 16 * tc + (lane & 15);
;           const float r = __builtin_amdgcn_rcpf(1.f + __builtin_amdgcn_exp2f(acc[tc][reg] + ba[tc]));
;           const float ii = __builtin_amdgcn_rcpf(1.f + __builtin_amdgcn_exp2f(acc[tc + 4][reg] + bi[tc]));
;           const float la = -c8[tc] * r;
;           const float a = __builtin_amdgcn_exp2f(la);
;           const float ucv = bf2f(sm_uc[(sb * 64 + tl) * LDSS + c]);
;           const float bt = __builtin_amdgcn_sqrtf(fmaxf(1.f - a * a, 0.f)) * (ii * ucv);
	v_mfma_f32_16x16x32_bf16 v[28:31], v[126:129], v[242:245], v[28:31]
	v_mfma_f32_16x16x32_bf16 v[118:121], v[126:129], v[194:197], v[118:121]
	s_lshl_b32 s0, s56, 8
	s_add_u32 s0, s0, 0x20000
	s_add_u32 s4, s20, s0
	s_addc_u32 s5, s21, 0
	global_load_dwordx4 v[238:241], v251, s[4:5]
	global_load_dwordx4 v[242:245], v251, s[4:5] offset:64
	s_add_u32 s4, s4, 0x2000
	s_addc_u32 s5, s5, 0
	global_load_dwordx4 v[246:249], v251, s[4:5]
	global_load_dwordx4 v[194:197], v251, s[4:5] offset:64
	s_nop 7
	s_nop 7
	v_add_f32_e32 v0, v0, v75
	v_add_f32_e32 v1, v1, v75
	v_add_f32_e32 v2, v2, v75
	v_add_f32_e32 v3, v3, v75
	v_add_f32_e32 v90, v90, v84
	v_add_f32_e32 v91, v91, v84
	v_add_f32_e32 v92, v92, v84
	v_add_f32_e32 v93, v93, v84
	v_exp_f32_e32 v0, v0
	v_exp_f32_e32 v1, v1
	v_exp_f32_e32 v2, v2
	v_exp_f32_e32 v3, v3
	v_exp_f32_e32 v90, v90
	v_exp_f32_e32 v91, v91
	v_exp_f32_e32 v92, v92
	v_exp_f32_e32 v93, v93
	v_add_f32_e32 v0, 1.0, v0
	v_add_f32_e32 v1, 1.0, v1
	v_add_f32_e32 v2, 1.0, v2
	v_add_f32_e32 v3, 1.0, v3
	v_add_f32_e32 v90, 1.0, v90
	v_add_f32_e32 v91, 1.0, v91
	v_add_f32_e32 v92, 1.0, v92
	v_add_f32_e32 v93, 1.0, v93
	v_rcp_f32_e32 v0, v0
	v_rcp_f32_e32 v1, v1
	v_rcp_f32_e32 v2, v2
	v_rcp_f32_e32 v3, v3
	v_rcp_f32_e32 v90, v90
	v_rcp_f32_e32 v91, v91
	v_rcp_f32_e32 v92, v92
	v_rcp_f32_e32 v93, v93
	v_mul_f32_e32 v0, v85, v0
	v_mul_f32_e32 v1, v85, v1
	v_mul_f32_e32 v2, v85, v2
	v_mul_f32_e32 v3, v85, v3
	v_mul_f32_e32 v90, v90, v162
	v_mul_f32_e32 v91, v91, v163
	v_mul_f32_e32 v92, v92, v164
	v_mul_f32_e32 v93, v93, v165
	v_exp_f32_e32 v0, v0
	v_exp_f32_e32 v1, v1
	v_exp_f32_e32 v2, v2
	v_exp_f32_e32 v3, v3
	s_nop 0
	v_fma_f32 v138, -v0, v0, 1.0
	v_fma_f32 v139, -v1, v1, 1.0
	v_fma_f32 v140, -v2, v2, 1.0
	v_fma_f32 v141, -v3, v3, 1.0
	v_max_f32_e32 v138, 0, v138
	v_max_f32_e32 v139, 0, v139
	v_max_f32_e32 v140, 0, v140
	v_max_f32_e32 v141, 0, v141
	v_sqrt_f32_e32 v138, v138
	v_sqrt_f32_e32 v139, v139
	v_sqrt_f32_e32 v140, v140
	v_sqrt_f32_e32 v141, v141
	s_nop 0
	v_mul_f32_e32 v90, v138, v90
	v_mul_f32_e32 v91, v139, v91
	v_mul_f32_e32 v92, v140, v92
	v_mul_f32_e32 v93, v141, v93
	v_add_f32_e32 v4, v4, v75
	v_add_f32_e32 v5, v5, v75
	v_add_f32_e32 v6, v6, v75
	v_add_f32_e32 v7, v7, v75
	v_add_f32_e32 v94, v94, v84
	v_add_f32_e32 v95, v95, v84
	v_add_f32_e32 v96, v96, v84
	v_add_f32_e32 v97, v97, v84
	v_exp_f32_e32 v4, v4
	v_exp_f32_e32 v5, v5
	v_exp_f32_e32 v6, v6
	v_exp_f32_e32 v7, v7
	v_exp_f32_e32 v94, v94
	v_exp_f32_e32 v95, v95
	v_exp_f32_e32 v96, v96
	v_exp_f32_e32 v97, v97
	v_add_f32_e32 v4, 1.0, v4
	v_add_f32_e32 v5, 1.0, v5
	v_add_f32_e32 v6, 1.0, v6
	v_add_f32_e32 v7, 1.0, v7
	v_add_f32_e32 v94, 1.0, v94
	v_add_f32_e32 v95, 1.0, v95
	v_add_f32_e32 v96, 1.0, v96
	v_add_f32_e32 v97, 1.0, v97
	v_rcp_f32_e32 v4, v4
	v_rcp_f32_e32 v5, v5
	v_rcp_f32_e32 v6, v6
	v_rcp_f32_e32 v7, v7
	v_rcp_f32_e32 v94, v94
	v_rcp_f32_e32 v95, v95
	v_rcp_f32_e32 v96, v96
	v_rcp_f32_e32 v97, v97
	v_mul_f32_e32 v4, v85, v4
	v_mul_f32_e32 v5, v85, v5
	v_mul_f32_e32 v6, v85, v6
	v_mul_f32_e32 v7, v85, v7
	v_mul_f32_e32 v94, v94, v166
	v_mul_f32_e32 v95, v95, v167
	v_mul_f32_e32 v96, v96, v168
	v_mul_f32_e32 v97, v97, v169
	v_exp_f32_e32 v4, v4
	v_exp_f32_e32 v5, v5
	v_exp_f32_e32 v6, v6
	v_exp_f32_e32 v7, v7
	s_nop 0
	v_fma_f32 v138, -v4, v4, 1.0
	v_fma_f32 v139, -v5, v5, 1.0
	v_fma_f32 v140, -v6, v6, 1.0
	v_fma_f32 v141, -v7, v7, 1.0
	v_max_f32_e32 v138, 0, v138
	v_max_f32_e32 v139, 0, v139
	v_max_f32_e32 v140, 0, v140
	v_max_f32_e32 v141, 0, v141
	v_sqrt_f32_e32 v138, v138
	v_sqrt_f32_e32 v139, v139
	v_sqrt_f32_e32 v140, v140
	v_sqrt_f32_e32 v141, v141
	s_nop 0
	v_mul_f32_e32 v94, v138, v94
	v_mul_f32_e32 v95, v139, v95
	v_mul_f32_e32 v96, v140, v96
	v_mul_f32_e32 v97, v141, v97
	v_add_f32_e32 v8, v8, v75
	v_add_f32_e32 v9, v9, v75
	v_add_f32_e32 v10, v10, v75
	v_add_f32_e32 v11, v11, v75
	v_add_f32_e32 v98, v98, v84
	v_add_f32_e32 v99, v99, v84
	v_add_f32_e32 v100, v100, v84
	v_add_f32_e32 v101, v101, v84
	v_exp_f32_e32 v8, v8
	v_exp_f32_e32 v9, v9
	v_exp_f32_e32 v10, v10
	v_exp_f32_e32 v11, v11
	v_exp_f32_e32 v98, v98
	v_exp_f32_e32 v99, v99
	v_exp_f32_e32 v100, v100
	v_exp_f32_e32 v101, v101
	v_add_f32_e32 v8, 1.0, v8
	v_add_f32_e32 v9, 1.0, v9
	v_add_f32_e32 v10, 1.0, v10
	v_add_f32_e32 v11, 1.0, v11
	v_add_f32_e32 v98, 1.0, v98
	v_add_f32_e32 v99, 1.0, v99
	v_add_f32_e32 v100, 1.0, v100
	v_add_f32_e32 v101, 1.0, v101
	v_rcp_f32_e32 v8, v8
	v_rcp_f32_e32 v9, v9
	v_rcp_f32_e32 v10, v10
	v_rcp_f32_e32 v11, v11
	v_rcp_f32_e32 v98, v98
	v_rcp_f32_e32 v99, v99
	v_rcp_f32_e32 v100, v100
	v_rcp_f32_e32 v101, v101
	v_mul_f32_e32 v8, v85, v8
	v_mul_f32_e32 v9, v85, v9
	v_mul_f32_e32 v10, v85, v10
	v_mul_f32_e32 v11, v85, v11
	v_mul_f32_e32 v98, v98, v170
	v_mul_f32_e32 v99, v99, v171
	v_mul_f32_e32 v100, v100, v172
	v_mul_f32_e32 v101, v101, v173
	v_exp_f32_e32 v8, v8
	v_exp_f32_e32 v9, v9
	v_exp_f32_e32 v10, v10
	v_exp_f32_e32 v11, v11
	s_nop 0
	v_fma_f32 v138, -v8, v8, 1.0
	v_fma_f32 v139, -v9, v9, 1.0
	v_fma_f32 v140, -v10, v10, 1.0
	v_fma_f32 v141, -v11, v11, 1.0
	v_max_f32_e32 v138, 0, v138
	v_max_f32_e32 v139, 0, v139
	v_max_f32_e32 v140, 0, v140
	v_max_f32_e32 v141, 0, v141
	v_sqrt_f32_e32 v138, v138
	v_sqrt_f32_e32 v139, v139
	v_sqrt_f32_e32 v140, v140
	v_sqrt_f32_e32 v141, v141
	s_nop 0
	v_mul_f32_e32 v98, v138, v98
	v_mul_f32_e32 v99, v139, v99
	v_mul_f32_e32 v100, v140, v100
	v_mul_f32_e32 v101, v141, v101
	v_add_f32_e32 v12, v12, v75
	v_add_f32_e32 v13, v13, v75
	v_add_f32_e32 v14, v14, v75
	v_add_f32_e32 v15, v15, v75
	v_add_f32_e32 v102, v102, v84
	v_add_f32_e32 v103, v103, v84
	v_add_f32_e32 v104, v104, v84
	v_add_f32_e32 v105, v105, v84
; __device__ __forceinline__ float bf2f(u16 h) { return __uint_as_float(((unsigned)h) << 16); }
; __device__ __forceinline__ void lru_tile(const Params& P, int chunk, int head, int pass, char* smem_raw) {
;     ...
;           const float r = __builtin_amdgcn_rcpf(1.f + __builtin_amdgcn_exp2f(acc[tc][reg] + ba[tc]));
;           const float ii = __builtin_amdgcn_rcpf(1.f + __builtin_amdgcn_exp2f(acc[tc + 4][reg] + bi[tc]));
;           const float la = -c8[tc] * r;
;           const float a = __builtin_amdgcn_exp2f(la);
;           const float ucv = bf2f(sm_uc[(sb * 64 + tl) * LDSS + c]);
;           const float bt = __builtin_amdgcn_sqrtf(fmaxf(1.f - a * a, 0.f)) * (ii * ucv);
	v_exp_f32_e32 v12, v12
	v_exp_f32_e32 v13, v13
	v_exp_f32_e32 v14, v14
	v_exp_f32_e32 v15, v15
	v_exp_f32_e32 v102, v102
	v_exp_f32_e32 v103, v103
	v_exp_f32_e32 v104, v104
	v_exp_f32_e32 v105, v105
	v_add_f32_e32 v12, 1.0, v12
	v_add_f32_e32 v13, 1.0, v13
	v_add_f32_e32 v14, 1.0, v14
	v_add_f32_e32 v15, 1.0, v15
	v_add_f32_e32 v102, 1.0, v102
	v_add_f32_e32 v103, 1.0, v103
	v_add_f32_e32 v104, 1.0, v104
	v_add_f32_e32 v105, 1.0, v105
	v_rcp_f32_e32 v12, v12
	v_rcp_f32_e32 v13, v13
	v_rcp_f32_e32 v14, v14
	v_rcp_f32_e32 v15, v15
	v_rcp_f32_e32 v102, v102
	v_rcp_f32_e32 v103, v103
	v_rcp_f32_e32 v104, v104
	v_rcp_f32_e32 v105, v105
	v_mul_f32_e32 v12, v85, v12
	v_mul_f32_e32 v13, v85, v13
	v_mul_f32_e32 v14, v85, v14
	v_mul_f32_e32 v15, v85, v15
	v_mul_f32_e32 v102, v102, v174
	v_mul_f32_e32 v103, v103, v175
	v_mul_f32_e32 v104, v104, v176
	v_mul_f32_e32 v105, v105, v177
	v_exp_f32_e32 v12, v12
	v_exp_f32_e32 v13, v13
	v_exp_f32_e32 v14, v14
	v_exp_f32_e32 v15, v15
	s_nop 0
	v_fma_f32 v138, -v12, v12, 1.0
	v_fma_f32 v139, -v13, v13, 1.0
	v_fma_f32 v140, -v14, v14, 1.0
	v_fma_f32 v141, -v15, v15, 1.0
	v_max_f32_e32 v138, 0, v138
	v_max_f32_e32 v139, 0, v139
	v_max_f32_e32 v140, 0, v140
	v_max_f32_e32 v141, 0, v141
	v_sqrt_f32_e32 v138, v138
	v_sqrt_f32_e32 v139, v139
	v_sqrt_f32_e32 v140, v140
	v_sqrt_f32_e32 v141, v141
	s_nop 0
	v_mul_f32_e32 v102, v138, v102
	v_mul_f32_e32 v103, v139, v103
	v_mul_f32_e32 v104, v140, v104
	v_mul_f32_e32 v105, v141, v105
	v_add_f32_e32 v16, v16, v75
	v_add_f32_e32 v17, v17, v75
	v_add_f32_e32 v18, v18, v75
	v_add_f32_e32 v19, v19, v75
	v_add_f32_e32 v106, v106, v84
	v_add_f32_e32 v107, v107, v84
	v_add_f32_e32 v108, v108, v84
	v_add_f32_e32 v109, v109, v84
	v_exp_f32_e32 v16, v16
	v_exp_f32_e32 v17, v17
	v_exp_f32_e32 v18, v18
	v_exp_f32_e32 v19, v19
	v_exp_f32_e32 v106, v106
	v_exp_f32_e32 v107, v107
	v_exp_f32_e32 v108, v108
	v_exp_f32_e32 v109, v109
	v_add_f32_e32 v16, 1.0, v16
	v_add_f32_e32 v17, 1.0, v17
	v_add_f32_e32 v18, 1.0, v18
	v_add_f32_e32 v19, 1.0, v19
	v_add_f32_e32 v106, 1.0, v106
	v_add_f32_e32 v107, 1.0, v107
	v_add_f32_e32 v108, 1.0, v108
	v_add_f32_e32 v109, 1.0, v109
	v_rcp_f32_e32 v16, v16
	v_rcp_f32_e32 v17, v17
	v_rcp_f32_e32 v18, v18
	v_rcp_f32_e32 v19, v19
	v_rcp_f32_e32 v106, v106
	v_rcp_f32_e32 v107, v107
	v_rcp_f32_e32 v108, v108
	v_rcp_f32_e32 v109, v109
	v_mul_f32_e32 v16, v85, v16
	v_mul_f32_e32 v17, v85, v17
	v_mul_f32_e32 v18, v85, v18
	v_mul_f32_e32 v19, v85, v19
	v_mul_f32_e32 v106, v106, v178
	v_mul_f32_e32 v107, v107, v179
	v_mul_f32_e32 v108, v108, v180
	v_mul_f32_e32 v109, v109, v181
	v_exp_f32_e32 v16, v16
	v_exp_f32_e32 v17, v17
	v_exp_f32_e32 v18, v18
	v_exp_f32_e32 v19, v19
	s_nop 0
	v_fma_f32 v138, -v16, v16, 1.0
	v_fma_f32 v139, -v17, v17, 1.0
	v_fma_f32 v140, -v18, v18, 1.0
	v_fma_f32 v141, -v19, v19, 1.0
	v_max_f32_e32 v138, 0, v138
	v_max_f32_e32 v139, 0, v139
	v_max_f32_e32 v140, 0, v140
	v_max_f32_e32 v141, 0, v141
	v_sqrt_f32_e32 v138, v138
	v_sqrt_f32_e32 v139, v139
	v_sqrt_f32_e32 v140, v140
	v_sqrt_f32_e32 v141, v141
	s_nop 0
	v_mul_f32_e32 v106, v138, v106
	v_mul_f32_e32 v107, v139, v107
	v_mul_f32_e32 v108, v140, v108
	v_mul_f32_e32 v109, v141, v109
	v_add_f32_e32 v20, v20, v75
	v_add_f32_e32 v21, v21, v75
	v_add_f32_e32 v22, v22, v75
	v_add_f32_e32 v23, v23, v75
	v_add_f32_e32 v110, v110, v84
	v_add_f32_e32 v111, v111, v84
	v_add_f32_e32 v112, v112, v84
	v_add_f32_e32 v113, v113, v84
	v_exp_f32_e32 v20, v20
	v_exp_f32_e32 v21, v21
	v_exp_f32_e32 v22, v22
	v_exp_f32_e32 v23, v23
	v_exp_f32_e32 v110, v110
	v_exp_f32_e32 v111, v111
	v_exp_f32_e32 v112, v112
	v_exp_f32_e32 v113, v113
	v_add_f32_e32 v20, 1.0, v20
	v_add_f32_e32 v21, 1.0, v21
	v_add_f32_e32 v22, 1.0, v22
	v_add_f32_e32 v23, 1.0, v23
	v_add_f32_e32 v110, 1.0, v110
	v_add_f32_e32 v111, 1.0, v111
	v_add_f32_e32 v112, 1.0, v112
	v_add_f32_e32 v113, 1.0, v113
	v_rcp_f32_e32 v20, v20
	v_rcp_f32_e32 v21, v21
	v_rcp_f32_e32 v22, v22
	v_rcp_f32_e32 v23, v23
	v_rcp_f32_e32 v110, v110
	v_rcp_f32_e32 v111, v111
	v_rcp_f32_e32 v112, v112
	v_rcp_f32_e32 v113, v113
	v_mul_f32_e32 v20, v85, v20
	v_mul_f32_e32 v21, v85, v21
	v_mul_f32_e32 v22, v85, v22
	v_mul_f32_e32 v23, v85, v23
	v_mul_f32_e32 v110, v110, v182
	v_mul_f32_e32 v111, v111, v183
	v_mul_f32_e32 v112, v112, v184
	v_mul_f32_e32 v113, v113, v185
	v_exp_f32_e32 v20, v20
	v_exp_f32_e32 v21, v21
	v_exp_f32_e32 v22, v22
	v_exp_f32_e32 v23, v23
	s_nop 0
	v_fma_f32 v138, -v20, v20, 1.0
	v_fma_f32 v139, -v21, v21, 1.0
	v_fma_f32 v140, -v22, v22, 1.0
	v_fma_f32 v141, -v23, v23, 1.0
	v_max_f32_e32 v138, 0, v138
	v_max_f32_e32 v139, 0, v139
	v_max_f32_e32 v140, 0, v140
	v_max_f32_e32 v141, 0, v141
	v_sqrt_f32_e32 v138, v138
	v_sqrt_f32_e32 v139, v139
	v_sqrt_f32_e32 v140, v140
	v_sqrt_f32_e32 v141, v141
	s_nop 0
	v_mul_f32_e32 v110, v138, v110
	v_mul_f32_e32 v111, v139, v111
	v_mul_f32_e32 v112, v140, v112
	v_mul_f32_e32 v113, v141, v113
	v_add_f32_e32 v24, v24, v75
	v_add_f32_e32 v25, v25, v75
	v_add_f32_e32 v26, v26, v75
	v_add_f32_e32 v27, v27, v75
	v_add_f32_e32 v114, v114, v84
	v_add_f32_e32 v115, v115, v84
	v_add_f32_e32 v116, v116, v84
	v_add_f32_e32 v117, v117, v84
	v_exp_f32_e32 v24, v24
	v_exp_f32_e32 v25, v25
	v_exp_f32_e32 v26, v26
	v_exp_f32_e32 v27, v27
	v_exp_f32_e32 v114, v114
	v_exp_f32_e32 v115, v115
	v_exp_f32_e32 v116, v116
	v_exp_f32_e32 v117, v117
	v_add_f32_e32 v24, 1.0, v24
	v_add_f32_e32 v25, 1.0, v25
	v_add_f32_e32 v26, 1.0, v26
	v_add_f32_e32 v27, 1.0, v27
	v_add_f32_e32 v114, 1.0, v114
	v_add_f32_e32 v115, 1.0, v115
	v_add_f32_e32 v116, 1.0, v116
	v_add_f32_e32 v117, 1.0, v117
	v_rcp_f32_e32 v24, v24
	v_rcp_f32_e32 v25, v25
; __device__ __forceinline__ float bf2f(u16 h) { return __uint_as_float(((unsigned)h) << 16); }
; __device__ __forceinline__ void lru_tile(const Params& P, int chunk, int head, int pass, char* smem_raw) {
;     ...
;           const float r = __builtin_amdgcn_rcpf(1.f + __builtin_amdgcn_exp2f(acc[tc][reg] + ba[tc]));
;           const float ii = __builtin_amdgcn_rcpf(1.f + __builtin_amdgcn_exp2f(acc[tc + 4][reg] + bi[tc]));
;           const float la = -c8[tc] * r;
;           const float a = __builtin_amdgcn_exp2f(la);
;           const float ucv = bf2f(sm_uc[(sb * 64 + tl) * LDSS + c]);
;           const float bt = __builtin_amdgcn_sqrtf(fmaxf(1.f - a * a, 0.f)) * (ii * ucv);
;           sm_a[tl * 64 + c] = a;
;           sm_b[tl * 64 + c] = bt;
;         }
;       __syncthreads();
;       const int pos = (d == 0) ? q : 3 - q;
;       {
;         float Pp = 1.f, H = 0.f;
; #pragma unroll 4
;         for (int i = 0; i < 16; ++i) {
;           const int tl = (d == 0) ? (q * 16 + i) : (q * 16 + 15 - i);
;           const float a = sm_a[tl * 64 + ch], b = sm_b[tl * 64 + ch];
;           H = a * H + b; Pp *= a;
;         }
;         sm_ph[pos * 64 + ch] = make_float2(Pp, H);
;       }
;       __syncthreads();
;       const float2 p0 = sm_ph[ch], p1 = sm_ph[64 + ch], p2 = sm_ph[128 + ch], p3 = sm_ph[192 + ch];
;       if (pass == 2) {
;         float hin = cB;
;         if (pos > 0) hin = p0.x * hin + p0.y;
;         if (pos > 1) hin = p1.x * hin + p1.y;
;         if (pos > 2) hin = p2.x * hin + p2.y;
;         float h = hin;
;         float hfp[16], gp[16];
;         if (d == 1) {
; #pragma unroll
;           for (int i = 0; i < 16; ++i) {
;             const long rowp = row0 + sb * 64 + q * 16 + 15 - i;
;             hfp[i] = hfbuf[rowp * 512 + gch];
;             gp[i] = bf2f(P.zq[rowp * 1536 + 512 + gch]);
;           }
;         }
; #pragma unroll
;         for (int i = 0; i < 16; ++i) {
;           const int tl = (d == 0) ? (q * 16 + i) : (q * 16 + 15 - i);
;           const float a = sm_a[tl * 64 + ch], b = sm_b[tl * 64 + ch];
;           h = a * h + b;
;           const long row = row0 + sb * 64 + tl;
;           if (d == 0) {
;             hfw[row * 512 + gch] = h;
	v_rcp_f32_e32 v26, v26
	v_rcp_f32_e32 v27, v27
	v_rcp_f32_e32 v114, v114
	v_rcp_f32_e32 v115, v115
	v_rcp_f32_e32 v116, v116
	v_rcp_f32_e32 v117, v117
	v_mul_f32_e32 v24, v85, v24
	v_mul_f32_e32 v25, v85, v25
	v_mul_f32_e32 v26, v85, v26
	v_mul_f32_e32 v27, v85, v27
	v_mul_f32_e32 v114, v114, v186
	v_mul_f32_e32 v115, v115, v187
	v_mul_f32_e32 v116, v116, v188
	v_mul_f32_e32 v117, v117, v189
	v_exp_f32_e32 v24, v24
	v_exp_f32_e32 v25, v25
	v_exp_f32_e32 v26, v26
	v_exp_f32_e32 v27, v27
	s_nop 0
	v_fma_f32 v138, -v24, v24, 1.0
	v_fma_f32 v139, -v25, v25, 1.0
	v_fma_f32 v140, -v26, v26, 1.0
	v_fma_f32 v141, -v27, v27, 1.0
	v_max_f32_e32 v138, 0, v138
	v_max_f32_e32 v139, 0, v139
	v_max_f32_e32 v140, 0, v140
	v_max_f32_e32 v141, 0, v141
	v_sqrt_f32_e32 v138, v138
	v_sqrt_f32_e32 v139, v139
	v_sqrt_f32_e32 v140, v140
	v_sqrt_f32_e32 v141, v141
	s_nop 0
	v_mul_f32_e32 v114, v138, v114
	v_mul_f32_e32 v115, v139, v115
	v_mul_f32_e32 v116, v140, v116
	v_mul_f32_e32 v117, v141, v117
	v_add_f32_e32 v28, v28, v75
	v_add_f32_e32 v29, v29, v75
	v_add_f32_e32 v30, v30, v75
	v_add_f32_e32 v31, v31, v75
	v_add_f32_e32 v118, v118, v84
	v_add_f32_e32 v119, v119, v84
	v_add_f32_e32 v120, v120, v84
	v_add_f32_e32 v121, v121, v84
	v_exp_f32_e32 v28, v28
	v_exp_f32_e32 v29, v29
	v_exp_f32_e32 v30, v30
	v_exp_f32_e32 v31, v31
	v_exp_f32_e32 v118, v118
	v_exp_f32_e32 v119, v119
	v_exp_f32_e32 v120, v120
	v_exp_f32_e32 v121, v121
	v_add_f32_e32 v28, 1.0, v28
	v_add_f32_e32 v29, 1.0, v29
	v_add_f32_e32 v30, 1.0, v30
	v_add_f32_e32 v31, 1.0, v31
	v_add_f32_e32 v118, 1.0, v118
	v_add_f32_e32 v119, 1.0, v119
	v_add_f32_e32 v120, 1.0, v120
	v_add_f32_e32 v121, 1.0, v121
	v_rcp_f32_e32 v28, v28
	v_rcp_f32_e32 v29, v29
	v_rcp_f32_e32 v30, v30
	v_rcp_f32_e32 v31, v31
	v_rcp_f32_e32 v118, v118
	v_rcp_f32_e32 v119, v119
	v_rcp_f32_e32 v120, v120
	v_rcp_f32_e32 v121, v121
	v_mul_f32_e32 v28, v85, v28
	v_mul_f32_e32 v29, v85, v29
	v_mul_f32_e32 v30, v85, v30
	v_mul_f32_e32 v31, v85, v31
	v_mul_f32_e32 v118, v118, v190
	v_mul_f32_e32 v119, v119, v191
	v_mul_f32_e32 v120, v120, v192
	v_mul_f32_e32 v121, v121, v193
	v_exp_f32_e32 v28, v28
	v_exp_f32_e32 v29, v29
	v_exp_f32_e32 v30, v30
	v_exp_f32_e32 v31, v31
	s_nop 0
	v_fma_f32 v138, -v28, v28, 1.0
	v_fma_f32 v139, -v29, v29, 1.0
	v_fma_f32 v140, -v30, v30, 1.0
	v_fma_f32 v141, -v31, v31, 1.0
	v_max_f32_e32 v138, 0, v138
	v_max_f32_e32 v139, 0, v139
	v_max_f32_e32 v140, 0, v140
	v_max_f32_e32 v141, 0, v141
	v_sqrt_f32_e32 v138, v138
	v_sqrt_f32_e32 v139, v139
	v_sqrt_f32_e32 v140, v140
	v_sqrt_f32_e32 v141, v141
	s_nop 0
	v_mul_f32_e32 v118, v138, v118
	v_mul_f32_e32 v119, v139, v119
	v_mul_f32_e32 v120, v140, v120
	v_mul_f32_e32 v121, v141, v121
	v_mov_b32_e32 v253, v0
	v_mov_b32_e32 v254, v90
	v_fma_f32 v254, v1, v254, v91
	v_mul_f32_e32 v253, v253, v1
	v_fma_f32 v254, v2, v254, v92
	v_mul_f32_e32 v253, v253, v2
	v_fma_f32 v254, v3, v254, v93
	v_mul_f32_e32 v253, v253, v3
	v_fma_f32 v254, v4, v254, v94
	v_mul_f32_e32 v253, v253, v4
	v_fma_f32 v254, v5, v254, v95
	v_mul_f32_e32 v253, v253, v5
	v_fma_f32 v254, v6, v254, v96
	v_mul_f32_e32 v253, v253, v6
	v_fma_f32 v254, v7, v254, v97
	v_mul_f32_e32 v253, v253, v7
	v_fma_f32 v254, v8, v254, v98
	v_mul_f32_e32 v253, v253, v8
	v_fma_f32 v254, v9, v254, v99
	v_mul_f32_e32 v253, v253, v9
	v_fma_f32 v254, v10, v254, v100
	v_mul_f32_e32 v253, v253, v10
	v_fma_f32 v254, v11, v254, v101
	v_mul_f32_e32 v253, v253, v11
	v_fma_f32 v254, v12, v254, v102
	v_mul_f32_e32 v253, v253, v12
	v_fma_f32 v254, v13, v254, v103
	v_mul_f32_e32 v253, v253, v13
	v_fma_f32 v254, v14, v254, v104
	v_mul_f32_e32 v253, v253, v14
	v_fma_f32 v254, v15, v254, v105
	v_mul_f32_e32 v253, v253, v15
	v_fma_f32 v254, v16, v254, v106
	v_mul_f32_e32 v253, v253, v16
	v_fma_f32 v254, v17, v254, v107
	v_mul_f32_e32 v253, v253, v17
	v_fma_f32 v254, v18, v254, v108
	v_mul_f32_e32 v253, v253, v18
	v_fma_f32 v254, v19, v254, v109
	v_mul_f32_e32 v253, v253, v19
	v_fma_f32 v254, v20, v254, v110
	v_mul_f32_e32 v253, v253, v20
	v_fma_f32 v254, v21, v254, v111
	v_mul_f32_e32 v253, v253, v21
	v_fma_f32 v254, v22, v254, v112
	v_mul_f32_e32 v253, v253, v22
	v_fma_f32 v254, v23, v254, v113
	v_mul_f32_e32 v253, v253, v23
	v_fma_f32 v254, v24, v254, v114
	v_mul_f32_e32 v253, v253, v24
	v_fma_f32 v254, v25, v254, v115
	v_mul_f32_e32 v253, v253, v25
	v_fma_f32 v254, v26, v254, v116
	v_mul_f32_e32 v253, v253, v26
	v_fma_f32 v254, v27, v254, v117
	v_mul_f32_e32 v253, v253, v27
	v_fma_f32 v254, v28, v254, v118
	v_mul_f32_e32 v253, v253, v28
	v_fma_f32 v254, v29, v254, v119
	v_mul_f32_e32 v253, v253, v29
	v_fma_f32 v254, v30, v254, v120
	v_mul_f32_e32 v253, v253, v30
	v_fma_f32 v254, v31, v254, v121
	v_mul_f32_e32 v253, v253, v31
	v_mov_b32_e32 v138, v253
	v_mov_b32_e32 v139, v253
	s_nop 1
	v_permlane16_swap_b32_e32 v138, v139
	v_mov_b32_e32 v140, v138
	v_mov_b32_e32 v141, v139
	s_nop 1
	v_permlane32_swap_b32_e32 v138, v140
	v_permlane32_swap_b32_e32 v139, v141
	v_mov_b32_e32 v198, v254
	v_mov_b32_e32 v199, v254
	s_nop 1
	v_permlane16_swap_b32_e32 v198, v199
	v_mov_b32_e32 v200, v198
	v_mov_b32_e32 v201, v199
	s_nop 1
	v_permlane32_swap_b32_e32 v198, v200
	v_permlane32_swap_b32_e32 v199, v201
	v_mov_b32_e32 v136, v148
	v_fma_f32 v150, v138, v136, v198
	v_fma_f32 v151, v139, v150, v199
	v_fma_f32 v202, v140, v151, v200
	v_mov_b32_e32 v254, v136
	v_cndmask_b32_e64 v254, v254, v150, s[72:73]
	v_cndmask_b32_e64 v254, v254, v151, s[74:75]
	v_cndmask_b32_e64 v254, v254, v202, s[76:77]
	v_fma_f32 v205, v0, v254, v90
	v_fma_f32 v206, v1, v205, v91
	v_fma_f32 v207, v2, v206, v92
	v_fma_f32 v208, v3, v207, v93
	v_fma_f32 v209, v4, v208, v94
	v_fma_f32 v210, v5, v209, v95
	v_fma_f32 v211, v6, v210, v96
	v_fma_f32 v212, v7, v211, v97
	v_fma_f32 v213, v8, v212, v98
	v_fma_f32 v214, v9, v213, v99
	v_fma_f32 v215, v10, v214, v100
	v_fma_f32 v216, v11, v215, v101
	v_fma_f32 v217, v12, v216, v102
	v_fma_f32 v218, v13, v217, v103
	v_fma_f32 v219, v14, v218, v104
	v_fma_f32 v220, v15, v219, v105
	v_fma_f32 v221, v16, v220, v106
	v_fma_f32 v222, v17, v221, v107
	v_fma_f32 v223, v18, v222, v108
	v_fma_f32 v224, v19, v223, v109
	v_fma_f32 v225, v20, v224, v110
	v_fma_f32 v226, v21, v225, v111
	v_fma_f32 v227, v22, v226, v112
	v_fma_f32 v228, v23, v227, v113
	v_fma_f32 v229, v24, v228, v114
	v_fma_f32 v230, v25, v229, v115
	v_fma_f32 v231, v26, v230, v116
	v_fma_f32 v232, v27, v231, v117
	v_fma_f32 v233, v28, v232, v118
	v_fma_f32 v234, v29, v233, v119
	v_fma_f32 v235, v30, v234, v120
	v_fma_f32 v236, v31, v235, v121
	ds_read_b128 v[76:79], v131 offset:0
	ds_read_b128 v[80:83], v133 offset:0
	ds_read_b128 v[122:125], v131 offset:512
	ds_read_b128 v[126:129], v133 offset:512
	s_waitcnt vmcnt(0)
; __device__ __forceinline__ float bf2f(u16 h) { return __uint_as_float(((unsigned)h) << 16); }
; __device__ __forceinline__ void lru_tile(const Params& P, int chunk, int head, int pass, char* smem_raw) {
;     ...
;       for (int s = 0; s < 2; ++s) {
;         const bf16x8 af = *reinterpret_cast<const bf16x8*>(&sm_uc[(sb * 64 + wid * 16 + (lane & 15)) * LDSS + s * 32 + (lane >> 4) * 8]);
; #pragma unroll
;         for (int t = 0; t < 8; ++t) {
;           const bf16x8 bfr = *reinterpret_cast<const bf16x8*>(&sm_w[(t * 16 + (lane & 15)) * LDSS + s * 32 + (lane >> 4) * 8]);
;           acc[t] = __builtin_amdgcn_mfma_f32_16x16x32_bf16(af, bfr, acc[t], 0, 0, 0);
;         }
;       }
; #pragma unroll
;       for (int tc = 0; tc < 4; ++tc)
; #pragma unroll
;         for (int reg = 0; reg < 4; ++reg) {
;           const int tl = wid * 16 + (lane >> 4) * 4 + reg;
;           const int c = 16 * tc + (lane & 15);
;           const float r = __builtin_amdgcn_rcpf(1.f + __builtin_amdgcn_exp2f(acc[tc][reg] + ba[tc]));
;           const float ii = __builtin_amdgcn_rcpf(1.f + __builtin_amdgcn_exp2f(acc[tc + 4][reg] + bi[tc]));
;           const float la = -c8[tc] * r;
;           const float a = __builtin_amdgcn_exp2f(la);
;           const float ucv = bf2f(sm_uc[(sb * 64 + tl) * LDSS + c]);
;           const float bt = __builtin_amdgcn_sqrtf(fmaxf(1.f - a * a, 0.f)) * (ii * ucv);
	s_waitcnt lgkmcnt(3)
	v_mfma_f32_16x16x32_bf16 v[0:3], v[76:79], v[238:241], 0
	v_mfma_f32_16x16x32_bf16 v[90:93], v[76:79], v[246:249], 0
	ds_read_b128 v[76:79], v131 offset:1024
	s_waitcnt lgkmcnt(3)
	v_mfma_f32_16x16x32_bf16 v[0:3], v[80:83], v[242:245], v[0:3]
	v_mfma_f32_16x16x32_bf16 v[90:93], v[80:83], v[194:197], v[90:93]
	ds_read_b128 v[80:83], v133 offset:1024
	s_waitcnt lgkmcnt(3)
	v_mfma_f32_16x16x32_bf16 v[4:7], v[122:125], v[238:241], 0
	v_mfma_f32_16x16x32_bf16 v[94:97], v[122:125], v[246:249], 0
	ds_read_b128 v[122:125], v131 offset:1536
	s_waitcnt lgkmcnt(3)
	v_mfma_f32_16x16x32_bf16 v[4:7], v[126:129], v[242:245], v[4:7]
	v_mfma_f32_16x16x32_bf16 v[94:97], v[126:129], v[194:197], v[94:97]
	ds_read_b128 v[126:129], v133 offset:1536
	s_waitcnt lgkmcnt(3)
	v_mfma_f32_16x16x32_bf16 v[8:11], v[76:79], v[238:241], 0
	v_mfma_f32_16x16x32_bf16 v[98:101], v[76:79], v[246:249], 0
	ds_read_b128 v[76:79], v131 offset:2048
	s_waitcnt lgkmcnt(3)
	v_mfma_f32_16x16x32_bf16 v[8:11], v[80:83], v[242:245], v[8:11]
	v_mfma_f32_16x16x32_bf16 v[98:101], v[80:83], v[194:197], v[98:101]
	ds_read_b128 v[80:83], v133 offset:2048
	s_waitcnt lgkmcnt(3)
	v_mfma_f32_16x16x32_bf16 v[12:15], v[122:125], v[238:241], 0
	v_mfma_f32_16x16x32_bf16 v[102:105], v[122:125], v[246:249], 0
	ds_read_b128 v[122:125], v131 offset:2560
	s_waitcnt lgkmcnt(3)
	v_mfma_f32_16x16x32_bf16 v[12:15], v[126:129], v[242:245], v[12:15]
	v_mfma_f32_16x16x32_bf16 v[102:105], v[126:129], v[194:197], v[102:105]
	ds_read_b128 v[126:129], v133 offset:2560
	s_waitcnt lgkmcnt(3)
	v_mfma_f32_16x16x32_bf16 v[16:19], v[76:79], v[238:241], 0
	v_mfma_f32_16x16x32_bf16 v[106:109], v[76:79], v[246:249], 0
	ds_read_b128 v[76:79], v131 offset:3072
	s_waitcnt lgkmcnt(3)
	v_mfma_f32_16x16x32_bf16 v[16:19], v[80:83], v[242:245], v[16:19]
	v_mfma_f32_16x16x32_bf16 v[106:109], v[80:83], v[194:197], v[106:109]
	ds_read_b128 v[80:83], v133 offset:3072
	s_waitcnt lgkmcnt(3)
	v_mfma_f32_16x16x32_bf16 v[20:23], v[122:125], v[238:241], 0
	v_mfma_f32_16x16x32_bf16 v[110:113], v[122:125], v[246:249], 0
	ds_read_b128 v[122:125], v131 offset:3584
	s_waitcnt lgkmcnt(3)
	v_mfma_f32_16x16x32_bf16 v[20:23], v[126:129], v[242:245], v[20:23]
	v_mfma_f32_16x16x32_bf16 v[110:113], v[126:129], v[194:197], v[110:113]
	ds_read_b128 v[126:129], v133 offset:3584
	s_waitcnt lgkmcnt(3)
	v_mfma_f32_16x16x32_bf16 v[24:27], v[76:79], v[238:241], 0
	v_mfma_f32_16x16x32_bf16 v[114:117], v[76:79], v[246:249], 0
	s_waitcnt lgkmcnt(2)
	v_mfma_f32_16x16x32_bf16 v[24:27], v[80:83], v[242:245], v[24:27]
	v_mfma_f32_16x16x32_bf16 v[114:117], v[80:83], v[194:197], v[114:117]
	s_waitcnt lgkmcnt(1)
	v_mfma_f32_16x16x32_bf16 v[28:31], v[122:125], v[238:241], 0
	v_mfma_f32_16x16x32_bf16 v[118:121], v[122:125], v[246:249], 0
	s_waitcnt lgkmcnt(0)
	v_mfma_f32_16x16x32_bf16 v[28:31], v[126:129], v[242:245], v[28:31]
	v_mfma_f32_16x16x32_bf16 v[118:121], v[126:129], v[194:197], v[118:121]
	s_lshl_b32 s0, s56, 8
	s_add_u32 s0, s0, 0x0
	s_add_u32 s4, s20, s0
	s_addc_u32 s5, s21, 0
	global_load_dwordx4 v[238:241], v251, s[4:5]
	global_load_dwordx4 v[242:245], v251, s[4:5] offset:64
	s_add_u32 s4, s4, 0x2000
	s_addc_u32 s5, s5, 0
	global_load_dwordx4 v[246:249], v251, s[4:5]
	global_load_dwordx4 v[194:197], v251, s[4:5] offset:64
	s_nop 7
	s_nop 7
	v_add_f32_e32 v0, v0, v145
	v_add_f32_e32 v1, v1, v145
	v_add_f32_e32 v2, v2, v145
	v_add_f32_e32 v3, v3, v145
	v_add_f32_e32 v90, v90, v146
	v_add_f32_e32 v91, v91, v146
	v_add_f32_e32 v92, v92, v146
	v_add_f32_e32 v93, v93, v146
	v_exp_f32_e32 v0, v0
	v_exp_f32_e32 v1, v1
	v_exp_f32_e32 v2, v2
	v_exp_f32_e32 v3, v3
	v_exp_f32_e32 v90, v90
	v_exp_f32_e32 v91, v91
	v_exp_f32_e32 v92, v92
	v_exp_f32_e32 v93, v93
	v_add_f32_e32 v0, 1.0, v0
	v_add_f32_e32 v1, 1.0, v1
	v_add_f32_e32 v2, 1.0, v2
	v_add_f32_e32 v3, 1.0, v3
	v_add_f32_e32 v90, 1.0, v90
	v_add_f32_e32 v91, 1.0, v91
	v_add_f32_e32 v92, 1.0, v92
	v_add_f32_e32 v93, 1.0, v93
	v_rcp_f32_e32 v0, v0
	v_rcp_f32_e32 v1, v1
	v_rcp_f32_e32 v2, v2
	v_rcp_f32_e32 v3, v3
	v_rcp_f32_e32 v90, v90
	v_rcp_f32_e32 v91, v91
	v_rcp_f32_e32 v92, v92
	v_rcp_f32_e32 v93, v93
	v_mul_f32_e32 v0, v147, v0
	v_mul_f32_e32 v1, v147, v1
	v_mul_f32_e32 v2, v147, v2
	v_mul_f32_e32 v3, v147, v3
	v_mul_f32_e32 v90, v90, v162
	v_mul_f32_e32 v91, v91, v163
	v_mul_f32_e32 v92, v92, v164
	v_mul_f32_e32 v93, v93, v165
	v_exp_f32_e32 v0, v0
	v_exp_f32_e32 v1, v1
	v_exp_f32_e32 v2, v2
	v_exp_f32_e32 v3, v3
	s_nop 0
	v_fma_f32 v138, -v0, v0, 1.0
	v_fma_f32 v139, -v1, v1, 1.0
	v_fma_f32 v140, -v2, v2, 1.0
	v_fma_f32 v141, -v3, v3, 1.0
	v_max_f32_e32 v138, 0, v138
	v_max_f32_e32 v139, 0, v139
	v_max_f32_e32 v140, 0, v140
	v_max_f32_e32 v141, 0, v141
	v_sqrt_f32_e32 v138, v138
	v_sqrt_f32_e32 v139, v139
	v_sqrt_f32_e32 v140, v140
	v_sqrt_f32_e32 v141, v141
	s_nop 0
	v_mul_f32_e32 v90, v138, v90
	v_mul_f32_e32 v91, v139, v91
	v_mul_f32_e32 v92, v140, v92
	v_mul_f32_e32 v93, v141, v93
	v_add_f32_e32 v4, v4, v145
	v_add_f32_e32 v5, v5, v145
	v_add_f32_e32 v6, v6, v145
	v_add_f32_e32 v7, v7, v145
	v_add_f32_e32 v94, v94, v146
	v_add_f32_e32 v95, v95, v146
	v_add_f32_e32 v96, v96, v146
	v_add_f32_e32 v97, v97, v146
	v_exp_f32_e32 v4, v4
	v_exp_f32_e32 v5, v5
	v_exp_f32_e32 v6, v6
	v_exp_f32_e32 v7, v7
	v_exp_f32_e32 v94, v94
	v_exp_f32_e32 v95, v95
	v_exp_f32_e32 v96, v96
	v_exp_f32_e32 v97, v97
	v_add_f32_e32 v4, 1.0, v4
	v_add_f32_e32 v5, 1.0, v5
	v_add_f32_e32 v6, 1.0, v6
	v_add_f32_e32 v7, 1.0, v7
	v_add_f32_e32 v94, 1.0, v94
	v_add_f32_e32 v95, 1.0, v95
	v_add_f32_e32 v96, 1.0, v96
	v_add_f32_e32 v97, 1.0, v97
	v_rcp_f32_e32 v4, v4
	v_rcp_f32_e32 v5, v5
	v_rcp_f32_e32 v6, v6
; __device__ __forceinline__ float bf2f(u16 h) { return __uint_as_float(((unsigned)h) << 16); }
; __device__ __forceinline__ void lru_tile(const Params& P, int chunk, int head, int pass, char* smem_raw) {
;     ...
;           const float r = __builtin_amdgcn_rcpf(1.f + __builtin_amdgcn_exp2f(acc[tc][reg] + ba[tc]));
;           const float ii = __builtin_amdgcn_rcpf(1.f + __builtin_amdgcn_exp2f(acc[tc + 4][reg] + bi[tc]));
;           const float la = -c8[tc] * r;
;           const float a = __builtin_amdgcn_exp2f(la);
;           const float ucv = bf2f(sm_uc[(sb * 64 + tl) * LDSS + c]);
;           const float bt = __builtin_amdgcn_sqrtf(fmaxf(1.f - a * a, 0.f)) * (ii * ucv);
	v_rcp_f32_e32 v7, v7
	v_rcp_f32_e32 v94, v94
	v_rcp_f32_e32 v95, v95
	v_rcp_f32_e32 v96, v96
	v_rcp_f32_e32 v97, v97
	v_mul_f32_e32 v4, v147, v4
	v_mul_f32_e32 v5, v147, v5
	v_mul_f32_e32 v6, v147, v6
	v_mul_f32_e32 v7, v147, v7
	v_mul_f32_e32 v94, v94, v166
	v_mul_f32_e32 v95, v95, v167
	v_mul_f32_e32 v96, v96, v168
	v_mul_f32_e32 v97, v97, v169
	v_exp_f32_e32 v4, v4
	v_exp_f32_e32 v5, v5
	v_exp_f32_e32 v6, v6
	v_exp_f32_e32 v7, v7
	s_nop 0
	v_fma_f32 v138, -v4, v4, 1.0
	v_fma_f32 v139, -v5, v5, 1.0
	v_fma_f32 v140, -v6, v6, 1.0
	v_fma_f32 v141, -v7, v7, 1.0
	v_max_f32_e32 v138, 0, v138
	v_max_f32_e32 v139, 0, v139
	v_max_f32_e32 v140, 0, v140
	v_max_f32_e32 v141, 0, v141
	v_sqrt_f32_e32 v138, v138
	v_sqrt_f32_e32 v139, v139
	v_sqrt_f32_e32 v140, v140
	v_sqrt_f32_e32 v141, v141
	s_nop 0
	v_mul_f32_e32 v94, v138, v94
	v_mul_f32_e32 v95, v139, v95
	v_mul_f32_e32 v96, v140, v96
	v_mul_f32_e32 v97, v141, v97
	v_add_f32_e32 v8, v8, v145
	v_add_f32_e32 v9, v9, v145
	v_add_f32_e32 v10, v10, v145
	v_add_f32_e32 v11, v11, v145
	v_add_f32_e32 v98, v98, v146
	v_add_f32_e32 v99, v99, v146
	v_add_f32_e32 v100, v100, v146
	v_add_f32_e32 v101, v101, v146
	v_exp_f32_e32 v8, v8
	v_exp_f32_e32 v9, v9
	v_exp_f32_e32 v10, v10
	v_exp_f32_e32 v11, v11
	v_exp_f32_e32 v98, v98
	v_exp_f32_e32 v99, v99
	v_exp_f32_e32 v100, v100
	v_exp_f32_e32 v101, v101
	v_add_f32_e32 v8, 1.0, v8
	v_add_f32_e32 v9, 1.0, v9
	v_add_f32_e32 v10, 1.0, v10
	v_add_f32_e32 v11, 1.0, v11
	v_add_f32_e32 v98, 1.0, v98
	v_add_f32_e32 v99, 1.0, v99
	v_add_f32_e32 v100, 1.0, v100
	v_add_f32_e32 v101, 1.0, v101
	v_rcp_f32_e32 v8, v8
	v_rcp_f32_e32 v9, v9
	v_rcp_f32_e32 v10, v10
	v_rcp_f32_e32 v11, v11
	v_rcp_f32_e32 v98, v98
	v_rcp_f32_e32 v99, v99
	v_rcp_f32_e32 v100, v100
	v_rcp_f32_e32 v101, v101
	v_mul_f32_e32 v8, v147, v8
	v_mul_f32_e32 v9, v147, v9
	v_mul_f32_e32 v10, v147, v10
	v_mul_f32_e32 v11, v147, v11
	v_mul_f32_e32 v98, v98, v170
	v_mul_f32_e32 v99, v99, v171
	v_mul_f32_e32 v100, v100, v172
	v_mul_f32_e32 v101, v101, v173
	v_exp_f32_e32 v8, v8
	v_exp_f32_e32 v9, v9
	v_exp_f32_e32 v10, v10
	v_exp_f32_e32 v11, v11
	s_nop 0
	v_fma_f32 v138, -v8, v8, 1.0
	v_fma_f32 v139, -v9, v9, 1.0
	v_fma_f32 v140, -v10, v10, 1.0
	v_fma_f32 v141, -v11, v11, 1.0
	v_max_f32_e32 v138, 0, v138
	v_max_f32_e32 v139, 0, v139
	v_max_f32_e32 v140, 0, v140
	v_max_f32_e32 v141, 0, v141
	v_sqrt_f32_e32 v138, v138
	v_sqrt_f32_e32 v139, v139
	v_sqrt_f32_e32 v140, v140
	v_sqrt_f32_e32 v141, v141
	s_nop 0
	v_mul_f32_e32 v98, v138, v98
	v_mul_f32_e32 v99, v139, v99
	v_mul_f32_e32 v100, v140, v100
	v_mul_f32_e32 v101, v141, v101
	v_add_f32_e32 v12, v12, v145
	v_add_f32_e32 v13, v13, v145
	v_add_f32_e32 v14, v14, v145
	v_add_f32_e32 v15, v15, v145
	v_add_f32_e32 v102, v102, v146
	v_add_f32_e32 v103, v103, v146
	v_add_f32_e32 v104, v104, v146
	v_add_f32_e32 v105, v105, v146
	v_exp_f32_e32 v12, v12
	v_exp_f32_e32 v13, v13
	v_exp_f32_e32 v14, v14
	v_exp_f32_e32 v15, v15
	v_exp_f32_e32 v102, v102
	v_exp_f32_e32 v103, v103
	v_exp_f32_e32 v104, v104
	v_exp_f32_e32 v105, v105
	v_add_f32_e32 v12, 1.0, v12
	v_add_f32_e32 v13, 1.0, v13
	v_add_f32_e32 v14, 1.0, v14
	v_add_f32_e32 v15, 1.0, v15
	v_add_f32_e32 v102, 1.0, v102
	v_add_f32_e32 v103, 1.0, v103
	v_add_f32_e32 v104, 1.0, v104
	v_add_f32_e32 v105, 1.0, v105
	v_rcp_f32_e32 v12, v12
	v_rcp_f32_e32 v13, v13
	v_rcp_f32_e32 v14, v14
	v_rcp_f32_e32 v15, v15
	v_rcp_f32_e32 v102, v102
	v_rcp_f32_e32 v103, v103
	v_rcp_f32_e32 v104, v104
	v_rcp_f32_e32 v105, v105
	v_mul_f32_e32 v12, v147, v12
	v_mul_f32_e32 v13, v147, v13
	v_mul_f32_e32 v14, v147, v14
	v_mul_f32_e32 v15, v147, v15
	v_mul_f32_e32 v102, v102, v174
	v_mul_f32_e32 v103, v103, v175
	v_mul_f32_e32 v104, v104, v176
	v_mul_f32_e32 v105, v105, v177
	v_exp_f32_e32 v12, v12
	v_exp_f32_e32 v13, v13
	v_exp_f32_e32 v14, v14
	v_exp_f32_e32 v15, v15
	s_nop 0
	v_fma_f32 v138, -v12, v12, 1.0
	v_fma_f32 v139, -v13, v13, 1.0
	v_fma_f32 v140, -v14, v14, 1.0
	v_fma_f32 v141, -v15, v15, 1.0
	v_max_f32_e32 v138, 0, v138
	v_max_f32_e32 v139, 0, v139
	v_max_f32_e32 v140, 0, v140
	v_max_f32_e32 v141, 0, v141
	v_sqrt_f32_e32 v138, v138
	v_sqrt_f32_e32 v139, v139
	v_sqrt_f32_e32 v140, v140
	v_sqrt_f32_e32 v141, v141
	s_nop 0
	v_mul_f32_e32 v102, v138, v102
	v_mul_f32_e32 v103, v139, v103
	v_mul_f32_e32 v104, v140, v104
	v_mul_f32_e32 v105, v141, v105
	v_add_f32_e32 v16, v16, v145
	v_add_f32_e32 v17, v17, v145
	v_add_f32_e32 v18, v18, v145
	v_add_f32_e32 v19, v19, v145
	v_add_f32_e32 v106, v106, v146
	v_add_f32_e32 v107, v107, v146
	v_add_f32_e32 v108, v108, v146
	v_add_f32_e32 v109, v109, v146
	v_exp_f32_e32 v16, v16
	v_exp_f32_e32 v17, v17
	v_exp_f32_e32 v18, v18
	v_exp_f32_e32 v19, v19
	v_exp_f32_e32 v106, v106
	v_exp_f32_e32 v107, v107
	v_exp_f32_e32 v108, v108
	v_exp_f32_e32 v109, v109
	v_add_f32_e32 v16, 1.0, v16
	v_add_f32_e32 v17, 1.0, v17
	v_add_f32_e32 v18, 1.0, v18
	v_add_f32_e32 v19, 1.0, v19
	v_add_f32_e32 v106, 1.0, v106
	v_add_f32_e32 v107, 1.0, v107
	v_add_f32_e32 v108, 1.0, v108
	v_add_f32_e32 v109, 1.0, v109
	v_rcp_f32_e32 v16, v16
	v_rcp_f32_e32 v17, v17
	v_rcp_f32_e32 v18, v18
	v_rcp_f32_e32 v19, v19
	v_rcp_f32_e32 v106, v106
	v_rcp_f32_e32 v107, v107
	v_rcp_f32_e32 v108, v108
	v_rcp_f32_e32 v109, v109
	v_mul_f32_e32 v16, v147, v16
	v_mul_f32_e32 v17, v147, v17
	v_mul_f32_e32 v18, v147, v18
	v_mul_f32_e32 v19, v147, v19
	v_mul_f32_e32 v106, v106, v178
	v_mul_f32_e32 v107, v107, v179
	v_mul_f32_e32 v108, v108, v180
	v_mul_f32_e32 v109, v109, v181
	v_exp_f32_e32 v16, v16
	v_exp_f32_e32 v17, v17
	v_exp_f32_e32 v18, v18
	v_exp_f32_e32 v19, v19
	s_nop 0
	v_fma_f32 v138, -v16, v16, 1.0
	v_fma_f32 v139, -v17, v17, 1.0
; __device__ __forceinline__ float bf2f(u16 h) { return __uint_as_float(((unsigned)h) << 16); }
; __device__ __forceinline__ void lru_tile(const Params& P, int chunk, int head, int pass, char* smem_raw) {
;     ...
;           const float r = __builtin_amdgcn_rcpf(1.f + __builtin_amdgcn_exp2f(acc[tc][reg] + ba[tc]));
;           const float ii = __builtin_amdgcn_rcpf(1.f + __builtin_amdgcn_exp2f(acc[tc + 4][reg] + bi[tc]));
;           const float la = -c8[tc] * r;
;           const float a = __builtin_amdgcn_exp2f(la);
;           const float ucv = bf2f(sm_uc[(sb * 64 + tl) * LDSS + c]);
;           const float bt = __builtin_amdgcn_sqrtf(fmaxf(1.f - a * a, 0.f)) * (ii * ucv);
	v_fma_f32 v140, -v18, v18, 1.0
	v_fma_f32 v141, -v19, v19, 1.0
	v_max_f32_e32 v138, 0, v138
	v_max_f32_e32 v139, 0, v139
	v_max_f32_e32 v140, 0, v140
	v_max_f32_e32 v141, 0, v141
	v_sqrt_f32_e32 v138, v138
	v_sqrt_f32_e32 v139, v139
	v_sqrt_f32_e32 v140, v140
	v_sqrt_f32_e32 v141, v141
	s_nop 0
	v_mul_f32_e32 v106, v138, v106
	v_mul_f32_e32 v107, v139, v107
	v_mul_f32_e32 v108, v140, v108
	v_mul_f32_e32 v109, v141, v109
	v_add_f32_e32 v20, v20, v145
	v_add_f32_e32 v21, v21, v145
	v_add_f32_e32 v22, v22, v145
	v_add_f32_e32 v23, v23, v145
	v_add_f32_e32 v110, v110, v146
	v_add_f32_e32 v111, v111, v146
	v_add_f32_e32 v112, v112, v146
	v_add_f32_e32 v113, v113, v146
	v_exp_f32_e32 v20, v20
	v_exp_f32_e32 v21, v21
	v_exp_f32_e32 v22, v22
	v_exp_f32_e32 v23, v23
	v_exp_f32_e32 v110, v110
	v_exp_f32_e32 v111, v111
	v_exp_f32_e32 v112, v112
	v_exp_f32_e32 v113, v113
	v_add_f32_e32 v20, 1.0, v20
	v_add_f32_e32 v21, 1.0, v21
	v_add_f32_e32 v22, 1.0, v22
	v_add_f32_e32 v23, 1.0, v23
	v_add_f32_e32 v110, 1.0, v110
	v_add_f32_e32 v111, 1.0, v111
	v_add_f32_e32 v112, 1.0, v112
	v_add_f32_e32 v113, 1.0, v113
	v_rcp_f32_e32 v20, v20
	v_rcp_f32_e32 v21, v21
	v_rcp_f32_e32 v22, v22
	v_rcp_f32_e32 v23, v23
	v_rcp_f32_e32 v110, v110
	v_rcp_f32_e32 v111, v111
	v_rcp_f32_e32 v112, v112
	v_rcp_f32_e32 v113, v113
	v_mul_f32_e32 v20, v147, v20
	v_mul_f32_e32 v21, v147, v21
	v_mul_f32_e32 v22, v147, v22
	v_mul_f32_e32 v23, v147, v23
	v_mul_f32_e32 v110, v110, v182
	v_mul_f32_e32 v111, v111, v183
	v_mul_f32_e32 v112, v112, v184
	v_mul_f32_e32 v113, v113, v185
	v_exp_f32_e32 v20, v20
	v_exp_f32_e32 v21, v21
	v_exp_f32_e32 v22, v22
	v_exp_f32_e32 v23, v23
	s_nop 0
	v_fma_f32 v138, -v20, v20, 1.0
	v_fma_f32 v139, -v21, v21, 1.0
	v_fma_f32 v140, -v22, v22, 1.0
	v_fma_f32 v141, -v23, v23, 1.0
	v_max_f32_e32 v138, 0, v138
	v_max_f32_e32 v139, 0, v139
	v_max_f32_e32 v140, 0, v140
	v_max_f32_e32 v141, 0, v141
	v_sqrt_f32_e32 v138, v138
	v_sqrt_f32_e32 v139, v139
	v_sqrt_f32_e32 v140, v140
	v_sqrt_f32_e32 v141, v141
	s_nop 0
	v_mul_f32_e32 v110, v138, v110
	v_mul_f32_e32 v111, v139, v111
	v_mul_f32_e32 v112, v140, v112
	v_mul_f32_e32 v113, v141, v113
	v_add_f32_e32 v24, v24, v145
	v_add_f32_e32 v25, v25, v145
	v_add_f32_e32 v26, v26, v145
	v_add_f32_e32 v27, v27, v145
	v_add_f32_e32 v114, v114, v146
	v_add_f32_e32 v115, v115, v146
	v_add_f32_e32 v116, v116, v146
	v_add_f32_e32 v117, v117, v146
	v_exp_f32_e32 v24, v24
	v_exp_f32_e32 v25, v25
	v_exp_f32_e32 v26, v26
	v_exp_f32_e32 v27, v27
	v_exp_f32_e32 v114, v114
	v_exp_f32_e32 v115, v115
	v_exp_f32_e32 v116, v116
	v_exp_f32_e32 v117, v117
	v_add_f32_e32 v24, 1.0, v24
	v_add_f32_e32 v25, 1.0, v25
	v_add_f32_e32 v26, 1.0, v26
	v_add_f32_e32 v27, 1.0, v27
	v_add_f32_e32 v114, 1.0, v114
	v_add_f32_e32 v115, 1.0, v115
	v_add_f32_e32 v116, 1.0, v116
	v_add_f32_e32 v117, 1.0, v117
	v_rcp_f32_e32 v24, v24
	v_rcp_f32_e32 v25, v25
	v_rcp_f32_e32 v26, v26
	v_rcp_f32_e32 v27, v27
	v_rcp_f32_e32 v114, v114
	v_rcp_f32_e32 v115, v115
	v_rcp_f32_e32 v116, v116
	v_rcp_f32_e32 v117, v117
	v_mul_f32_e32 v24, v147, v24
	v_mul_f32_e32 v25, v147, v25
	v_mul_f32_e32 v26, v147, v26
	v_mul_f32_e32 v27, v147, v27
	v_mul_f32_e32 v114, v114, v186
	v_mul_f32_e32 v115, v115, v187
	v_mul_f32_e32 v116, v116, v188
	v_mul_f32_e32 v117, v117, v189
	v_exp_f32_e32 v24, v24
	v_exp_f32_e32 v25, v25
	v_exp_f32_e32 v26, v26
	v_exp_f32_e32 v27, v27
	s_nop 0
	v_fma_f32 v138, -v24, v24, 1.0
	v_fma_f32 v139, -v25, v25, 1.0
	v_fma_f32 v140, -v26, v26, 1.0
	v_fma_f32 v141, -v27, v27, 1.0
	v_max_f32_e32 v138, 0, v138
	v_max_f32_e32 v139, 0, v139
	v_max_f32_e32 v140, 0, v140
	v_max_f32_e32 v141, 0, v141
	v_sqrt_f32_e32 v138, v138
	v_sqrt_f32_e32 v139, v139
	v_sqrt_f32_e32 v140, v140
	v_sqrt_f32_e32 v141, v141
	s_nop 0
	v_mul_f32_e32 v114, v138, v114
	v_mul_f32_e32 v115, v139, v115
	v_mul_f32_e32 v116, v140, v116
	v_mul_f32_e32 v117, v141, v117
	v_add_f32_e32 v28, v28, v145
	v_add_f32_e32 v29, v29, v145
	v_add_f32_e32 v30, v30, v145
	v_add_f32_e32 v31, v31, v145
	v_add_f32_e32 v118, v118, v146
	v_add_f32_e32 v119, v119, v146
	v_add_f32_e32 v120, v120, v146
	v_add_f32_e32 v121, v121, v146
	v_exp_f32_e32 v28, v28
	v_exp_f32_e32 v29, v29
	v_exp_f32_e32 v30, v30
	v_exp_f32_e32 v31, v31
	v_exp_f32_e32 v118, v118
	v_exp_f32_e32 v119, v119
	v_exp_f32_e32 v120, v120
	v_exp_f32_e32 v121, v121
	v_add_f32_e32 v28, 1.0, v28
	v_add_f32_e32 v29, 1.0, v29
	v_add_f32_e32 v30, 1.0, v30
	v_add_f32_e32 v31, 1.0, v31
	v_add_f32_e32 v118, 1.0, v118
	v_add_f32_e32 v119, 1.0, v119
	v_add_f32_e32 v120, 1.0, v120
	v_add_f32_e32 v121, 1.0, v121
	v_rcp_f32_e32 v28, v28
	v_rcp_f32_e32 v29, v29
	v_rcp_f32_e32 v30, v30
	v_rcp_f32_e32 v31, v31
	v_rcp_f32_e32 v118, v118
	v_rcp_f32_e32 v119, v119
	v_rcp_f32_e32 v120, v120
	v_rcp_f32_e32 v121, v121
	v_mul_f32_e32 v28, v147, v28
	v_mul_f32_e32 v29, v147, v29
	v_mul_f32_e32 v30, v147, v30
	v_mul_f32_e32 v31, v147, v31
	v_mul_f32_e32 v118, v118, v190
	v_mul_f32_e32 v119, v119, v191
	v_mul_f32_e32 v120, v120, v192
	v_mul_f32_e32 v121, v121, v193
	v_exp_f32_e32 v28, v28
	v_exp_f32_e32 v29, v29
	v_exp_f32_e32 v30, v30
	v_exp_f32_e32 v31, v31
	s_nop 0
	v_fma_f32 v138, -v28, v28, 1.0
	v_fma_f32 v139, -v29, v29, 1.0
	v_fma_f32 v140, -v30, v30, 1.0
	v_fma_f32 v141, -v31, v31, 1.0
	v_max_f32_e32 v138, 0, v138
	v_max_f32_e32 v139, 0, v139
	v_max_f32_e32 v140, 0, v140
	v_max_f32_e32 v141, 0, v141
	v_sqrt_f32_e32 v138, v138
	v_sqrt_f32_e32 v139, v139
	v_sqrt_f32_e32 v140, v140
	v_sqrt_f32_e32 v141, v141
	s_nop 0
	v_mul_f32_e32 v118, v138, v118
	v_mul_f32_e32 v119, v139, v119
	v_mul_f32_e32 v120, v140, v120
	v_mul_f32_e32 v121, v141, v121
	s_mul_i32 s0, s71, 0x60000
; __device__ __forceinline__ float bf2f(u16 h) { return __uint_as_float(((unsigned)h) << 16); }
; __device__ __forceinline__ void lru_tile(const Params& P, int chunk, int head, int pass, char* smem_raw) {
;     ...
;       if (pass == 2) {
;         float hin = cB;
;         if (pos > 0) hin = p0.x * hin + p0.y;
;         if (pos > 1) hin = p1.x * hin + p1.y;
;         if (pos > 2) hin = p2.x * hin + p2.y;
;         float h = hin;
;         float hfp[16], gp[16];
;         if (d == 1) {
; #pragma unroll
;           for (int i = 0; i < 16; ++i) {
;             const long rowp = row0 + sb * 64 + q * 16 + 15 - i;
;             hfp[i] = hfbuf[rowp * 512 + gch];
;             gp[i] = bf2f(P.zq[rowp * 1536 + 512 + gch]);
;           }
;         }
; #pragma unroll
;         for (int i = 0; i < 16; ++i) {
;           const int tl = (d == 0) ? (q * 16 + i) : (q * 16 + 15 - i);
;           const float a = sm_a[tl * 64 + ch], b = sm_b[tl * 64 + ch];
;           h = a * h + b;
;           const long row = row0 + sb * 64 + tl;
	s_lshl_b32 s1, s56, 1
	s_add_u32 s0, s0, s1
	s_add_u32 s0, s0, 0x400
	s_add_u32 s4, s10, s0
	s_addc_u32 s5, s11, 0
	global_load_ushort v162, v134, s[4:5]
	s_add_u32 s4, s4, 0xc00
	s_addc_u32 s5, s5, 0
	global_load_ushort v163, v134, s[4:5]
	s_add_u32 s4, s4, 0xc00
	s_addc_u32 s5, s5, 0
	global_load_ushort v164, v134, s[4:5]
	s_add_u32 s4, s4, 0xc00
	s_addc_u32 s5, s5, 0
	global_load_ushort v165, v134, s[4:5]
	s_add_u32 s4, s4, 0xc00
	s_addc_u32 s5, s5, 0
	global_load_ushort v166, v134, s[4:5]
	s_add_u32 s4, s4, 0xc00
	s_addc_u32 s5, s5, 0
	global_load_ushort v167, v134, s[4:5]
	s_add_u32 s4, s4, 0xc00
	s_addc_u32 s5, s5, 0
	global_load_ushort v168, v134, s[4:5]
	s_add_u32 s4, s4, 0xc00
	s_addc_u32 s5, s5, 0
	global_load_ushort v169, v134, s[4:5]
	s_add_u32 s4, s4, 0xc00
	s_addc_u32 s5, s5, 0
	global_load_ushort v170, v134, s[4:5]
	s_add_u32 s4, s4, 0xc00
	s_addc_u32 s5, s5, 0
	global_load_ushort v171, v134, s[4:5]
	s_add_u32 s4, s4, 0xc00
	s_addc_u32 s5, s5, 0
	global_load_ushort v172, v134, s[4:5]
	s_add_u32 s4, s4, 0xc00
	s_addc_u32 s5, s5, 0
	global_load_ushort v173, v134, s[4:5]
	s_add_u32 s4, s4, 0xc00
	s_addc_u32 s5, s5, 0
	global_load_ushort v174, v134, s[4:5]
	s_add_u32 s4, s4, 0xc00
	s_addc_u32 s5, s5, 0
	global_load_ushort v175, v134, s[4:5]
	s_add_u32 s4, s4, 0xc00
	s_addc_u32 s5, s5, 0
	global_load_ushort v176, v134, s[4:5]
	s_add_u32 s4, s4, 0xc00
	s_addc_u32 s5, s5, 0
	global_load_ushort v177, v134, s[4:5]
	s_add_u32 s4, s4, 0xc00
	s_addc_u32 s5, s5, 0
	global_load_ushort v178, v134, s[4:5]
	s_add_u32 s4, s4, 0xc00
	s_addc_u32 s5, s5, 0
	global_load_ushort v179, v134, s[4:5]
	s_add_u32 s4, s4, 0xc00
	s_addc_u32 s5, s5, 0
	global_load_ushort v180, v134, s[4:5]
	s_add_u32 s4, s4, 0xc00
	s_addc_u32 s5, s5, 0
	global_load_ushort v181, v134, s[4:5]
	s_add_u32 s4, s4, 0xc00
	s_addc_u32 s5, s5, 0
	global_load_ushort v182, v134, s[4:5]
	s_add_u32 s4, s4, 0xc00
	s_addc_u32 s5, s5, 0
	global_load_ushort v183, v134, s[4:5]
	s_add_u32 s4, s4, 0xc00
	s_addc_u32 s5, s5, 0
	global_load_ushort v184, v134, s[4:5]
	s_add_u32 s4, s4, 0xc00
	s_addc_u32 s5, s5, 0
	global_load_ushort v185, v134, s[4:5]
	s_add_u32 s4, s4, 0xc00
	s_addc_u32 s5, s5, 0
	global_load_ushort v186, v134, s[4:5]
	s_add_u32 s4, s4, 0xc00
	s_addc_u32 s5, s5, 0
	global_load_ushort v187, v134, s[4:5]
	s_add_u32 s4, s4, 0xc00
	s_addc_u32 s5, s5, 0
	global_load_ushort v188, v134, s[4:5]
	s_add_u32 s4, s4, 0xc00
	s_addc_u32 s5, s5, 0
	global_load_ushort v189, v134, s[4:5]
	s_add_u32 s4, s4, 0xc00
	s_addc_u32 s5, s5, 0
	global_load_ushort v190, v134, s[4:5]
	s_add_u32 s4, s4, 0xc00
	s_addc_u32 s5, s5, 0
	global_load_ushort v191, v134, s[4:5]
	s_add_u32 s4, s4, 0xc00
	s_addc_u32 s5, s5, 0
	global_load_ushort v192, v134, s[4:5]
	s_add_u32 s4, s4, 0xc00
	s_addc_u32 s5, s5, 0
	global_load_ushort v193, v134, s[4:5]
	v_mov_b32_e32 v253, v31
	v_mov_b32_e32 v254, v121
	v_fma_f32 v254, v30, v254, v120
	v_mul_f32_e32 v253, v253, v30
	v_fma_f32 v254, v29, v254, v119
	v_mul_f32_e32 v253, v253, v29
	v_fma_f32 v254, v28, v254, v118
	v_mul_f32_e32 v253, v253, v28
	v_fma_f32 v254, v27, v254, v117
	v_mul_f32_e32 v253, v253, v27
	v_fma_f32 v254, v26, v254, v116
	v_mul_f32_e32 v253, v253, v26
	v_fma_f32 v254, v25, v254, v115
	v_mul_f32_e32 v253, v253, v25
	v_fma_f32 v254, v24, v254, v114
	v_mul_f32_e32 v253, v253, v24
	v_fma_f32 v254, v23, v254, v113
	v_mul_f32_e32 v253, v253, v23
	v_fma_f32 v254, v22, v254, v112
	v_mul_f32_e32 v253, v253, v22
	v_fma_f32 v254, v21, v254, v111
	v_mul_f32_e32 v253, v253, v21
	v_fma_f32 v254, v20, v254, v110
	v_mul_f32_e32 v253, v253, v20
	v_fma_f32 v254, v19, v254, v109
	v_mul_f32_e32 v253, v253, v19
	v_fma_f32 v254, v18, v254, v108
	v_mul_f32_e32 v253, v253, v18
	v_fma_f32 v254, v17, v254, v107
	v_mul_f32_e32 v253, v253, v17
	v_fma_f32 v254, v16, v254, v106
	v_mul_f32_e32 v253, v253, v16
	v_fma_f32 v254, v15, v254, v105
	v_mul_f32_e32 v253, v253, v15
	v_fma_f32 v254, v14, v254, v104
	v_mul_f32_e32 v253, v253, v14
	v_fma_f32 v254, v13, v254, v103
	v_mul_f32_e32 v253, v253, v13
	v_fma_f32 v254, v12, v254, v102
	v_mul_f32_e32 v253, v253, v12
	v_fma_f32 v254, v11, v254, v101
	v_mul_f32_e32 v253, v253, v11
	v_fma_f32 v254, v10, v254, v100
	v_mul_f32_e32 v253, v253, v10
	v_fma_f32 v254, v9, v254, v99
	v_mul_f32_e32 v253, v253, v9
	v_fma_f32 v254, v8, v254, v98
	v_mul_f32_e32 v253, v253, v8
	v_fma_f32 v254, v7, v254, v97
	v_mul_f32_e32 v253, v253, v7
	v_fma_f32 v254, v6, v254, v96
	v_mul_f32_e32 v253, v253, v6
	v_fma_f32 v254, v5, v254, v95
	v_mul_f32_e32 v253, v253, v5
	v_fma_f32 v254, v4, v254, v94
	v_mul_f32_e32 v253, v253, v4
	v_fma_f32 v254, v3, v254, v93
	v_mul_f32_e32 v253, v253, v3
	v_fma_f32 v254, v2, v254, v92
	v_mul_f32_e32 v253, v253, v2
	v_fma_f32 v254, v1, v254, v91
	v_mul_f32_e32 v253, v253, v1
	v_fma_f32 v254, v0, v254, v90
	v_mul_f32_e32 v253, v253, v0
	v_mov_b32_e32 v138, v253
	v_mov_b32_e32 v139, v253
	s_nop 1
	v_permlane16_swap_b32_e32 v138, v139
	v_mov_b32_e32 v140, v138
	v_mov_b32_e32 v141, v139
	s_nop 1
	v_permlane32_swap_b32_e32 v138, v140
	v_permlane32_swap_b32_e32 v139, v141
	v_mov_b32_e32 v198, v254
	v_mov_b32_e32 v199, v254
	s_nop 1
	v_permlane16_swap_b32_e32 v198, v199
	v_mov_b32_e32 v200, v198
	v_mov_b32_e32 v201, v199
	s_nop 1
	v_permlane32_swap_b32_e32 v198, v200
	v_permlane32_swap_b32_e32 v199, v201
	v_mov_b32_e32 v202, v149
	v_fma_f32 v151, v141, v202, v201
	v_fma_f32 v150, v140, v151, v200
	v_fma_f32 v136, v139, v150, v199
	v_mov_b32_e32 v254, v202
	v_cndmask_b32_e64 v254, v254, v151, s[78:79]
	v_cndmask_b32_e64 v254, v254, v150, s[80:81]
	v_cndmask_b32_e64 v254, v254, v136, s[82:83]
	v_fma_f32 v121, v31, v254, v121
	v_fma_f32 v120, v30, v121, v120
	v_fma_f32 v119, v29, v120, v119
	v_fma_f32 v118, v28, v119, v118
	v_fma_f32 v117, v27, v118, v117
	v_fma_f32 v116, v26, v117, v116
	v_fma_f32 v115, v25, v116, v115
	v_fma_f32 v114, v24, v115, v114
	v_fma_f32 v113, v23, v114, v113
	v_fma_f32 v112, v22, v113, v112
	v_fma_f32 v111, v21, v112, v111
	v_fma_f32 v110, v20, v111, v110
	v_fma_f32 v109, v19, v110, v109
	v_fma_f32 v108, v18, v109, v108
	v_fma_f32 v107, v17, v108, v107
	v_fma_f32 v106, v16, v107, v106
	v_fma_f32 v105, v15, v106, v105
	v_fma_f32 v104, v14, v105, v104
	v_fma_f32 v103, v13, v104, v103
	v_fma_f32 v102, v12, v103, v102
	v_fma_f32 v101, v11, v102, v101
	v_fma_f32 v100, v10, v101, v100
	v_fma_f32 v99, v9, v100, v99
	v_fma_f32 v98, v8, v99, v98
	v_fma_f32 v97, v7, v98, v97
	v_fma_f32 v96, v6, v97, v96
	v_fma_f32 v95, v5, v96, v95
	v_fma_f32 v94, v4, v95, v94
	v_fma_f32 v93, v3, v94, v93
	v_fma_f32 v92, v2, v93, v92
	v_fma_f32 v91, v1, v92, v91
	v_fma_f32 v90, v0, v91, v90
	s_waitcnt vmcnt(0)
; __device__ __forceinline__ void lru_tile(const Params& P, int chunk, int head, int pass, char* smem_raw) {
;     ...
;           } else {
;             const float hfv = hfp[i];
;             const float g = gp[i];
;             const float tz = 0.7978845608028654f * (g + 0.044715f * g * g * g);
;             const float th = 1.f - 2.f * __builtin_amdgcn_rcpf(1.f + __expf(2.f * tz));
;             const float ge = 0.5f * g * (1.f + th);
;             P.cat[row * 1024 + gch] = f2bf((hfv + h) * ge);
	v_lshlrev_b32_e32 v162, 16, v162
	v_lshlrev_b32_e32 v163, 16, v163
	v_lshlrev_b32_e32 v164, 16, v164
	v_lshlrev_b32_e32 v165, 16, v165
	v_lshlrev_b32_e32 v166, 16, v166
	v_lshlrev_b32_e32 v167, 16, v167
	v_lshlrev_b32_e32 v168, 16, v168
	v_lshlrev_b32_e32 v169, 16, v169
	v_lshlrev_b32_e32 v170, 16, v170
	v_lshlrev_b32_e32 v171, 16, v171
	v_lshlrev_b32_e32 v172, 16, v172
	v_lshlrev_b32_e32 v173, 16, v173
	v_lshlrev_b32_e32 v174, 16, v174
	v_lshlrev_b32_e32 v175, 16, v175
	v_lshlrev_b32_e32 v176, 16, v176
	v_lshlrev_b32_e32 v177, 16, v177
	v_lshlrev_b32_e32 v178, 16, v178
	v_lshlrev_b32_e32 v179, 16, v179
	v_lshlrev_b32_e32 v180, 16, v180
	v_lshlrev_b32_e32 v181, 16, v181
	v_lshlrev_b32_e32 v182, 16, v182
	v_lshlrev_b32_e32 v183, 16, v183
	v_lshlrev_b32_e32 v184, 16, v184
	v_lshlrev_b32_e32 v185, 16, v185
	v_lshlrev_b32_e32 v186, 16, v186
	v_lshlrev_b32_e32 v187, 16, v187
	v_lshlrev_b32_e32 v188, 16, v188
	v_lshlrev_b32_e32 v189, 16, v189
	v_lshlrev_b32_e32 v190, 16, v190
	v_lshlrev_b32_e32 v191, 16, v191
	v_lshlrev_b32_e32 v192, 16, v192
	v_lshlrev_b32_e32 v193, 16, v193
	v_mov_b32_e32 v202, 0x3d372713
	v_mul_f32_e32 v138, v162, v162
	v_mul_f32_e32 v139, v163, v163
	v_mul_f32_e32 v140, v164, v164
	v_mul_f32_e32 v141, v165, v165
	v_mul_f32_e32 v138, v138, v162
	v_mul_f32_e32 v139, v139, v163
	v_mul_f32_e32 v140, v140, v164
	v_mul_f32_e32 v141, v141, v165
	v_fma_f32 v138, v202, v138, v162
	v_fma_f32 v139, v202, v139, v163
	v_fma_f32 v140, v202, v140, v164
	v_fma_f32 v141, v202, v141, v165
	v_mul_f32_e32 v138, 0x40135761, v138
	v_mul_f32_e32 v139, 0x40135761, v139
	v_mul_f32_e32 v140, 0x40135761, v140
	v_mul_f32_e32 v141, 0x40135761, v141
	v_exp_f32_e32 v138, v138
	v_exp_f32_e32 v139, v139
	v_exp_f32_e32 v140, v140
	v_exp_f32_e32 v141, v141
	s_nop 0
	v_add_f32_e32 v138, 1.0, v138
	v_add_f32_e32 v139, 1.0, v139
	v_add_f32_e32 v140, 1.0, v140
	v_add_f32_e32 v141, 1.0, v141
	v_rcp_f32_e32 v138, v138
	v_rcp_f32_e32 v139, v139
	v_rcp_f32_e32 v140, v140
	v_rcp_f32_e32 v141, v141
	s_nop 0
	v_fma_f32 v138, -2.0, v138, 1.0
	v_fma_f32 v139, -2.0, v139, 1.0
	v_fma_f32 v140, -2.0, v140, 1.0
	v_fma_f32 v141, -2.0, v141, 1.0
	v_add_f32_e32 v138, 1.0, v138
	v_add_f32_e32 v139, 1.0, v139
	v_add_f32_e32 v140, 1.0, v140
	v_add_f32_e32 v141, 1.0, v141
	v_mul_f32_e32 v162, 0.5, v162
	v_mul_f32_e32 v163, 0.5, v163
	v_mul_f32_e32 v164, 0.5, v164
	v_mul_f32_e32 v165, 0.5, v165
	v_mul_f32_e32 v162, v162, v138
	v_mul_f32_e32 v163, v163, v139
	v_mul_f32_e32 v164, v164, v140
	v_mul_f32_e32 v165, v165, v141
	v_add_f32_e32 v90, v205, v90
	v_add_f32_e32 v91, v206, v91
	v_add_f32_e32 v92, v207, v92
	v_add_f32_e32 v93, v208, v93
	v_mul_f32_e32 v90, v90, v162
	v_mul_f32_e32 v91, v91, v163
	v_mul_f32_e32 v92, v92, v164
	v_mul_f32_e32 v93, v93, v165
	v_cvt_pk_bf16_f32 v90, v90, v90
	v_cvt_pk_bf16_f32 v91, v91, v91
	v_cvt_pk_bf16_f32 v92, v92, v92
	v_cvt_pk_bf16_f32 v93, v93, v93
	v_mul_f32_e32 v138, v166, v166
	v_mul_f32_e32 v139, v167, v167
	v_mul_f32_e32 v140, v168, v168
	v_mul_f32_e32 v141, v169, v169
	v_mul_f32_e32 v138, v138, v166
	v_mul_f32_e32 v139, v139, v167
	v_mul_f32_e32 v140, v140, v168
	v_mul_f32_e32 v141, v141, v169
	v_fma_f32 v138, v202, v138, v166
	v_fma_f32 v139, v202, v139, v167
	v_fma_f32 v140, v202, v140, v168
	v_fma_f32 v141, v202, v141, v169
	v_mul_f32_e32 v138, 0x40135761, v138
	v_mul_f32_e32 v139, 0x40135761, v139
	v_mul_f32_e32 v140, 0x40135761, v140
	v_mul_f32_e32 v141, 0x40135761, v141
	v_exp_f32_e32 v138, v138
	v_exp_f32_e32 v139, v139
	v_exp_f32_e32 v140, v140
	v_exp_f32_e32 v141, v141
	s_nop 0
	v_add_f32_e32 v138, 1.0, v138
	v_add_f32_e32 v139, 1.0, v139
	v_add_f32_e32 v140, 1.0, v140
	v_add_f32_e32 v141, 1.0, v141
	v_rcp_f32_e32 v138, v138
	v_rcp_f32_e32 v139, v139
	v_rcp_f32_e32 v140, v140
	v_rcp_f32_e32 v141, v141
	s_nop 0
	v_fma_f32 v138, -2.0, v138, 1.0
	v_fma_f32 v139, -2.0, v139, 1.0
	v_fma_f32 v140, -2.0, v140, 1.0
	v_fma_f32 v141, -2.0, v141, 1.0
	v_add_f32_e32 v138, 1.0, v138
	v_add_f32_e32 v139, 1.0, v139
	v_add_f32_e32 v140, 1.0, v140
	v_add_f32_e32 v141, 1.0, v141
	v_mul_f32_e32 v166, 0.5, v166
	v_mul_f32_e32 v167, 0.5, v167
	v_mul_f32_e32 v168, 0.5, v168
	v_mul_f32_e32 v169, 0.5, v169
	v_mul_f32_e32 v166, v166, v138
	v_mul_f32_e32 v167, v167, v139
	v_mul_f32_e32 v168, v168, v140
	v_mul_f32_e32 v169, v169, v141
	v_add_f32_e32 v94, v209, v94
	v_add_f32_e32 v95, v210, v95
	v_add_f32_e32 v96, v211, v96
	v_add_f32_e32 v97, v212, v97
	v_mul_f32_e32 v94, v94, v166
	v_mul_f32_e32 v95, v95, v167
	v_mul_f32_e32 v96, v96, v168
	v_mul_f32_e32 v97, v97, v169
	v_cvt_pk_bf16_f32 v94, v94, v94
	v_cvt_pk_bf16_f32 v95, v95, v95
	v_cvt_pk_bf16_f32 v96, v96, v96
	v_cvt_pk_bf16_f32 v97, v97, v97
	v_mul_f32_e32 v138, v170, v170
	v_mul_f32_e32 v139, v171, v171
	v_mul_f32_e32 v140, v172, v172
	v_mul_f32_e32 v141, v173, v173
	v_mul_f32_e32 v138, v138, v170
	v_mul_f32_e32 v139, v139, v171
	v_mul_f32_e32 v140, v140, v172
	v_mul_f32_e32 v141, v141, v173
	v_fma_f32 v138, v202, v138, v170
	v_fma_f32 v139, v202, v139, v171
	v_fma_f32 v140, v202, v140, v172
	v_fma_f32 v141, v202, v141, v173
	v_mul_f32_e32 v138, 0x40135761, v138
	v_mul_f32_e32 v139, 0x40135761, v139
	v_mul_f32_e32 v140, 0x40135761, v140
	v_mul_f32_e32 v141, 0x40135761, v141
	v_exp_f32_e32 v138, v138
	v_exp_f32_e32 v139, v139
	v_exp_f32_e32 v140, v140
	v_exp_f32_e32 v141, v141
	s_nop 0
	v_add_f32_e32 v138, 1.0, v138
	v_add_f32_e32 v139, 1.0, v139
	v_add_f32_e32 v140, 1.0, v140
	v_add_f32_e32 v141, 1.0, v141
	v_rcp_f32_e32 v138, v138
	v_rcp_f32_e32 v139, v139
	v_rcp_f32_e32 v140, v140
	v_rcp_f32_e32 v141, v141
	s_nop 0
	v_fma_f32 v138, -2.0, v138, 1.0
	v_fma_f32 v139, -2.0, v139, 1.0
; __device__ __forceinline__ void lru_tile(const Params& P, int chunk, int head, int pass, char* smem_raw) {
;     ...
;             const float hfv = hfp[i];
;             const float g = gp[i];
;             const float tz = 0.7978845608028654f * (g + 0.044715f * g * g * g);
;             const float th = 1.f - 2.f * __builtin_amdgcn_rcpf(1.f + __expf(2.f * tz));
;             const float ge = 0.5f * g * (1.f + th);
;             P.cat[row * 1024 + gch] = f2bf((hfv + h) * ge);
	v_fma_f32 v140, -2.0, v140, 1.0
	v_fma_f32 v141, -2.0, v141, 1.0
	v_add_f32_e32 v138, 1.0, v138
	v_add_f32_e32 v139, 1.0, v139
	v_add_f32_e32 v140, 1.0, v140
	v_add_f32_e32 v141, 1.0, v141
	v_mul_f32_e32 v170, 0.5, v170
	v_mul_f32_e32 v171, 0.5, v171
	v_mul_f32_e32 v172, 0.5, v172
	v_mul_f32_e32 v173, 0.5, v173
	v_mul_f32_e32 v170, v170, v138
	v_mul_f32_e32 v171, v171, v139
	v_mul_f32_e32 v172, v172, v140
	v_mul_f32_e32 v173, v173, v141
	v_add_f32_e32 v98, v213, v98
	v_add_f32_e32 v99, v214, v99
	v_add_f32_e32 v100, v215, v100
	v_add_f32_e32 v101, v216, v101
	v_mul_f32_e32 v98, v98, v170
	v_mul_f32_e32 v99, v99, v171
	v_mul_f32_e32 v100, v100, v172
	v_mul_f32_e32 v101, v101, v173
	v_cvt_pk_bf16_f32 v98, v98, v98
	v_cvt_pk_bf16_f32 v99, v99, v99
	v_cvt_pk_bf16_f32 v100, v100, v100
	v_cvt_pk_bf16_f32 v101, v101, v101
	v_mul_f32_e32 v138, v174, v174
	v_mul_f32_e32 v139, v175, v175
	v_mul_f32_e32 v140, v176, v176
	v_mul_f32_e32 v141, v177, v177
	v_mul_f32_e32 v138, v138, v174
	v_mul_f32_e32 v139, v139, v175
	v_mul_f32_e32 v140, v140, v176
	v_mul_f32_e32 v141, v141, v177
	v_fma_f32 v138, v202, v138, v174
	v_fma_f32 v139, v202, v139, v175
	v_fma_f32 v140, v202, v140, v176
	v_fma_f32 v141, v202, v141, v177
	v_mul_f32_e32 v138, 0x40135761, v138
	v_mul_f32_e32 v139, 0x40135761, v139
	v_mul_f32_e32 v140, 0x40135761, v140
	v_mul_f32_e32 v141, 0x40135761, v141
	v_exp_f32_e32 v138, v138
	v_exp_f32_e32 v139, v139
	v_exp_f32_e32 v140, v140
	v_exp_f32_e32 v141, v141
	s_nop 0
	v_add_f32_e32 v138, 1.0, v138
	v_add_f32_e32 v139, 1.0, v139
	v_add_f32_e32 v140, 1.0, v140
	v_add_f32_e32 v141, 1.0, v141
	v_rcp_f32_e32 v138, v138
	v_rcp_f32_e32 v139, v139
	v_rcp_f32_e32 v140, v140
	v_rcp_f32_e32 v141, v141
	s_nop 0
	v_fma_f32 v138, -2.0, v138, 1.0
	v_fma_f32 v139, -2.0, v139, 1.0
	v_fma_f32 v140, -2.0, v140, 1.0
	v_fma_f32 v141, -2.0, v141, 1.0
	v_add_f32_e32 v138, 1.0, v138
	v_add_f32_e32 v139, 1.0, v139
	v_add_f32_e32 v140, 1.0, v140
	v_add_f32_e32 v141, 1.0, v141
	v_mul_f32_e32 v174, 0.5, v174
	v_mul_f32_e32 v175, 0.5, v175
	v_mul_f32_e32 v176, 0.5, v176
	v_mul_f32_e32 v177, 0.5, v177
	v_mul_f32_e32 v174, v174, v138
	v_mul_f32_e32 v175, v175, v139
	v_mul_f32_e32 v176, v176, v140
	v_mul_f32_e32 v177, v177, v141
	v_add_f32_e32 v102, v217, v102
	v_add_f32_e32 v103, v218, v103
	v_add_f32_e32 v104, v219, v104
	v_add_f32_e32 v105, v220, v105
	v_mul_f32_e32 v102, v102, v174
	v_mul_f32_e32 v103, v103, v175
	v_mul_f32_e32 v104, v104, v176
	v_mul_f32_e32 v105, v105, v177
	v_cvt_pk_bf16_f32 v102, v102, v102
	v_cvt_pk_bf16_f32 v103, v103, v103
	v_cvt_pk_bf16_f32 v104, v104, v104
	v_cvt_pk_bf16_f32 v105, v105, v105
	v_mul_f32_e32 v138, v178, v178
	v_mul_f32_e32 v139, v179, v179
	v_mul_f32_e32 v140, v180, v180
	v_mul_f32_e32 v141, v181, v181
	v_mul_f32_e32 v138, v138, v178
	v_mul_f32_e32 v139, v139, v179
	v_mul_f32_e32 v140, v140, v180
	v_mul_f32_e32 v141, v141, v181
	v_fma_f32 v138, v202, v138, v178
	v_fma_f32 v139, v202, v139, v179
	v_fma_f32 v140, v202, v140, v180
	v_fma_f32 v141, v202, v141, v181
	v_mul_f32_e32 v138, 0x40135761, v138
	v_mul_f32_e32 v139, 0x40135761, v139
	v_mul_f32_e32 v140, 0x40135761, v140
	v_mul_f32_e32 v141, 0x40135761, v141
	v_exp_f32_e32 v138, v138
	v_exp_f32_e32 v139, v139
	v_exp_f32_e32 v140, v140
	v_exp_f32_e32 v141, v141
	s_nop 0
	v_add_f32_e32 v138, 1.0, v138
	v_add_f32_e32 v139, 1.0, v139
	v_add_f32_e32 v140, 1.0, v140
	v_add_f32_e32 v141, 1.0, v141
	v_rcp_f32_e32 v138, v138
	v_rcp_f32_e32 v139, v139
	v_rcp_f32_e32 v140, v140
	v_rcp_f32_e32 v141, v141
	s_nop 0
	v_fma_f32 v138, -2.0, v138, 1.0
	v_fma_f32 v139, -2.0, v139, 1.0
	v_fma_f32 v140, -2.0, v140, 1.0
	v_fma_f32 v141, -2.0, v141, 1.0
	v_add_f32_e32 v138, 1.0, v138
	v_add_f32_e32 v139, 1.0, v139
	v_add_f32_e32 v140, 1.0, v140
	v_add_f32_e32 v141, 1.0, v141
	v_mul_f32_e32 v178, 0.5, v178
	v_mul_f32_e32 v179, 0.5, v179
	v_mul_f32_e32 v180, 0.5, v180
	v_mul_f32_e32 v181, 0.5, v181
	v_mul_f32_e32 v178, v178, v138
	v_mul_f32_e32 v179, v179, v139
	v_mul_f32_e32 v180, v180, v140
	v_mul_f32_e32 v181, v181, v141
	v_add_f32_e32 v106, v221, v106
	v_add_f32_e32 v107, v222, v107
	v_add_f32_e32 v108, v223, v108
	v_add_f32_e32 v109, v224, v109
	v_mul_f32_e32 v106, v106, v178
	v_mul_f32_e32 v107, v107, v179
	v_mul_f32_e32 v108, v108, v180
	v_mul_f32_e32 v109, v109, v181
	v_cvt_pk_bf16_f32 v106, v106, v106
	v_cvt_pk_bf16_f32 v107, v107, v107
	v_cvt_pk_bf16_f32 v108, v108, v108
	v_cvt_pk_bf16_f32 v109, v109, v109
	v_mul_f32_e32 v138, v182, v182
	v_mul_f32_e32 v139, v183, v183
	v_mul_f32_e32 v140, v184, v184
	v_mul_f32_e32 v141, v185, v185
	v_mul_f32_e32 v138, v138, v182
	v_mul_f32_e32 v139, v139, v183
	v_mul_f32_e32 v140, v140, v184
	v_mul_f32_e32 v141, v141, v185
	v_fma_f32 v138, v202, v138, v182
	v_fma_f32 v139, v202, v139, v183
	v_fma_f32 v140, v202, v140, v184
	v_fma_f32 v141, v202, v141, v185
	v_mul_f32_e32 v138, 0x40135761, v138
	v_mul_f32_e32 v139, 0x40135761, v139
	v_mul_f32_e32 v140, 0x40135761, v140
	v_mul_f32_e32 v141, 0x40135761, v141
	v_exp_f32_e32 v138, v138
	v_exp_f32_e32 v139, v139
	v_exp_f32_e32 v140, v140
	v_exp_f32_e32 v141, v141
	s_nop 0
	v_add_f32_e32 v138, 1.0, v138
	v_add_f32_e32 v139, 1.0, v139
	v_add_f32_e32 v140, 1.0, v140
	v_add_f32_e32 v141, 1.0, v141
	v_rcp_f32_e32 v138, v138
	v_rcp_f32_e32 v139, v139
	v_rcp_f32_e32 v140, v140
	v_rcp_f32_e32 v141, v141
	s_nop 0
	v_fma_f32 v138, -2.0, v138, 1.0
	v_fma_f32 v139, -2.0, v139, 1.0
	v_fma_f32 v140, -2.0, v140, 1.0
	v_fma_f32 v141, -2.0, v141, 1.0
	v_add_f32_e32 v138, 1.0, v138
	v_add_f32_e32 v139, 1.0, v139
	v_add_f32_e32 v140, 1.0, v140
	v_add_f32_e32 v141, 1.0, v141
	v_mul_f32_e32 v182, 0.5, v182
	v_mul_f32_e32 v183, 0.5, v183
; __device__ __forceinline__ void lru_tile(const Params& P, int chunk, int head, int pass, char* smem_raw) {
;     ...
;             const float hfv = hfp[i];
;             const float g = gp[i];
;             const float tz = 0.7978845608028654f * (g + 0.044715f * g * g * g);
;             const float th = 1.f - 2.f * __builtin_amdgcn_rcpf(1.f + __expf(2.f * tz));
;             const float ge = 0.5f * g * (1.f + th);
;             P.cat[row * 1024 + gch] = f2bf((hfv + h) * ge);
	v_mul_f32_e32 v184, 0.5, v184
	v_mul_f32_e32 v185, 0.5, v185
	v_mul_f32_e32 v182, v182, v138
	v_mul_f32_e32 v183, v183, v139
	v_mul_f32_e32 v184, v184, v140
	v_mul_f32_e32 v185, v185, v141
	v_add_f32_e32 v110, v225, v110
	v_add_f32_e32 v111, v226, v111
	v_add_f32_e32 v112, v227, v112
	v_add_f32_e32 v113, v228, v113
	v_mul_f32_e32 v110, v110, v182
	v_mul_f32_e32 v111, v111, v183
	v_mul_f32_e32 v112, v112, v184
	v_mul_f32_e32 v113, v113, v185
	v_cvt_pk_bf16_f32 v110, v110, v110
	v_cvt_pk_bf16_f32 v111, v111, v111
	v_cvt_pk_bf16_f32 v112, v112, v112
	v_cvt_pk_bf16_f32 v113, v113, v113
	v_mul_f32_e32 v138, v186, v186
	v_mul_f32_e32 v139, v187, v187
	v_mul_f32_e32 v140, v188, v188
	v_mul_f32_e32 v141, v189, v189
	v_mul_f32_e32 v138, v138, v186
	v_mul_f32_e32 v139, v139, v187
	v_mul_f32_e32 v140, v140, v188
	v_mul_f32_e32 v141, v141, v189
	v_fma_f32 v138, v202, v138, v186
	v_fma_f32 v139, v202, v139, v187
	v_fma_f32 v140, v202, v140, v188
	v_fma_f32 v141, v202, v141, v189
	v_mul_f32_e32 v138, 0x40135761, v138
	v_mul_f32_e32 v139, 0x40135761, v139
	v_mul_f32_e32 v140, 0x40135761, v140
	v_mul_f32_e32 v141, 0x40135761, v141
	v_exp_f32_e32 v138, v138
	v_exp_f32_e32 v139, v139
	v_exp_f32_e32 v140, v140
	v_exp_f32_e32 v141, v141
	s_nop 0
	v_add_f32_e32 v138, 1.0, v138
	v_add_f32_e32 v139, 1.0, v139
	v_add_f32_e32 v140, 1.0, v140
	v_add_f32_e32 v141, 1.0, v141
	v_rcp_f32_e32 v138, v138
	v_rcp_f32_e32 v139, v139
	v_rcp_f32_e32 v140, v140
	v_rcp_f32_e32 v141, v141
	s_nop 0
	v_fma_f32 v138, -2.0, v138, 1.0
	v_fma_f32 v139, -2.0, v139, 1.0
	v_fma_f32 v140, -2.0, v140, 1.0
	v_fma_f32 v141, -2.0, v141, 1.0
	v_add_f32_e32 v138, 1.0, v138
	v_add_f32_e32 v139, 1.0, v139
	v_add_f32_e32 v140, 1.0, v140
	v_add_f32_e32 v141, 1.0, v141
	v_mul_f32_e32 v186, 0.5, v186
	v_mul_f32_e32 v187, 0.5, v187
	v_mul_f32_e32 v188, 0.5, v188
	v_mul_f32_e32 v189, 0.5, v189
	v_mul_f32_e32 v186, v186, v138
	v_mul_f32_e32 v187, v187, v139
	v_mul_f32_e32 v188, v188, v140
	v_mul_f32_e32 v189, v189, v141
	v_add_f32_e32 v114, v229, v114
	v_add_f32_e32 v115, v230, v115
	v_add_f32_e32 v116, v231, v116
	v_add_f32_e32 v117, v232, v117
	v_mul_f32_e32 v114, v114, v186
	v_mul_f32_e32 v115, v115, v187
	v_mul_f32_e32 v116, v116, v188
	v_mul_f32_e32 v117, v117, v189
	v_cvt_pk_bf16_f32 v114, v114, v114
	v_cvt_pk_bf16_f32 v115, v115, v115
	v_cvt_pk_bf16_f32 v116, v116, v116
	v_cvt_pk_bf16_f32 v117, v117, v117
	v_mul_f32_e32 v138, v190, v190
	v_mul_f32_e32 v139, v191, v191
	v_mul_f32_e32 v140, v192, v192
	v_mul_f32_e32 v141, v193, v193
	v_mul_f32_e32 v138, v138, v190
	v_mul_f32_e32 v139, v139, v191
	v_mul_f32_e32 v140, v140, v192
	v_mul_f32_e32 v141, v141, v193
	v_fma_f32 v138, v202, v138, v190
	v_fma_f32 v139, v202, v139, v191
	v_fma_f32 v140, v202, v140, v192
	v_fma_f32 v141, v202, v141, v193
	v_mul_f32_e32 v138, 0x40135761, v138
	v_mul_f32_e32 v139, 0x40135761, v139
	v_mul_f32_e32 v140, 0x40135761, v140
	v_mul_f32_e32 v141, 0x40135761, v141
	v_exp_f32_e32 v138, v138
	v_exp_f32_e32 v139, v139
	v_exp_f32_e32 v140, v140
	v_exp_f32_e32 v141, v141
	s_nop 0
	v_add_f32_e32 v138, 1.0, v138
	v_add_f32_e32 v139, 1.0, v139
	v_add_f32_e32 v140, 1.0, v140
	v_add_f32_e32 v141, 1.0, v141
	v_rcp_f32_e32 v138, v138
	v_rcp_f32_e32 v139, v139
	v_rcp_f32_e32 v140, v140
	v_rcp_f32_e32 v141, v141
	s_nop 0
	v_fma_f32 v138, -2.0, v138, 1.0
	v_fma_f32 v139, -2.0, v139, 1.0
	v_fma_f32 v140, -2.0, v140, 1.0
	v_fma_f32 v141, -2.0, v141, 1.0
	v_add_f32_e32 v138, 1.0, v138
	v_add_f32_e32 v139, 1.0, v139
	v_add_f32_e32 v140, 1.0, v140
	v_add_f32_e32 v141, 1.0, v141
	v_mul_f32_e32 v190, 0.5, v190
; __device__ __forceinline__ void lru_tile(const Params& P, int chunk, int head, int pass, char* smem_raw) {
;     ...
;             const float tz = 0.7978845608028654f * (g + 0.044715f * g * g * g);
;             const float th = 1.f - 2.f * __builtin_amdgcn_rcpf(1.f + __expf(2.f * tz));
;             const float ge = 0.5f * g * (1.f + th);
;             P.cat[row * 1024 + gch] = f2bf((hfv + h) * ge);
; __device__ __forceinline__ void run_phase(const Params& P, const int ph, char* smem_raw) {
;     ...
;       for (int t = VBID; t < 2112; t += VGRID) lru_tile(P, t >> 3, t & 7, 2, smv_raw);
	v_mul_f32_e32 v191, 0.5, v191
	v_mul_f32_e32 v192, 0.5, v192
	v_mul_f32_e32 v193, 0.5, v193
	v_mul_f32_e32 v190, v190, v138
	v_mul_f32_e32 v191, v191, v139
	v_mul_f32_e32 v192, v192, v140
	v_mul_f32_e32 v193, v193, v141
	v_add_f32_e32 v118, v233, v118
	v_add_f32_e32 v119, v234, v119
	v_add_f32_e32 v120, v235, v120
	v_add_f32_e32 v121, v236, v121
	v_mul_f32_e32 v118, v118, v190
	v_mul_f32_e32 v119, v119, v191
	v_mul_f32_e32 v120, v120, v192
	v_mul_f32_e32 v121, v121, v193
	v_cvt_pk_bf16_f32 v118, v118, v118
	v_cvt_pk_bf16_f32 v119, v119, v119
	v_cvt_pk_bf16_f32 v120, v120, v120
	v_cvt_pk_bf16_f32 v121, v121, v121
	s_lshl_b32 s0, s71, 18
	s_lshl_b32 s1, s56, 1
	s_add_u32 s0, s0, s1
	s_add_u32 s4, s12, s0
	s_addc_u32 s5, s13, 0
	global_store_short v237, v90, s[4:5]
	s_add_u32 s4, s4, 0x800
	s_addc_u32 s5, s5, 0
	global_store_short v237, v91, s[4:5]
	s_add_u32 s4, s4, 0x800
	s_addc_u32 s5, s5, 0
	global_store_short v237, v92, s[4:5]
	s_add_u32 s4, s4, 0x800
	s_addc_u32 s5, s5, 0
	global_store_short v237, v93, s[4:5]
	s_add_u32 s4, s4, 0x800
	s_addc_u32 s5, s5, 0
	global_store_short v237, v94, s[4:5]
	s_add_u32 s4, s4, 0x800
	s_addc_u32 s5, s5, 0
	global_store_short v237, v95, s[4:5]
	s_add_u32 s4, s4, 0x800
	s_addc_u32 s5, s5, 0
	global_store_short v237, v96, s[4:5]
	s_add_u32 s4, s4, 0x800
	s_addc_u32 s5, s5, 0
	global_store_short v237, v97, s[4:5]
	s_add_u32 s4, s4, 0x800
	s_addc_u32 s5, s5, 0
	global_store_short v237, v98, s[4:5]
	s_add_u32 s4, s4, 0x800
	s_addc_u32 s5, s5, 0
	global_store_short v237, v99, s[4:5]
	s_add_u32 s4, s4, 0x800
	s_addc_u32 s5, s5, 0
	global_store_short v237, v100, s[4:5]
	s_add_u32 s4, s4, 0x800
	s_addc_u32 s5, s5, 0
	global_store_short v237, v101, s[4:5]
	s_add_u32 s4, s4, 0x800
	s_addc_u32 s5, s5, 0
	global_store_short v237, v102, s[4:5]
	s_add_u32 s4, s4, 0x800
	s_addc_u32 s5, s5, 0
	global_store_short v237, v103, s[4:5]
	s_add_u32 s4, s4, 0x800
	s_addc_u32 s5, s5, 0
	global_store_short v237, v104, s[4:5]
	s_add_u32 s4, s4, 0x800
	s_addc_u32 s5, s5, 0
	global_store_short v237, v105, s[4:5]
	s_add_u32 s4, s4, 0x800
	s_addc_u32 s5, s5, 0
	global_store_short v237, v106, s[4:5]
	s_add_u32 s4, s4, 0x800
	s_addc_u32 s5, s5, 0
	global_store_short v237, v107, s[4:5]
	s_add_u32 s4, s4, 0x800
	s_addc_u32 s5, s5, 0
	global_store_short v237, v108, s[4:5]
	s_add_u32 s4, s4, 0x800
	s_addc_u32 s5, s5, 0
	global_store_short v237, v109, s[4:5]
	s_add_u32 s4, s4, 0x800
	s_addc_u32 s5, s5, 0
	global_store_short v237, v110, s[4:5]
	s_add_u32 s4, s4, 0x800
	s_addc_u32 s5, s5, 0
	global_store_short v237, v111, s[4:5]
	s_add_u32 s4, s4, 0x800
	s_addc_u32 s5, s5, 0
	global_store_short v237, v112, s[4:5]
	s_add_u32 s4, s4, 0x800
	s_addc_u32 s5, s5, 0
	global_store_short v237, v113, s[4:5]
	s_add_u32 s4, s4, 0x800
	s_addc_u32 s5, s5, 0
	global_store_short v237, v114, s[4:5]
	s_add_u32 s4, s4, 0x800
	s_addc_u32 s5, s5, 0
	global_store_short v237, v115, s[4:5]
	s_add_u32 s4, s4, 0x800
	s_addc_u32 s5, s5, 0
	global_store_short v237, v116, s[4:5]
	s_add_u32 s4, s4, 0x800
	s_addc_u32 s5, s5, 0
	global_store_short v237, v117, s[4:5]
	s_add_u32 s4, s4, 0x800
	s_addc_u32 s5, s5, 0
	global_store_short v237, v118, s[4:5]
	s_add_u32 s4, s4, 0x800
	s_addc_u32 s5, s5, 0
	global_store_short v237, v119, s[4:5]
	s_add_u32 s4, s4, 0x800
	s_addc_u32 s5, s5, 0
	global_store_short v237, v120, s[4:5]
	s_add_u32 s4, s4, 0x800
	s_addc_u32 s5, s5, 0
	global_store_short v237, v121, s[4:5]
	s_add_u32 s69, s69, 1
	s_cmp_lt_u32 s69, s70
	s_cbranch_scc1 .Lmy_lrub_tile
	s_waitcnt lgkmcnt(0)
	s_barrier
	s_branch .LBB0_680
